# extra barrier per unit so both wave halves run GEMM epilogues side by side (P1,P2a,P5a,P5b,P6)
# speedup vs baseline: 1.0046x; 1.0046x over previous
.LBB0_184:
	v_readfirstlane_b32 s99, v0
	s_cmpk_lt_u32 s99, 0x100
	s_cbranch_scc1 .Lxb_p1_b
	s_barrier

.LBB0_188:
	ds_read_b128 v[130:133], v178
	ds_read_b128 v[134:137], v178 offset:1024
	ds_read_b128 v[138:141], v178 offset:2048
	ds_read_b128 v[142:145], v178 offset:3072
	s_add_u32 s15, s34, 0xfffc0080
	s_addc_u32 s16, s35, -1
	s_cmp_eq_u32 s14, 12
	s_cselect_b32 s39, s25, s16
	s_cselect_b32 s38, s31, s15
	s_cselect_b32 s37, s23, vcc_hi
	s_cselect_b32 s36, s90, vcc_lo
	v_lshl_add_u64 v[206:207], s[34:35], 0, v[164:165]
	s_add_i32 m0, s68, 0xc000
	ds_read_b128 v[146:149], v179
	ds_read_b128 v[174:177], v179 offset:1024
	ds_read_b128 v[182:185], v179 offset:2048
	ds_read_b128 v[186:189], v179 offset:3072
	ds_read_b128 v[190:193], v179 offset:4096
	ds_read_b128 v[194:197], v179 offset:5120
	ds_read_b128 v[198:201], v179 offset:6144
	ds_read_b128 v[202:205], v179 offset:7168
	global_load_lds_dwordx4 v[206:207], off
	v_lshl_add_u64 v[206:207], s[34:35], 0, v[166:167]
	s_add_i32 m0, s68, 0xe000
	s_nop 0
	global_load_lds_dwordx4 v[206:207], off
	s_waitcnt lgkmcnt(8)
	s_barrier
	s_waitcnt lgkmcnt(0)
	s_setprio 1
	s_waitcnt lgkmcnt(0)
	v_mfma_f32_16x16x32_bf16 v[126:129], v[130:133], v[146:149], v[126:129]
	v_mfma_f32_16x16x32_bf16 v[122:125], v[138:141], v[146:149], v[122:125]
	v_mfma_f32_16x16x32_bf16 v[110:113], v[130:133], v[182:185], v[110:113]
	v_mfma_f32_16x16x32_bf16 v[106:109], v[138:141], v[182:185], v[106:109]
	v_mfma_f32_16x16x32_bf16 v[94:97], v[130:133], v[190:193], v[94:97]
	v_mfma_f32_16x16x32_bf16 v[90:93], v[138:141], v[190:193], v[90:93]
	v_mfma_f32_16x16x32_bf16 v[78:81], v[130:133], v[198:201], v[78:81]
	v_mfma_f32_16x16x32_bf16 v[74:77], v[138:141], v[198:201], v[74:77]
	v_mfma_f32_16x16x32_bf16 v[126:129], v[134:137], v[174:177], v[126:129]
	v_mfma_f32_16x16x32_bf16 v[122:125], v[142:145], v[174:177], v[122:125]
	v_mfma_f32_16x16x32_bf16 v[110:113], v[134:137], v[186:189], v[110:113]
	v_mfma_f32_16x16x32_bf16 v[106:109], v[142:145], v[186:189], v[106:109]
	v_mfma_f32_16x16x32_bf16 v[94:97], v[134:137], v[194:197], v[94:97]
	v_mfma_f32_16x16x32_bf16 v[90:93], v[142:145], v[194:197], v[90:93]
	v_mfma_f32_16x16x32_bf16 v[78:81], v[134:137], v[202:205], v[78:81]
	v_mfma_f32_16x16x32_bf16 v[74:77], v[142:145], v[202:205], v[74:77]
	s_setprio 0
	s_barrier
	s_add_i32 s15, s13, s41
	v_lshl_add_u64 v[222:223], s[36:37], 0, v[152:153]
	s_mov_b32 m0, s15
	ds_read_b128 v[206:209], v180
	ds_read_b128 v[210:213], v180 offset:1024
	ds_read_b128 v[214:217], v180 offset:2048
	ds_read_b128 v[218:221], v180 offset:3072
	global_load_lds_dwordx4 v[222:223], off
	v_lshl_add_u64 v[224:225], s[36:37], 0, v[156:157]
	s_add_i32 m0, s15, 0x2000
	s_nop 0
	global_load_lds_dwordx4 v[224:225], off
	s_barrier
	s_waitcnt lgkmcnt(0)
	s_setprio 1
	s_waitcnt lgkmcnt(0)
	v_mfma_f32_16x16x32_bf16 v[118:121], v[206:209], v[146:149], v[118:121]
	v_mfma_f32_16x16x32_bf16 v[114:117], v[214:217], v[146:149], v[114:117]
	v_mfma_f32_16x16x32_bf16 v[102:105], v[206:209], v[182:185], v[102:105]
	v_mfma_f32_16x16x32_bf16 v[98:101], v[214:217], v[182:185], v[98:101]
	v_mfma_f32_16x16x32_bf16 v[86:89], v[206:209], v[190:193], v[86:89]
	v_mfma_f32_16x16x32_bf16 v[82:85], v[214:217], v[190:193], v[82:85]
	v_mfma_f32_16x16x32_bf16 v[70:73], v[206:209], v[198:201], v[70:73]
	v_mfma_f32_16x16x32_bf16 v[66:69], v[214:217], v[198:201], v[66:69]
	v_mfma_f32_16x16x32_bf16 v[118:121], v[210:213], v[174:177], v[118:121]
	v_mfma_f32_16x16x32_bf16 v[114:117], v[218:221], v[174:177], v[114:117]
	v_mfma_f32_16x16x32_bf16 v[102:105], v[210:213], v[186:189], v[102:105]
	v_mfma_f32_16x16x32_bf16 v[98:101], v[218:221], v[186:189], v[98:101]
	v_mfma_f32_16x16x32_bf16 v[86:89], v[210:213], v[194:197], v[86:89]
	v_mfma_f32_16x16x32_bf16 v[82:85], v[218:221], v[194:197], v[82:85]
	v_mfma_f32_16x16x32_bf16 v[70:73], v[210:213], v[202:205], v[70:73]
	v_mfma_f32_16x16x32_bf16 v[66:69], v[218:221], v[202:205], v[66:69]
	s_setprio 0
	s_mov_b32 m0, s68
	v_lshl_add_u64 v[226:227], s[38:39], 0, v[150:151]
	s_barrier
	ds_read_b128 v[146:149], v179 offset:16384
	ds_read_b128 v[174:177], v179 offset:17408
	ds_read_b128 v[182:185], v179 offset:18432
	ds_read_b128 v[186:189], v179 offset:19456
	ds_read_b128 v[190:193], v179 offset:20480
	ds_read_b128 v[194:197], v179 offset:21504
	ds_read_b128 v[198:201], v179 offset:22528
	ds_read_b128 v[202:205], v179 offset:23552
	global_load_lds_dwordx4 v[226:227], off
	v_lshl_add_u64 v[228:229], s[38:39], 0, v[154:155]
	s_mov_b32 m0, s69
	s_nop 0
	global_load_lds_dwordx4 v[228:229], off
	s_barrier
	s_waitcnt lgkmcnt(0)
	s_setprio 1
	s_waitcnt lgkmcnt(0)
	v_mfma_f32_16x16x32_bf16 v[62:65], v[130:133], v[146:149], v[62:65]
	v_mfma_f32_16x16x32_bf16 v[58:61], v[138:141], v[146:149], v[58:61]
	v_mfma_f32_16x16x32_bf16 v[46:49], v[130:133], v[182:185], v[46:49]
	v_mfma_f32_16x16x32_bf16 v[42:45], v[138:141], v[182:185], v[42:45]
	v_mfma_f32_16x16x32_bf16 v[30:33], v[130:133], v[190:193], v[30:33]
	v_mfma_f32_16x16x32_bf16 v[26:29], v[138:141], v[190:193], v[26:29]
	v_mfma_f32_16x16x32_bf16 v[14:17], v[130:133], v[198:201], v[14:17]
	v_mfma_f32_16x16x32_bf16 v[10:13], v[138:141], v[198:201], v[10:13]
	v_mfma_f32_16x16x32_bf16 v[62:65], v[134:137], v[174:177], v[62:65]
	v_mfma_f32_16x16x32_bf16 v[58:61], v[142:145], v[174:177], v[58:61]
	v_mfma_f32_16x16x32_bf16 v[46:49], v[134:137], v[186:189], v[46:49]
	v_mfma_f32_16x16x32_bf16 v[42:45], v[142:145], v[186:189], v[42:45]
	v_mfma_f32_16x16x32_bf16 v[30:33], v[134:137], v[194:197], v[30:33]
	v_mfma_f32_16x16x32_bf16 v[26:29], v[142:145], v[194:197], v[26:29]
	v_mfma_f32_16x16x32_bf16 v[14:17], v[134:137], v[202:205], v[14:17]
	v_mfma_f32_16x16x32_bf16 v[10:13], v[142:145], v[202:205], v[10:13]
	s_setprio 0
	s_barrier
	s_add_u32 s16, s36, 0x40000
	s_addc_u32 s17, s37, 0
	s_add_i32 s15, s88, s41
	v_lshl_add_u64 v[130:131], s[16:17], 0, v[152:153]
	s_mov_b32 m0, s15
	s_nop 0
	global_load_lds_dwordx4 v[130:131], off
	v_lshl_add_u64 v[130:131], s[16:17], 0, v[156:157]
	s_add_i32 m0, s15, 0x2000
	s_nop 0
	global_load_lds_dwordx4 v[130:131], off
	s_waitcnt vmcnt(6)
	s_barrier
	s_setprio 1
	v_mfma_f32_16x16x32_bf16 v[54:57], v[206:209], v[146:149], v[54:57]
	v_mfma_f32_16x16x32_bf16 v[50:53], v[214:217], v[146:149], v[50:53]
	v_mfma_f32_16x16x32_bf16 v[38:41], v[206:209], v[182:185], v[38:41]
	v_mfma_f32_16x16x32_bf16 v[34:37], v[214:217], v[182:185], v[34:37]
	v_mfma_f32_16x16x32_bf16 v[22:25], v[206:209], v[190:193], v[22:25]
	v_mfma_f32_16x16x32_bf16 v[18:21], v[214:217], v[190:193], v[18:21]
	v_mfma_f32_16x16x32_bf16 v[6:9], v[206:209], v[198:201], v[6:9]
	v_mfma_f32_16x16x32_bf16 v[2:5], v[214:217], v[198:201], v[2:5]
	v_mfma_f32_16x16x32_bf16 v[54:57], v[210:213], v[174:177], v[54:57]
	v_mfma_f32_16x16x32_bf16 v[50:53], v[218:221], v[174:177], v[50:53]
	v_mfma_f32_16x16x32_bf16 v[38:41], v[210:213], v[186:189], v[38:41]
	v_mfma_f32_16x16x32_bf16 v[34:37], v[218:221], v[186:189], v[34:37]
	v_mfma_f32_16x16x32_bf16 v[22:25], v[210:213], v[194:197], v[22:25]
	v_mfma_f32_16x16x32_bf16 v[18:21], v[218:221], v[194:197], v[18:21]
	v_mfma_f32_16x16x32_bf16 v[6:9], v[210:213], v[202:205], v[6:9]
	v_mfma_f32_16x16x32_bf16 v[2:5], v[218:221], v[202:205], v[2:5]
	s_setprio 0
	s_add_i32 s15, 0, 0x18000
	v_add_u32_e32 v142, s15, v161
	s_barrier
	ds_read_b128 v[130:133], v142
	ds_read_b128 v[134:137], v142 offset:1024
	ds_read_b128 v[138:141], v142 offset:2048
	ds_read_b128 v[142:145], v142 offset:3072
	s_add_u32 s16, s38, 0x40000
	s_addc_u32 s17, s39, 0
	s_mov_b32 m0, s84
	v_lshl_add_u64 v[206:207], s[16:17], 0, v[150:151]
	ds_read_b128 v[146:149], v179 offset:32768
	ds_read_b128 v[174:177], v179 offset:33792
	ds_read_b128 v[182:185], v179 offset:34816
	ds_read_b128 v[186:189], v179 offset:35840
	ds_read_b128 v[190:193], v179 offset:36864
	ds_read_b128 v[194:197], v179 offset:37888
	ds_read_b128 v[198:201], v179 offset:38912
	ds_read_b128 v[202:205], v179 offset:39936
	global_load_lds_dwordx4 v[206:207], off
	v_lshl_add_u64 v[206:207], s[16:17], 0, v[154:155]
	s_mov_b32 m0, s85
	s_nop 0
	global_load_lds_dwordx4 v[206:207], off
	s_waitcnt lgkmcnt(8)
	s_barrier
	s_waitcnt lgkmcnt(0)
	s_setprio 1
	s_waitcnt lgkmcnt(0)
	v_mfma_f32_16x16x32_bf16 v[126:129], v[130:133], v[146:149], v[126:129]
	v_mfma_f32_16x16x32_bf16 v[122:125], v[138:141], v[146:149], v[122:125]
	v_mfma_f32_16x16x32_bf16 v[110:113], v[130:133], v[182:185], v[110:113]
	v_mfma_f32_16x16x32_bf16 v[106:109], v[138:141], v[182:185], v[106:109]
	v_mfma_f32_16x16x32_bf16 v[94:97], v[130:133], v[190:193], v[94:97]
	v_mfma_f32_16x16x32_bf16 v[90:93], v[138:141], v[190:193], v[90:93]
	v_mfma_f32_16x16x32_bf16 v[78:81], v[130:133], v[198:201], v[78:81]
	v_mfma_f32_16x16x32_bf16 v[74:77], v[138:141], v[198:201], v[74:77]
	v_mfma_f32_16x16x32_bf16 v[126:129], v[134:137], v[174:177], v[126:129]
	v_mfma_f32_16x16x32_bf16 v[122:125], v[142:145], v[174:177], v[122:125]
	v_mfma_f32_16x16x32_bf16 v[110:113], v[134:137], v[186:189], v[110:113]
	v_mfma_f32_16x16x32_bf16 v[106:109], v[142:145], v[186:189], v[106:109]
	v_mfma_f32_16x16x32_bf16 v[94:97], v[134:137], v[194:197], v[94:97]
	v_mfma_f32_16x16x32_bf16 v[90:93], v[142:145], v[194:197], v[90:93]
	v_mfma_f32_16x16x32_bf16 v[78:81], v[134:137], v[202:205], v[78:81]
	v_mfma_f32_16x16x32_bf16 v[74:77], v[142:145], v[202:205], v[74:77]
	s_setprio 0
	s_barrier
	s_add_i32 s38, 0, 0x1c000
	s_add_i32 s15, s15, s41
	v_add_u32_e32 v158, s38, v161
	v_lshl_add_u64 v[222:223], v[222:223], 0, s[10:11]
	s_mov_b32 m0, s15
	ds_read_b128 v[206:209], v158
	ds_read_b128 v[210:213], v158 offset:1024
	ds_read_b128 v[214:217], v158 offset:2048
	ds_read_b128 v[218:221], v158 offset:3072
	global_load_lds_dwordx4 v[222:223], off
	v_lshl_add_u64 v[222:223], v[224:225], 0, s[10:11]
	s_add_i32 m0, s15, 0x2000
	s_nop 0
	global_load_lds_dwordx4 v[222:223], off
	s_barrier
	s_waitcnt lgkmcnt(0)
	s_setprio 1
	s_waitcnt lgkmcnt(0)
	v_mfma_f32_16x16x32_bf16 v[118:121], v[206:209], v[146:149], v[118:121]
	v_mfma_f32_16x16x32_bf16 v[114:117], v[214:217], v[146:149], v[114:117]
	v_mfma_f32_16x16x32_bf16 v[102:105], v[206:209], v[182:185], v[102:105]
	v_mfma_f32_16x16x32_bf16 v[98:101], v[214:217], v[182:185], v[98:101]
	v_mfma_f32_16x16x32_bf16 v[86:89], v[206:209], v[190:193], v[86:89]
	v_mfma_f32_16x16x32_bf16 v[82:85], v[214:217], v[190:193], v[82:85]
	v_mfma_f32_16x16x32_bf16 v[70:73], v[206:209], v[198:201], v[70:73]
	v_mfma_f32_16x16x32_bf16 v[66:69], v[214:217], v[198:201], v[66:69]
	v_mfma_f32_16x16x32_bf16 v[118:121], v[210:213], v[174:177], v[118:121]
	v_mfma_f32_16x16x32_bf16 v[114:117], v[218:221], v[174:177], v[114:117]
	v_mfma_f32_16x16x32_bf16 v[102:105], v[210:213], v[186:189], v[102:105]
	v_mfma_f32_16x16x32_bf16 v[98:101], v[218:221], v[186:189], v[98:101]
	v_mfma_f32_16x16x32_bf16 v[86:89], v[210:213], v[194:197], v[86:89]
	v_mfma_f32_16x16x32_bf16 v[82:85], v[218:221], v[194:197], v[82:85]
	v_mfma_f32_16x16x32_bf16 v[70:73], v[210:213], v[202:205], v[70:73]
	v_mfma_f32_16x16x32_bf16 v[66:69], v[218:221], v[202:205], v[66:69]
	s_setprio 0
	s_mov_b32 m0, s97
	v_lshl_add_u64 v[222:223], v[226:227], 0, s[10:11]
	s_barrier
	ds_read_b128 v[146:149], v179 offset:49152
	ds_read_b128 v[174:177], v179 offset:50176
	ds_read_b128 v[182:185], v179 offset:51200
	ds_read_b128 v[186:189], v179 offset:52224
	ds_read_b128 v[190:193], v179 offset:53248
	ds_read_b128 v[194:197], v179 offset:54272
	ds_read_b128 v[198:201], v179 offset:55296
	ds_read_b128 v[202:205], v179 offset:56320
	global_load_lds_dwordx4 v[222:223], off
	v_lshl_add_u64 v[222:223], v[228:229], 0, s[10:11]
	s_mov_b32 m0, s91
	s_nop 0
	global_load_lds_dwordx4 v[222:223], off
	s_barrier
	s_waitcnt lgkmcnt(0)
	s_setprio 1
	s_waitcnt lgkmcnt(0)
	v_mfma_f32_16x16x32_bf16 v[62:65], v[130:133], v[146:149], v[62:65]
	v_mfma_f32_16x16x32_bf16 v[58:61], v[138:141], v[146:149], v[58:61]
	v_mfma_f32_16x16x32_bf16 v[46:49], v[130:133], v[182:185], v[46:49]
	v_mfma_f32_16x16x32_bf16 v[42:45], v[138:141], v[182:185], v[42:45]
	v_mfma_f32_16x16x32_bf16 v[30:33], v[130:133], v[190:193], v[30:33]
	v_mfma_f32_16x16x32_bf16 v[26:29], v[138:141], v[190:193], v[26:29]
	v_mfma_f32_16x16x32_bf16 v[14:17], v[130:133], v[198:201], v[14:17]
	v_mfma_f32_16x16x32_bf16 v[10:13], v[138:141], v[198:201], v[10:13]
	v_mfma_f32_16x16x32_bf16 v[62:65], v[134:137], v[174:177], v[62:65]
	v_mfma_f32_16x16x32_bf16 v[58:61], v[142:145], v[174:177], v[58:61]
	v_mfma_f32_16x16x32_bf16 v[46:49], v[134:137], v[186:189], v[46:49]
	v_mfma_f32_16x16x32_bf16 v[42:45], v[142:145], v[186:189], v[42:45]
	v_mfma_f32_16x16x32_bf16 v[30:33], v[134:137], v[194:197], v[30:33]
	v_mfma_f32_16x16x32_bf16 v[26:29], v[142:145], v[194:197], v[26:29]
	v_mfma_f32_16x16x32_bf16 v[14:17], v[134:137], v[202:205], v[14:17]
	v_mfma_f32_16x16x32_bf16 v[10:13], v[142:145], v[202:205], v[10:13]
	s_setprio 0
	s_barrier
	s_add_u32 s16, s36, 0x40080
	s_addc_u32 s17, s37, 0
	s_add_i32 s15, s38, s41
	v_lshl_add_u64 v[130:131], s[16:17], 0, v[152:153]
	s_mov_b32 m0, s15
	s_nop 0
	global_load_lds_dwordx4 v[130:131], off
	v_lshl_add_u64 v[130:131], s[16:17], 0, v[156:157]
	s_add_i32 m0, s15, 0x2000
	s_nop 0
	global_load_lds_dwordx4 v[130:131], off
	s_waitcnt vmcnt(6)
	s_barrier
	s_setprio 1
	v_mfma_f32_16x16x32_bf16 v[54:57], v[206:209], v[146:149], v[54:57]
	v_mfma_f32_16x16x32_bf16 v[50:53], v[214:217], v[146:149], v[50:53]
	v_mfma_f32_16x16x32_bf16 v[38:41], v[206:209], v[182:185], v[38:41]
	v_mfma_f32_16x16x32_bf16 v[34:37], v[214:217], v[182:185], v[34:37]
	v_mfma_f32_16x16x32_bf16 v[22:25], v[206:209], v[190:193], v[22:25]
	v_mfma_f32_16x16x32_bf16 v[18:21], v[214:217], v[190:193], v[18:21]
	v_mfma_f32_16x16x32_bf16 v[6:9], v[206:209], v[198:201], v[6:9]
	v_mfma_f32_16x16x32_bf16 v[2:5], v[214:217], v[198:201], v[2:5]
	v_mfma_f32_16x16x32_bf16 v[54:57], v[210:213], v[174:177], v[54:57]
	v_mfma_f32_16x16x32_bf16 v[50:53], v[218:221], v[174:177], v[50:53]
	v_mfma_f32_16x16x32_bf16 v[38:41], v[210:213], v[186:189], v[38:41]
	v_mfma_f32_16x16x32_bf16 v[34:37], v[218:221], v[186:189], v[34:37]
	v_mfma_f32_16x16x32_bf16 v[22:25], v[210:213], v[194:197], v[22:25]
	v_mfma_f32_16x16x32_bf16 v[18:21], v[218:221], v[194:197], v[18:21]
	v_mfma_f32_16x16x32_bf16 v[6:9], v[210:213], v[202:205], v[6:9]
	v_mfma_f32_16x16x32_bf16 v[2:5], v[218:221], v[202:205], v[2:5]
	s_setprio 0
	s_add_i32 s14, s14, 2
	s_add_u32 s34, s34, 0x100
	s_addc_u32 s35, s35, 0
	s_add_u32 vcc_lo, vcc_lo, 0x100
	s_addc_u32 vcc_hi, vcc_hi, 0
	s_cmp_gt_u32 s14, 13
	s_barrier
	s_cbranch_scc0 .LBB0_188
	v_readfirstlane_b32 s99, v0
	s_cmpk_gt_u32 s99, 0xff
	s_cbranch_scc1 .Lxb_p1_a
	s_barrier
.Lxb_p1_a:
	v_lshl_add_u32 v174, s30, 8, v1
	s_cmp_gt_i32 s12, 3
	s_mov_b64 s[34:35], -1
	s_cbranch_scc0 .LBB0_204
	s_cmp_gt_u32 s12, 7
	s_cbranch_scc0 .LBB0_201
	s_cmp_lt_u32 s12, 16
	s_cbranch_scc0 .LBB0_193
	s_add_i32 s14, s12, -8
	v_lshl_or_b32 v158, s14, 8, v160
	v_lshl_add_u64 v[134:135], v[158:159], 2, s[70:71]
	global_load_dwordx4 v[138:141], v[134:135], off offset:16
	global_load_dwordx4 v[142:145], v[134:135], off
	global_load_dwordx4 v[130:133], v[134:135], off offset:528
	s_nop 0
	global_load_dwordx4 v[134:137], v[134:135], off offset:512
	s_lshl_b32 s15, s30, 3
	s_add_i32 s14, s15, s14
	s_ashr_i32 s15, s14, 31
	s_lshl_b64 s[14:15], s[14:15], 17
	v_readlane_b32 s16, v254, 9
	s_add_u32 s30, s16, s14
	v_readlane_b32 s14, v254, 10
	s_addc_u32 s31, s14, s15
	v_mov_b32_e32 v173, v159
	v_lshl_add_u64 v[176:177], s[30:31], 0, v[172:173]
	s_movk_i32 s14, 0x1000
	s_mov_b64 s[34:35], 0
	s_waitcnt vmcnt(0)
	v_add_f32_e32 v149, v123, v139
	v_add_f32_e32 v146, v126, v142
	v_add_f32_e32 v147, v127, v143
	v_mul_f32_e32 v146, 0xbfb8aa3b, v146
	v_mul_f32_e32 v147, 0xbfb8aa3b, v147
	v_exp_f32_e32 v146, v146
	v_exp_f32_e32 v147, v147
	v_add_f32_e32 v148, v129, v145
	v_mul_f32_e32 v148, 0xbfb8aa3b, v148
	v_add_f32_e32 v146, 1.0, v146
	v_add_f32_e32 v147, 1.0, v147
	v_rcp_f32_e32 v146, v146
	v_rcp_f32_e32 v147, v147
	v_exp_f32_e32 v148, v148
	v_mul_f32_e32 v149, 0xbfb8aa3b, v149
	v_exp_f32_e32 v149, v149
	v_cvt_pk_bf16_f32 v146, v146, v147
	v_add_f32_e32 v147, v128, v144
	v_mul_f32_e32 v147, 0xbfb8aa3b, v147
	v_exp_f32_e32 v147, v147
	v_add_f32_e32 v148, 1.0, v148
	v_rcp_f32_e32 v148, v148
	v_add_f32_e32 v149, 1.0, v149
	v_add_f32_e32 v147, 1.0, v147
	v_rcp_f32_e32 v147, v147
	v_rcp_f32_e32 v149, v149
	v_add_f32_e32 v158, v125, v141
	v_mul_f32_e32 v158, 0xbfb8aa3b, v158
	v_cvt_pk_bf16_f32 v147, v147, v148
	v_add_f32_e32 v148, v122, v138
	v_mul_f32_e32 v148, 0xbfb8aa3b, v148
	v_exp_f32_e32 v148, v148
	v_exp_f32_e32 v158, v158
	v_add_f32_e32 v173, v87, v135
	v_mul_f32_e32 v173, 0xbfb8aa3b, v173
	v_add_f32_e32 v148, 1.0, v148
	v_rcp_f32_e32 v148, v148
	v_add_f32_e32 v158, 1.0, v158
	v_rcp_f32_e32 v158, v158
	v_exp_f32_e32 v173, v173
	v_cvt_pk_bf16_f32 v148, v148, v149
	v_add_f32_e32 v149, v124, v140
	v_mul_f32_e32 v149, 0xbfb8aa3b, v149
	v_exp_f32_e32 v149, v149
	v_add_f32_e32 v173, 1.0, v173
	v_rcp_f32_e32 v173, v173
	v_add_f32_e32 v149, 1.0, v149
	v_rcp_f32_e32 v149, v149
	s_nop 0
	v_cvt_pk_bf16_f32 v149, v149, v158
	global_store_dwordx4 v172, v[146:149], s[30:31]
	v_add_f32_e32 v158, v117, v133
	v_mul_f32_e32 v158, 0xbfb8aa3b, v158
	v_add_f32_e32 v146, v118, v134
	v_add_f32_e32 v147, v119, v135
	v_mul_f32_e32 v146, 0xbfb8aa3b, v146
	v_mul_f32_e32 v147, 0xbfb8aa3b, v147
	v_exp_f32_e32 v146, v146
	v_exp_f32_e32 v147, v147
	v_add_f32_e32 v148, v121, v137
	v_mul_f32_e32 v148, 0xbfb8aa3b, v148
	v_add_f32_e32 v146, 1.0, v146
	v_add_f32_e32 v147, 1.0, v147
	v_rcp_f32_e32 v146, v146
	v_rcp_f32_e32 v147, v147
	v_exp_f32_e32 v148, v148
	v_add_f32_e32 v149, v115, v131
	v_mul_f32_e32 v149, 0xbfb8aa3b, v149
	v_cvt_pk_bf16_f32 v146, v146, v147
	v_add_f32_e32 v147, v120, v136
	v_mul_f32_e32 v147, 0xbfb8aa3b, v147
	v_exp_f32_e32 v147, v147
	v_add_f32_e32 v148, 1.0, v148
	v_rcp_f32_e32 v148, v148
	v_exp_f32_e32 v149, v149
	v_add_f32_e32 v147, 1.0, v147
	v_rcp_f32_e32 v147, v147
	v_exp_f32_e32 v158, v158
	v_add_f32_e32 v149, 1.0, v149
	v_rcp_f32_e32 v149, v149
	v_cvt_pk_bf16_f32 v147, v147, v148
	v_add_f32_e32 v148, v114, v130
	v_mul_f32_e32 v148, 0xbfb8aa3b, v148
	v_exp_f32_e32 v148, v148
	v_add_f32_e32 v158, 1.0, v158
	v_rcp_f32_e32 v158, v158
	v_add_f32_e32 v148, 1.0, v148
	v_rcp_f32_e32 v148, v148
	s_nop 0
	v_cvt_pk_bf16_f32 v148, v148, v149
	v_add_f32_e32 v149, v116, v132
	v_mul_f32_e32 v149, 0xbfb8aa3b, v149
	v_exp_f32_e32 v149, v149
	s_nop 0
	v_add_f32_e32 v149, 1.0, v149
	v_rcp_f32_e32 v149, v149
	s_nop 0
	v_cvt_pk_bf16_f32 v149, v149, v158
	global_store_dwordx4 v172, v[146:149], s[30:31] offset:1024
	v_add_f32_e32 v158, v109, v141
	v_mul_f32_e32 v158, 0xbfb8aa3b, v158
	v_add_f32_e32 v146, v110, v142
	v_add_f32_e32 v147, v111, v143
	v_mul_f32_e32 v146, 0xbfb8aa3b, v146
	v_mul_f32_e32 v147, 0xbfb8aa3b, v147
	v_exp_f32_e32 v146, v146
	v_exp_f32_e32 v147, v147
	v_add_f32_e32 v148, v113, v145
	v_mul_f32_e32 v148, 0xbfb8aa3b, v148
	v_add_f32_e32 v146, 1.0, v146
	v_add_f32_e32 v147, 1.0, v147
	v_rcp_f32_e32 v146, v146
	v_rcp_f32_e32 v147, v147
	v_exp_f32_e32 v148, v148
	v_add_f32_e32 v149, v107, v139
	v_mul_f32_e32 v149, 0xbfb8aa3b, v149
	v_cvt_pk_bf16_f32 v146, v146, v147
	v_add_f32_e32 v147, v112, v144
	v_mul_f32_e32 v147, 0xbfb8aa3b, v147
	v_exp_f32_e32 v147, v147
	v_add_f32_e32 v148, 1.0, v148
	v_rcp_f32_e32 v148, v148
	v_exp_f32_e32 v149, v149
	v_add_f32_e32 v147, 1.0, v147
	v_rcp_f32_e32 v147, v147
	v_exp_f32_e32 v158, v158
	v_add_f32_e32 v149, 1.0, v149
	v_rcp_f32_e32 v149, v149
	v_cvt_pk_bf16_f32 v147, v147, v148
	v_add_f32_e32 v148, v106, v138
	v_mul_f32_e32 v148, 0xbfb8aa3b, v148
	v_exp_f32_e32 v148, v148
	v_add_f32_e32 v158, 1.0, v158
	v_rcp_f32_e32 v158, v158
	v_add_f32_e32 v148, 1.0, v148
	v_rcp_f32_e32 v148, v148
	s_nop 0
	v_cvt_pk_bf16_f32 v148, v148, v149
	v_add_f32_e32 v149, v108, v140
	v_mul_f32_e32 v149, 0xbfb8aa3b, v149
	v_exp_f32_e32 v149, v149
	s_nop 0
	v_add_f32_e32 v149, 1.0, v149
	v_rcp_f32_e32 v149, v149
	s_nop 0
	v_cvt_pk_bf16_f32 v149, v149, v158
	global_store_dwordx4 v172, v[146:149], s[30:31] offset:2048
	v_add_f32_e32 v158, v101, v133
	v_mul_f32_e32 v158, 0xbfb8aa3b, v158
	v_add_f32_e32 v146, v102, v134
	v_add_f32_e32 v147, v103, v135
	v_mul_f32_e32 v146, 0xbfb8aa3b, v146
	v_mul_f32_e32 v147, 0xbfb8aa3b, v147
	v_exp_f32_e32 v146, v146
	v_exp_f32_e32 v147, v147
	v_add_f32_e32 v148, v105, v137
	v_mul_f32_e32 v148, 0xbfb8aa3b, v148
	v_add_f32_e32 v146, 1.0, v146
	v_add_f32_e32 v147, 1.0, v147
	v_rcp_f32_e32 v146, v146
	v_rcp_f32_e32 v147, v147
	v_exp_f32_e32 v148, v148
	v_add_f32_e32 v149, v99, v131
	v_mul_f32_e32 v149, 0xbfb8aa3b, v149
	v_cvt_pk_bf16_f32 v146, v146, v147
	v_add_f32_e32 v147, v104, v136
	v_mul_f32_e32 v147, 0xbfb8aa3b, v147
	v_exp_f32_e32 v147, v147
	v_add_f32_e32 v148, 1.0, v148
	v_rcp_f32_e32 v148, v148
	v_exp_f32_e32 v149, v149
	v_add_f32_e32 v147, 1.0, v147
	v_rcp_f32_e32 v147, v147
	v_exp_f32_e32 v158, v158
	v_add_f32_e32 v149, 1.0, v149
	v_rcp_f32_e32 v149, v149
	v_cvt_pk_bf16_f32 v147, v147, v148
	v_add_f32_e32 v148, v98, v130
	v_mul_f32_e32 v148, 0xbfb8aa3b, v148
	v_exp_f32_e32 v148, v148
	v_add_f32_e32 v158, 1.0, v158
	v_rcp_f32_e32 v158, v158
	v_add_f32_e32 v148, 1.0, v148
	v_rcp_f32_e32 v148, v148
	s_nop 0
	v_cvt_pk_bf16_f32 v148, v148, v149
	v_add_f32_e32 v149, v100, v132
	v_mul_f32_e32 v149, 0xbfb8aa3b, v149
	v_exp_f32_e32 v149, v149
	s_nop 0
	v_add_f32_e32 v149, 1.0, v149
	v_rcp_f32_e32 v149, v149
	s_nop 0
	v_cvt_pk_bf16_f32 v149, v149, v158
	global_store_dwordx4 v172, v[146:149], s[30:31] offset:3072
	v_add_f32_e32 v158, v86, v134
	v_mul_f32_e32 v158, 0xbfb8aa3b, v158
	v_add_f32_e32 v146, v94, v142
	v_add_f32_e32 v147, v95, v143
	v_mul_f32_e32 v146, 0xbfb8aa3b, v146
	v_mul_f32_e32 v147, 0xbfb8aa3b, v147
	v_exp_f32_e32 v146, v146
	v_exp_f32_e32 v147, v147
	v_exp_f32_e32 v158, v158
	v_add_co_u32_e32 v148, vcc, s14, v176
	v_add_f32_e32 v146, 1.0, v146
	v_add_f32_e32 v147, 1.0, v147
	v_rcp_f32_e32 v146, v146
	v_rcp_f32_e32 v147, v147
	v_add_f32_e32 v158, 1.0, v158
	v_rcp_f32_e32 v158, v158
	v_addc_co_u32_e32 v149, vcc, 0, v177, vcc
	v_cvt_pk_bf16_f32 v182, v146, v147
	v_add_f32_e32 v146, v96, v144
	v_add_f32_e32 v147, v97, v145
	v_mul_f32_e32 v146, 0xbfb8aa3b, v146
	v_mul_f32_e32 v147, 0xbfb8aa3b, v147
	v_exp_f32_e32 v146, v146
	v_exp_f32_e32 v147, v147
	s_movk_i32 s14, 0x2000
	v_add_f32_e32 v146, 1.0, v146
	v_add_f32_e32 v147, 1.0, v147
	v_rcp_f32_e32 v146, v146
	v_rcp_f32_e32 v147, v147
	s_nop 0
	v_cvt_pk_bf16_f32 v183, v146, v147
	v_add_f32_e32 v146, v90, v138
	v_add_f32_e32 v147, v91, v139
	v_mul_f32_e32 v146, 0xbfb8aa3b, v146
	v_mul_f32_e32 v147, 0xbfb8aa3b, v147
	v_exp_f32_e32 v146, v146
	v_exp_f32_e32 v147, v147
	v_add_f32_e32 v146, 1.0, v146
	v_add_f32_e32 v147, 1.0, v147
	v_rcp_f32_e32 v146, v146
	v_rcp_f32_e32 v147, v147
	s_nop 0
	v_cvt_pk_bf16_f32 v184, v146, v147
	v_add_f32_e32 v146, v92, v140
	v_add_f32_e32 v147, v93, v141
	v_mul_f32_e32 v146, 0xbfb8aa3b, v146
	v_mul_f32_e32 v147, 0xbfb8aa3b, v147
	v_exp_f32_e32 v146, v146
	v_exp_f32_e32 v147, v147
	v_add_f32_e32 v146, 1.0, v146
	v_add_f32_e32 v147, 1.0, v147
	v_rcp_f32_e32 v146, v146
	v_rcp_f32_e32 v147, v147
	s_nop 0
	v_cvt_pk_bf16_f32 v185, v146, v147
	v_add_co_u32_e32 v146, vcc, s14, v176
	s_movk_i32 s14, 0x3000
	s_nop 0
	v_addc_co_u32_e32 v147, vcc, 0, v177, vcc
	global_store_dwordx4 v[146:147], v[182:185], off offset:-4096
	s_nop 1
	v_cvt_pk_bf16_f32 v182, v158, v173
	v_add_f32_e32 v158, v88, v136
	v_add_f32_e32 v173, v89, v137
	v_mul_f32_e32 v158, 0xbfb8aa3b, v158
	v_mul_f32_e32 v173, 0xbfb8aa3b, v173
	v_exp_f32_e32 v158, v158
	v_exp_f32_e32 v173, v173
	v_add_f32_e32 v158, 1.0, v158
	v_add_f32_e32 v173, 1.0, v173
	v_rcp_f32_e32 v158, v158
	v_rcp_f32_e32 v173, v173
	s_nop 0
	v_cvt_pk_bf16_f32 v183, v158, v173
	v_add_f32_e32 v158, v82, v130
	v_add_f32_e32 v173, v83, v131
	v_mul_f32_e32 v158, 0xbfb8aa3b, v158
	v_mul_f32_e32 v173, 0xbfb8aa3b, v173
	v_exp_f32_e32 v158, v158
	v_exp_f32_e32 v173, v173
	v_add_f32_e32 v158, 1.0, v158
	v_add_f32_e32 v173, 1.0, v173
	v_rcp_f32_e32 v158, v158
	v_rcp_f32_e32 v173, v173
	s_nop 0
	v_cvt_pk_bf16_f32 v184, v158, v173
	v_add_f32_e32 v158, v84, v132
	v_add_f32_e32 v173, v85, v133
	v_mul_f32_e32 v158, 0xbfb8aa3b, v158
	v_mul_f32_e32 v173, 0xbfb8aa3b, v173
	v_exp_f32_e32 v158, v158
	v_exp_f32_e32 v173, v173
	v_add_f32_e32 v158, 1.0, v158
	v_add_f32_e32 v173, 1.0, v173
	v_rcp_f32_e32 v158, v158
	v_rcp_f32_e32 v173, v173
	s_nop 0
	v_cvt_pk_bf16_f32 v185, v158, v173
	v_add_f32_e32 v158, v78, v142
	v_add_f32_e32 v173, v79, v143
	v_mul_f32_e32 v158, 0xbfb8aa3b, v158
	v_mul_f32_e32 v173, 0xbfb8aa3b, v173
	v_exp_f32_e32 v158, v158
	v_exp_f32_e32 v173, v173
	global_store_dwordx4 v[148:149], v[182:185], off offset:1024
	v_add_f32_e32 v158, 1.0, v158
	v_add_f32_e32 v173, 1.0, v173
	v_rcp_f32_e32 v158, v158
	v_rcp_f32_e32 v173, v173
	s_nop 0
	v_cvt_pk_bf16_f32 v182, v158, v173
	v_add_f32_e32 v158, v80, v144
	v_add_f32_e32 v173, v81, v145
	v_mul_f32_e32 v158, 0xbfb8aa3b, v158
	v_mul_f32_e32 v173, 0xbfb8aa3b, v173
	v_exp_f32_e32 v158, v158
	v_exp_f32_e32 v173, v173
	v_add_f32_e32 v158, 1.0, v158
	v_add_f32_e32 v173, 1.0, v173
	v_rcp_f32_e32 v158, v158
	v_rcp_f32_e32 v173, v173
	s_nop 0
	v_cvt_pk_bf16_f32 v183, v158, v173
	v_add_f32_e32 v158, v74, v138
	v_add_f32_e32 v173, v75, v139
	v_mul_f32_e32 v158, 0xbfb8aa3b, v158
	v_mul_f32_e32 v173, 0xbfb8aa3b, v173
	v_exp_f32_e32 v158, v158
	v_exp_f32_e32 v173, v173
	v_add_f32_e32 v158, 1.0, v158
	v_add_f32_e32 v173, 1.0, v173
	v_rcp_f32_e32 v158, v158
	v_rcp_f32_e32 v173, v173
	s_nop 0
	v_cvt_pk_bf16_f32 v184, v158, v173
	v_add_f32_e32 v158, v76, v140
	v_add_f32_e32 v173, v77, v141
	v_mul_f32_e32 v158, 0xbfb8aa3b, v158
	v_mul_f32_e32 v173, 0xbfb8aa3b, v173
	v_exp_f32_e32 v158, v158
	v_exp_f32_e32 v173, v173
	v_add_f32_e32 v158, 1.0, v158
	v_add_f32_e32 v173, 1.0, v173
	v_rcp_f32_e32 v158, v158
	v_rcp_f32_e32 v173, v173
	s_nop 0
	v_cvt_pk_bf16_f32 v185, v158, v173
	v_add_f32_e32 v158, v70, v134
	v_add_f32_e32 v173, v71, v135
	v_mul_f32_e32 v158, 0xbfb8aa3b, v158
	v_mul_f32_e32 v173, 0xbfb8aa3b, v173
	v_exp_f32_e32 v158, v158
	v_exp_f32_e32 v173, v173
	global_store_dwordx4 v[148:149], v[182:185], off offset:2048
	v_add_f32_e32 v158, 1.0, v158
	v_add_f32_e32 v173, 1.0, v173
	v_rcp_f32_e32 v158, v158
	v_rcp_f32_e32 v173, v173
	s_nop 0
	v_cvt_pk_bf16_f32 v182, v158, v173
	v_add_f32_e32 v158, v72, v136
	v_add_f32_e32 v173, v73, v137
	v_mul_f32_e32 v158, 0xbfb8aa3b, v158
	v_mul_f32_e32 v173, 0xbfb8aa3b, v173
	v_exp_f32_e32 v158, v158
	v_exp_f32_e32 v173, v173
	v_add_f32_e32 v158, 1.0, v158
	v_add_f32_e32 v173, 1.0, v173
	v_rcp_f32_e32 v158, v158
	v_rcp_f32_e32 v173, v173
	s_nop 0
	v_cvt_pk_bf16_f32 v183, v158, v173
	v_add_f32_e32 v158, v66, v130
	v_add_f32_e32 v173, v67, v131
	v_mul_f32_e32 v158, 0xbfb8aa3b, v158
	v_mul_f32_e32 v173, 0xbfb8aa3b, v173
	v_exp_f32_e32 v158, v158
	v_exp_f32_e32 v173, v173
	v_add_f32_e32 v158, 1.0, v158
	v_add_f32_e32 v173, 1.0, v173
	v_rcp_f32_e32 v158, v158
	v_rcp_f32_e32 v173, v173
	s_nop 0
	v_cvt_pk_bf16_f32 v184, v158, v173
	v_add_f32_e32 v158, v68, v132
	v_add_f32_e32 v173, v69, v133
	v_mul_f32_e32 v158, 0xbfb8aa3b, v158
	v_mul_f32_e32 v173, 0xbfb8aa3b, v173
	v_exp_f32_e32 v158, v158
	v_exp_f32_e32 v173, v173
	v_add_f32_e32 v158, 1.0, v158
	v_add_f32_e32 v173, 1.0, v173
	v_rcp_f32_e32 v158, v158
	v_rcp_f32_e32 v173, v173
	s_nop 0
	v_cvt_pk_bf16_f32 v185, v158, v173
	global_store_dwordx4 v[148:149], v[182:185], off offset:3072
	v_add_f32_e32 v148, v62, v142
	v_add_f32_e32 v149, v63, v143
	v_mul_f32_e32 v148, 0xbfb8aa3b, v148
	v_mul_f32_e32 v149, 0xbfb8aa3b, v149
	v_exp_f32_e32 v148, v148
	v_exp_f32_e32 v149, v149
	v_add_f32_e32 v148, 1.0, v148
	v_add_f32_e32 v149, 1.0, v149
	v_rcp_f32_e32 v148, v148
	v_rcp_f32_e32 v149, v149
	s_nop 0
	v_cvt_pk_bf16_f32 v182, v148, v149
	v_add_f32_e32 v148, v64, v144
	v_add_f32_e32 v149, v65, v145
	v_mul_f32_e32 v148, 0xbfb8aa3b, v148
	v_mul_f32_e32 v149, 0xbfb8aa3b, v149
	v_exp_f32_e32 v148, v148
	v_exp_f32_e32 v149, v149
	v_add_f32_e32 v148, 1.0, v148
	v_add_f32_e32 v149, 1.0, v149
	v_rcp_f32_e32 v148, v148
	v_rcp_f32_e32 v149, v149
	s_nop 0
	v_cvt_pk_bf16_f32 v183, v148, v149
	v_add_f32_e32 v148, v58, v138
	v_add_f32_e32 v149, v59, v139
	v_mul_f32_e32 v148, 0xbfb8aa3b, v148
	v_mul_f32_e32 v149, 0xbfb8aa3b, v149
	v_exp_f32_e32 v148, v148
	v_exp_f32_e32 v149, v149
	v_add_f32_e32 v148, 1.0, v148
	v_add_f32_e32 v149, 1.0, v149
	v_rcp_f32_e32 v148, v148
	v_rcp_f32_e32 v149, v149
	s_nop 0
	v_cvt_pk_bf16_f32 v184, v148, v149
	v_add_f32_e32 v148, v60, v140
	v_add_f32_e32 v149, v61, v141
	v_mul_f32_e32 v148, 0xbfb8aa3b, v148
	v_mul_f32_e32 v149, 0xbfb8aa3b, v149
	v_exp_f32_e32 v148, v148
	v_exp_f32_e32 v149, v149
	v_add_f32_e32 v148, 1.0, v148
	v_add_f32_e32 v149, 1.0, v149
	v_rcp_f32_e32 v148, v148
	v_rcp_f32_e32 v149, v149
	s_nop 0
	v_cvt_pk_bf16_f32 v185, v148, v149
	v_add_f32_e32 v148, v54, v134
	v_add_f32_e32 v149, v55, v135
	v_mul_f32_e32 v148, 0xbfb8aa3b, v148
	v_mul_f32_e32 v149, 0xbfb8aa3b, v149
	v_exp_f32_e32 v148, v148
	v_exp_f32_e32 v149, v149
	global_store_dwordx4 v[146:147], v[182:185], off
	v_add_f32_e32 v148, 1.0, v148
	v_add_f32_e32 v149, 1.0, v149
	v_rcp_f32_e32 v148, v148
	v_rcp_f32_e32 v149, v149
	s_nop 0
	v_cvt_pk_bf16_f32 v182, v148, v149
	v_add_f32_e32 v148, v56, v136
	v_add_f32_e32 v149, v57, v137
	v_mul_f32_e32 v148, 0xbfb8aa3b, v148
	v_mul_f32_e32 v149, 0xbfb8aa3b, v149
	v_exp_f32_e32 v148, v148
	v_exp_f32_e32 v149, v149
	v_add_f32_e32 v148, 1.0, v148
	v_add_f32_e32 v149, 1.0, v149
	v_rcp_f32_e32 v148, v148
	v_rcp_f32_e32 v149, v149
	s_nop 0
	v_cvt_pk_bf16_f32 v183, v148, v149
	v_add_f32_e32 v148, v50, v130
	v_add_f32_e32 v149, v51, v131
	v_mul_f32_e32 v148, 0xbfb8aa3b, v148
	v_mul_f32_e32 v149, 0xbfb8aa3b, v149
	v_exp_f32_e32 v148, v148
	v_exp_f32_e32 v149, v149
	v_add_f32_e32 v148, 1.0, v148
	v_add_f32_e32 v149, 1.0, v149
	v_rcp_f32_e32 v148, v148
	v_rcp_f32_e32 v149, v149
	s_nop 0
	v_cvt_pk_bf16_f32 v184, v148, v149
	v_add_f32_e32 v148, v52, v132
	v_add_f32_e32 v149, v53, v133
	v_mul_f32_e32 v148, 0xbfb8aa3b, v148
	v_mul_f32_e32 v149, 0xbfb8aa3b, v149
	v_exp_f32_e32 v148, v148
	v_exp_f32_e32 v149, v149
	v_add_f32_e32 v148, 1.0, v148
	v_add_f32_e32 v149, 1.0, v149
	v_rcp_f32_e32 v148, v148
	v_rcp_f32_e32 v149, v149
	s_nop 0
	v_cvt_pk_bf16_f32 v185, v148, v149
	v_add_f32_e32 v148, v46, v142
	v_add_f32_e32 v149, v47, v143
	v_mul_f32_e32 v148, 0xbfb8aa3b, v148
	v_mul_f32_e32 v149, 0xbfb8aa3b, v149
	v_exp_f32_e32 v148, v148
	v_exp_f32_e32 v149, v149
	global_store_dwordx4 v[146:147], v[182:185], off offset:1024
	v_add_f32_e32 v148, 1.0, v148
	v_add_f32_e32 v149, 1.0, v149
	v_rcp_f32_e32 v148, v148
	v_rcp_f32_e32 v149, v149
	s_nop 0
	v_cvt_pk_bf16_f32 v182, v148, v149
	v_add_f32_e32 v148, v48, v144
	v_add_f32_e32 v149, v49, v145
	v_mul_f32_e32 v148, 0xbfb8aa3b, v148
	v_mul_f32_e32 v149, 0xbfb8aa3b, v149
	v_exp_f32_e32 v148, v148
	v_exp_f32_e32 v149, v149
	v_add_f32_e32 v148, 1.0, v148
	v_add_f32_e32 v149, 1.0, v149
	v_rcp_f32_e32 v148, v148
	v_rcp_f32_e32 v149, v149
	s_nop 0
	v_cvt_pk_bf16_f32 v183, v148, v149
	v_add_f32_e32 v148, v42, v138
	v_add_f32_e32 v149, v43, v139
	v_mul_f32_e32 v148, 0xbfb8aa3b, v148
	v_mul_f32_e32 v149, 0xbfb8aa3b, v149
	v_exp_f32_e32 v148, v148
	v_exp_f32_e32 v149, v149
	v_add_f32_e32 v148, 1.0, v148
	v_add_f32_e32 v149, 1.0, v149
	v_rcp_f32_e32 v148, v148
	v_rcp_f32_e32 v149, v149
	s_nop 0
	v_cvt_pk_bf16_f32 v184, v148, v149
	v_add_f32_e32 v148, v44, v140
	v_add_f32_e32 v149, v45, v141
	v_mul_f32_e32 v148, 0xbfb8aa3b, v148
	v_mul_f32_e32 v149, 0xbfb8aa3b, v149
	v_exp_f32_e32 v148, v148
	v_exp_f32_e32 v149, v149
	v_add_f32_e32 v148, 1.0, v148
	v_add_f32_e32 v149, 1.0, v149
	v_rcp_f32_e32 v148, v148
	v_rcp_f32_e32 v149, v149
	s_nop 0
	v_cvt_pk_bf16_f32 v185, v148, v149
	v_add_f32_e32 v148, v38, v134
	v_add_f32_e32 v149, v39, v135
	v_mul_f32_e32 v148, 0xbfb8aa3b, v148
	v_mul_f32_e32 v149, 0xbfb8aa3b, v149
	v_exp_f32_e32 v148, v148
	v_exp_f32_e32 v149, v149
	global_store_dwordx4 v[146:147], v[182:185], off offset:2048
	v_add_f32_e32 v148, 1.0, v148
	v_add_f32_e32 v149, 1.0, v149
	v_rcp_f32_e32 v148, v148
	v_rcp_f32_e32 v149, v149
	s_nop 0
	v_cvt_pk_bf16_f32 v182, v148, v149
	v_add_f32_e32 v148, v40, v136
	v_add_f32_e32 v149, v41, v137
	v_mul_f32_e32 v148, 0xbfb8aa3b, v148
	v_mul_f32_e32 v149, 0xbfb8aa3b, v149
	v_exp_f32_e32 v148, v148
	v_exp_f32_e32 v149, v149
	v_add_f32_e32 v148, 1.0, v148
	v_add_f32_e32 v149, 1.0, v149
	v_rcp_f32_e32 v148, v148
	v_rcp_f32_e32 v149, v149
	s_nop 0
	v_cvt_pk_bf16_f32 v183, v148, v149
	v_add_f32_e32 v148, v34, v130
	v_add_f32_e32 v149, v35, v131
	v_mul_f32_e32 v148, 0xbfb8aa3b, v148
	v_mul_f32_e32 v149, 0xbfb8aa3b, v149
	v_exp_f32_e32 v148, v148
	v_exp_f32_e32 v149, v149
	v_add_f32_e32 v148, 1.0, v148
	v_add_f32_e32 v149, 1.0, v149
	v_rcp_f32_e32 v148, v148
	v_rcp_f32_e32 v149, v149
	s_nop 0
	v_cvt_pk_bf16_f32 v184, v148, v149
	v_add_f32_e32 v148, v36, v132
	v_add_f32_e32 v149, v37, v133
	v_mul_f32_e32 v148, 0xbfb8aa3b, v148
	v_mul_f32_e32 v149, 0xbfb8aa3b, v149
	v_exp_f32_e32 v148, v148
	v_exp_f32_e32 v149, v149
	v_add_f32_e32 v148, 1.0, v148
	v_add_f32_e32 v149, 1.0, v149
	v_rcp_f32_e32 v148, v148
	v_rcp_f32_e32 v149, v149
	s_nop 0
	v_cvt_pk_bf16_f32 v185, v148, v149
	global_store_dwordx4 v[146:147], v[182:185], off offset:3072
	v_add_f32_e32 v146, v30, v142
	v_add_f32_e32 v147, v31, v143
	v_mul_f32_e32 v146, 0xbfb8aa3b, v146
	v_mul_f32_e32 v147, 0xbfb8aa3b, v147
	v_exp_f32_e32 v146, v146
	v_exp_f32_e32 v147, v147
	v_add_f32_e32 v148, v22, v134
	v_add_f32_e32 v149, v23, v135
	v_add_f32_e32 v146, 1.0, v146
	v_add_f32_e32 v147, 1.0, v147
	v_rcp_f32_e32 v146, v146
	v_rcp_f32_e32 v147, v147
	v_mul_f32_e32 v148, 0xbfb8aa3b, v148
	v_mul_f32_e32 v149, 0xbfb8aa3b, v149
	v_exp_f32_e32 v148, v148
	v_cvt_pk_bf16_f32 v182, v146, v147
	v_add_f32_e32 v146, v32, v144
	v_add_f32_e32 v147, v33, v145
	v_mul_f32_e32 v146, 0xbfb8aa3b, v146
	v_mul_f32_e32 v147, 0xbfb8aa3b, v147
	v_exp_f32_e32 v146, v146
	v_exp_f32_e32 v147, v147
	v_exp_f32_e32 v149, v149
	v_add_f32_e32 v148, 1.0, v148
	v_add_f32_e32 v146, 1.0, v146
	v_add_f32_e32 v147, 1.0, v147
	v_rcp_f32_e32 v146, v146
	v_rcp_f32_e32 v147, v147
	v_add_f32_e32 v149, 1.0, v149
	v_rcp_f32_e32 v148, v148
	v_rcp_f32_e32 v149, v149
	v_cvt_pk_bf16_f32 v183, v146, v147
	v_add_f32_e32 v146, v26, v138
	v_add_f32_e32 v147, v27, v139
	v_mul_f32_e32 v146, 0xbfb8aa3b, v146
	v_mul_f32_e32 v147, 0xbfb8aa3b, v147
	v_exp_f32_e32 v146, v146
	v_exp_f32_e32 v147, v147
	v_add_f32_e32 v142, v14, v142
	v_add_f32_e32 v143, v15, v143
	v_add_f32_e32 v146, 1.0, v146
	v_add_f32_e32 v147, 1.0, v147
	v_rcp_f32_e32 v146, v146
	v_rcp_f32_e32 v147, v147
	v_add_f32_e32 v134, v6, v134
	v_add_f32_e32 v135, v7, v135
	v_mul_f32_e32 v142, 0xbfb8aa3b, v142
	v_cvt_pk_bf16_f32 v184, v146, v147
	v_add_f32_e32 v146, v28, v140
	v_add_f32_e32 v147, v29, v141
	v_mul_f32_e32 v146, 0xbfb8aa3b, v146
	v_mul_f32_e32 v147, 0xbfb8aa3b, v147
	v_exp_f32_e32 v146, v146
	v_exp_f32_e32 v147, v147
	v_mul_f32_e32 v143, 0xbfb8aa3b, v143
	v_mul_f32_e32 v134, 0xbfb8aa3b, v134
	v_add_f32_e32 v146, 1.0, v146
	v_add_f32_e32 v147, 1.0, v147
	v_rcp_f32_e32 v146, v146
	v_rcp_f32_e32 v147, v147
	v_mul_f32_e32 v135, 0xbfb8aa3b, v135
	v_exp_f32_e32 v142, v142
	v_exp_f32_e32 v143, v143
	v_cvt_pk_bf16_f32 v185, v146, v147
	v_add_co_u32_e32 v146, vcc, s14, v176
	v_exp_f32_e32 v134, v134
	s_nop 0
	v_addc_co_u32_e32 v147, vcc, 0, v177, vcc
	global_store_dwordx4 v[146:147], v[182:185], off
	v_exp_f32_e32 v135, v135
	v_add_f32_e32 v142, 1.0, v142
	v_cvt_pk_bf16_f32 v182, v148, v149
	v_add_f32_e32 v148, v24, v136
	v_add_f32_e32 v149, v25, v137
	v_mul_f32_e32 v148, 0xbfb8aa3b, v148
	v_mul_f32_e32 v149, 0xbfb8aa3b, v149
	v_exp_f32_e32 v148, v148
	v_exp_f32_e32 v149, v149
	v_add_f32_e32 v143, 1.0, v143
	v_add_f32_e32 v134, 1.0, v134
	v_add_f32_e32 v148, 1.0, v148
	v_add_f32_e32 v149, 1.0, v149
	v_add_f32_e32 v135, 1.0, v135
	v_rcp_f32_e32 v148, v148
	v_rcp_f32_e32 v149, v149
	v_rcp_f32_e32 v142, v142
	v_rcp_f32_e32 v143, v143
	v_rcp_f32_e32 v134, v134
	v_rcp_f32_e32 v135, v135
	v_cvt_pk_bf16_f32 v183, v148, v149
	v_add_f32_e32 v148, v18, v130
	v_add_f32_e32 v149, v19, v131
	v_cvt_pk_bf16_f32 v142, v142, v143
	v_add_f32_e32 v143, v16, v144
	v_add_f32_e32 v144, v17, v145
	v_add_f32_e32 v138, v10, v138
	v_add_f32_e32 v139, v11, v139
	v_cvt_pk_bf16_f32 v134, v134, v135
	v_add_f32_e32 v135, v8, v136
	v_add_f32_e32 v136, v9, v137
	v_add_f32_e32 v130, v2, v130
	v_add_f32_e32 v131, v3, v131
	v_mul_f32_e32 v148, 0xbfb8aa3b, v148
	v_mul_f32_e32 v149, 0xbfb8aa3b, v149
	v_mul_f32_e32 v143, 0xbfb8aa3b, v143
	v_mul_f32_e32 v144, 0xbfb8aa3b, v144
	v_mul_f32_e32 v138, 0xbfb8aa3b, v138
	v_mul_f32_e32 v139, 0xbfb8aa3b, v139
	v_mul_f32_e32 v135, 0xbfb8aa3b, v135
	v_mul_f32_e32 v136, 0xbfb8aa3b, v136
	v_mul_f32_e32 v130, 0xbfb8aa3b, v130
	v_mul_f32_e32 v131, 0xbfb8aa3b, v131
	v_exp_f32_e32 v148, v148
	v_exp_f32_e32 v149, v149
	v_exp_f32_e32 v143, v143
	v_exp_f32_e32 v144, v144
	v_exp_f32_e32 v138, v138
	v_exp_f32_e32 v139, v139
	v_exp_f32_e32 v135, v135
	v_exp_f32_e32 v136, v136
	v_exp_f32_e32 v130, v130
	v_exp_f32_e32 v131, v131
	v_add_f32_e32 v148, 1.0, v148
	v_add_f32_e32 v149, 1.0, v149
	v_add_f32_e32 v143, 1.0, v143
	v_add_f32_e32 v144, 1.0, v144
	v_add_f32_e32 v138, 1.0, v138
	v_add_f32_e32 v139, 1.0, v139
	v_add_f32_e32 v135, 1.0, v135
	v_add_f32_e32 v136, 1.0, v136
	v_add_f32_e32 v130, 1.0, v130
	v_add_f32_e32 v131, 1.0, v131
	v_rcp_f32_e32 v148, v148
	v_rcp_f32_e32 v149, v149
	v_rcp_f32_e32 v143, v143
	v_rcp_f32_e32 v144, v144
	v_rcp_f32_e32 v138, v138
	v_rcp_f32_e32 v139, v139
	v_rcp_f32_e32 v135, v135
	v_rcp_f32_e32 v136, v136
	v_rcp_f32_e32 v130, v130
	v_rcp_f32_e32 v131, v131
	v_cvt_pk_bf16_f32 v184, v148, v149
	v_add_f32_e32 v148, v20, v132
	v_add_f32_e32 v149, v21, v133
	v_cvt_pk_bf16_f32 v143, v143, v144
	v_cvt_pk_bf16_f32 v144, v138, v139
	v_add_f32_e32 v138, v12, v140
	v_add_f32_e32 v139, v13, v141
	v_cvt_pk_bf16_f32 v135, v135, v136
	v_cvt_pk_bf16_f32 v136, v130, v131
	v_add_f32_e32 v130, v4, v132
	v_add_f32_e32 v131, v5, v133
	v_mul_f32_e32 v148, 0xbfb8aa3b, v148
	v_mul_f32_e32 v149, 0xbfb8aa3b, v149
	v_mul_f32_e32 v138, 0xbfb8aa3b, v138
	v_mul_f32_e32 v139, 0xbfb8aa3b, v139
	v_mul_f32_e32 v130, 0xbfb8aa3b, v130
	v_mul_f32_e32 v131, 0xbfb8aa3b, v131
	v_exp_f32_e32 v148, v148
	v_exp_f32_e32 v149, v149
	v_exp_f32_e32 v138, v138
	v_exp_f32_e32 v139, v139
	v_exp_f32_e32 v130, v130
	v_exp_f32_e32 v131, v131
	v_add_f32_e32 v148, 1.0, v148
	v_add_f32_e32 v149, 1.0, v149
	v_add_f32_e32 v138, 1.0, v138
	v_add_f32_e32 v139, 1.0, v139
	v_add_f32_e32 v130, 1.0, v130
	v_add_f32_e32 v131, 1.0, v131
	v_rcp_f32_e32 v148, v148
	v_rcp_f32_e32 v149, v149
	v_rcp_f32_e32 v138, v138
	v_rcp_f32_e32 v139, v139
	v_rcp_f32_e32 v130, v130
	v_rcp_f32_e32 v131, v131
	v_cvt_pk_bf16_f32 v185, v148, v149
	v_cvt_pk_bf16_f32 v145, v138, v139
	global_store_dwordx4 v[146:147], v[182:185], off offset:1024
	v_cvt_pk_bf16_f32 v137, v130, v131
	global_store_dwordx4 v[146:147], v[142:145], off offset:2048
	global_store_dwordx4 v[146:147], v[134:137], off offset:3072

.LBB0_443:
	ds_read_b128 v[130:133], v203
	ds_read_b128 v[134:137], v203 offset:1024
	ds_read_b128 v[138:141], v203 offset:2048
	ds_read_b128 v[142:145], v203 offset:3072
	s_add_u32 s6, s4, 0xfffd0080
	s_addc_u32 s7, s5, -1
	s_cmp_eq_u32 s67, 8
	s_cselect_b32 s9, s21, s7
	s_cselect_b32 s8, s20, s6
	s_cselect_b32 s7, s1, s66
	s_cselect_b32 s6, s0, s23
	v_lshl_add_u64 v[230:231], s[4:5], 0, v[174:175]
	s_add_i32 m0, s34, 0xc000
	ds_read_b128 v[146:149], v204
	ds_read_b128 v[150:153], v204 offset:1024
	ds_read_b128 v[180:183], v204 offset:2048
	ds_read_b128 v[210:213], v204 offset:3072
	ds_read_b128 v[214:217], v204 offset:4096
	ds_read_b128 v[218:221], v204 offset:5120
	ds_read_b128 v[222:225], v204 offset:6144
	ds_read_b128 v[226:229], v204 offset:7168
	global_load_lds_dwordx4 v[230:231], off
	v_lshl_add_u64 v[230:231], s[4:5], 0, v[176:177]
	s_add_i32 m0, s34, 0xe000
	s_nop 0
	global_load_lds_dwordx4 v[230:231], off
	s_waitcnt lgkmcnt(8)
	s_barrier
	s_waitcnt lgkmcnt(0)
	s_setprio 1
	s_waitcnt lgkmcnt(0)
	v_mfma_f32_16x16x32_bf16 v[126:129], v[130:133], v[146:149], v[126:129]
	v_mfma_f32_16x16x32_bf16 v[122:125], v[138:141], v[146:149], v[122:125]
	v_mfma_f32_16x16x32_bf16 v[110:113], v[130:133], v[180:183], v[110:113]
	v_mfma_f32_16x16x32_bf16 v[106:109], v[138:141], v[180:183], v[106:109]
	v_mfma_f32_16x16x32_bf16 v[98:101], v[130:133], v[214:217], v[98:101]
	v_mfma_f32_16x16x32_bf16 v[90:93], v[138:141], v[214:217], v[90:93]
	v_mfma_f32_16x16x32_bf16 v[82:85], v[130:133], v[222:225], v[82:85]
	v_mfma_f32_16x16x32_bf16 v[74:77], v[138:141], v[222:225], v[74:77]
	v_mfma_f32_16x16x32_bf16 v[126:129], v[134:137], v[150:153], v[126:129]
	v_mfma_f32_16x16x32_bf16 v[122:125], v[142:145], v[150:153], v[122:125]
	v_mfma_f32_16x16x32_bf16 v[110:113], v[134:137], v[210:213], v[110:113]
	v_mfma_f32_16x16x32_bf16 v[106:109], v[142:145], v[210:213], v[106:109]
	v_mfma_f32_16x16x32_bf16 v[98:101], v[134:137], v[218:221], v[98:101]
	v_mfma_f32_16x16x32_bf16 v[90:93], v[142:145], v[218:221], v[90:93]
	v_mfma_f32_16x16x32_bf16 v[82:85], v[134:137], v[226:229], v[82:85]
	v_mfma_f32_16x16x32_bf16 v[74:77], v[142:145], v[226:229], v[74:77]
	s_setprio 0
	s_barrier
	s_add_i32 s68, s51, s27
	v_lshl_add_u64 v[246:247], s[6:7], 0, v[156:157]
	s_mov_b32 m0, s68
	ds_read_b128 v[230:233], v205
	ds_read_b128 v[234:237], v205 offset:1024
	ds_read_b128 v[238:241], v205 offset:2048
	ds_read_b128 v[242:245], v205 offset:3072
	global_load_lds_dwordx4 v[246:247], off
	v_lshl_add_u64 v[248:249], s[6:7], 0, v[162:163]
	s_add_i32 m0, s68, 0x2000
	s_nop 0
	global_load_lds_dwordx4 v[248:249], off
	s_barrier
	s_waitcnt lgkmcnt(0)
	s_setprio 1
	s_waitcnt lgkmcnt(0)
	v_mfma_f32_16x16x32_bf16 v[118:121], v[230:233], v[146:149], v[118:121]
	v_mfma_f32_16x16x32_bf16 v[114:117], v[238:241], v[146:149], v[114:117]
	v_mfma_f32_16x16x32_bf16 v[102:105], v[230:233], v[180:183], v[102:105]
	v_mfma_f32_16x16x32_bf16 v[94:97], v[238:241], v[180:183], v[94:97]
	v_mfma_f32_16x16x32_bf16 v[86:89], v[230:233], v[214:217], v[86:89]
	v_mfma_f32_16x16x32_bf16 v[78:81], v[238:241], v[214:217], v[78:81]
	v_mfma_f32_16x16x32_bf16 v[70:73], v[230:233], v[222:225], v[70:73]
	v_mfma_f32_16x16x32_bf16 v[66:69], v[238:241], v[222:225], v[66:69]
	v_mfma_f32_16x16x32_bf16 v[118:121], v[234:237], v[150:153], v[118:121]
	v_mfma_f32_16x16x32_bf16 v[114:117], v[242:245], v[150:153], v[114:117]
	v_mfma_f32_16x16x32_bf16 v[102:105], v[234:237], v[210:213], v[102:105]
	v_mfma_f32_16x16x32_bf16 v[94:97], v[242:245], v[210:213], v[94:97]
	v_mfma_f32_16x16x32_bf16 v[86:89], v[234:237], v[218:221], v[86:89]
	v_mfma_f32_16x16x32_bf16 v[78:81], v[242:245], v[218:221], v[78:81]
	v_mfma_f32_16x16x32_bf16 v[70:73], v[234:237], v[226:229], v[70:73]
	v_mfma_f32_16x16x32_bf16 v[66:69], v[242:245], v[226:229], v[66:69]
	s_setprio 0
	s_mov_b32 m0, s34
	v_lshl_add_u64 v[250:251], s[8:9], 0, v[158:159]
	s_barrier
	ds_read_b128 v[146:149], v204 offset:16384
	ds_read_b128 v[150:153], v204 offset:17408
	ds_read_b128 v[180:183], v204 offset:18432
	ds_read_b128 v[210:213], v204 offset:19456
	ds_read_b128 v[214:217], v204 offset:20480
	ds_read_b128 v[218:221], v204 offset:21504
	ds_read_b128 v[222:225], v204 offset:22528
	ds_read_b128 v[226:229], v204 offset:23552
	global_load_lds_dwordx4 v[250:251], off
	v_lshl_add_u64 v[252:253], s[8:9], 0, v[160:161]
	s_mov_b32 m0, s35
	s_nop 0
	global_load_lds_dwordx4 v[252:253], off
	s_barrier
	s_waitcnt lgkmcnt(0)
	s_setprio 1
	s_waitcnt lgkmcnt(0)
	v_mfma_f32_16x16x32_bf16 v[62:65], v[130:133], v[146:149], v[62:65]
	v_mfma_f32_16x16x32_bf16 v[58:61], v[138:141], v[146:149], v[58:61]
	v_mfma_f32_16x16x32_bf16 v[46:49], v[130:133], v[180:183], v[46:49]
	v_mfma_f32_16x16x32_bf16 v[42:45], v[138:141], v[180:183], v[42:45]
	v_mfma_f32_16x16x32_bf16 v[30:33], v[130:133], v[214:217], v[30:33]
	v_mfma_f32_16x16x32_bf16 v[26:29], v[138:141], v[214:217], v[26:29]
	v_mfma_f32_16x16x32_bf16 v[14:17], v[130:133], v[222:225], v[14:17]
	v_mfma_f32_16x16x32_bf16 v[10:13], v[138:141], v[222:225], v[10:13]
	v_mfma_f32_16x16x32_bf16 v[62:65], v[134:137], v[150:153], v[62:65]
	v_mfma_f32_16x16x32_bf16 v[58:61], v[142:145], v[150:153], v[58:61]
	v_mfma_f32_16x16x32_bf16 v[46:49], v[134:137], v[210:213], v[46:49]
	v_mfma_f32_16x16x32_bf16 v[42:45], v[142:145], v[210:213], v[42:45]
	v_mfma_f32_16x16x32_bf16 v[30:33], v[134:137], v[218:221], v[30:33]
	v_mfma_f32_16x16x32_bf16 v[26:29], v[142:145], v[218:221], v[26:29]
	v_mfma_f32_16x16x32_bf16 v[14:17], v[134:137], v[226:229], v[14:17]
	v_mfma_f32_16x16x32_bf16 v[10:13], v[142:145], v[226:229], v[10:13]
	s_setprio 0
	s_barrier
	s_add_u32 s68, s6, 0x30000
	s_addc_u32 s69, s7, 0
	s_add_i32 s70, s52, s27
	v_lshl_add_u64 v[130:131], s[68:69], 0, v[156:157]
	s_mov_b32 m0, s70
	s_nop 0
	global_load_lds_dwordx4 v[130:131], off
	v_lshl_add_u64 v[130:131], s[68:69], 0, v[162:163]
	s_add_i32 m0, s70, 0x2000
	s_nop 0
	global_load_lds_dwordx4 v[130:131], off
	s_waitcnt vmcnt(6)
	s_barrier
	s_setprio 1
	v_mfma_f32_16x16x32_bf16 v[54:57], v[230:233], v[146:149], v[54:57]
	v_mfma_f32_16x16x32_bf16 v[50:53], v[238:241], v[146:149], v[50:53]
	v_mfma_f32_16x16x32_bf16 v[38:41], v[230:233], v[180:183], v[38:41]
	v_mfma_f32_16x16x32_bf16 v[34:37], v[238:241], v[180:183], v[34:37]
	v_mfma_f32_16x16x32_bf16 v[22:25], v[230:233], v[214:217], v[22:25]
	v_mfma_f32_16x16x32_bf16 v[18:21], v[238:241], v[214:217], v[18:21]
	v_mfma_f32_16x16x32_bf16 v[6:9], v[230:233], v[222:225], v[6:9]
	v_mfma_f32_16x16x32_bf16 v[2:5], v[238:241], v[222:225], v[2:5]
	v_mfma_f32_16x16x32_bf16 v[54:57], v[234:237], v[150:153], v[54:57]
	v_mfma_f32_16x16x32_bf16 v[50:53], v[242:245], v[150:153], v[50:53]
	v_mfma_f32_16x16x32_bf16 v[38:41], v[234:237], v[210:213], v[38:41]
	v_mfma_f32_16x16x32_bf16 v[34:37], v[242:245], v[210:213], v[34:37]
	v_mfma_f32_16x16x32_bf16 v[22:25], v[234:237], v[218:221], v[22:25]
	v_mfma_f32_16x16x32_bf16 v[18:21], v[242:245], v[218:221], v[18:21]
	v_mfma_f32_16x16x32_bf16 v[6:9], v[234:237], v[226:229], v[6:9]
	v_mfma_f32_16x16x32_bf16 v[2:5], v[242:245], v[226:229], v[2:5]
	s_setprio 0
	s_add_i32 s68, 0, 0x18000
	v_add_u32_e32 v142, s68, v202
	s_barrier
	ds_read_b128 v[130:133], v142
	ds_read_b128 v[134:137], v142 offset:1024
	ds_read_b128 v[138:141], v142 offset:2048
	ds_read_b128 v[142:145], v142 offset:3072
	s_add_u32 s8, s8, 0x30000
	s_addc_u32 s9, s9, 0
	s_mov_b32 m0, s36
	v_lshl_add_u64 v[230:231], s[8:9], 0, v[158:159]
	ds_read_b128 v[146:149], v204 offset:32768
	ds_read_b128 v[150:153], v204 offset:33792
	ds_read_b128 v[180:183], v204 offset:34816
	ds_read_b128 v[210:213], v204 offset:35840
	ds_read_b128 v[214:217], v204 offset:36864
	ds_read_b128 v[218:221], v204 offset:37888
	ds_read_b128 v[222:225], v204 offset:38912
	ds_read_b128 v[226:229], v204 offset:39936
	global_load_lds_dwordx4 v[230:231], off
	v_lshl_add_u64 v[230:231], s[8:9], 0, v[160:161]
	s_mov_b32 m0, s37
	s_nop 0
	global_load_lds_dwordx4 v[230:231], off
	s_waitcnt lgkmcnt(8)
	s_barrier
	s_waitcnt lgkmcnt(0)
	s_setprio 1
	s_waitcnt lgkmcnt(0)
	v_mfma_f32_16x16x32_bf16 v[126:129], v[130:133], v[146:149], v[126:129]
	v_mfma_f32_16x16x32_bf16 v[122:125], v[138:141], v[146:149], v[122:125]
	v_mfma_f32_16x16x32_bf16 v[110:113], v[130:133], v[180:183], v[110:113]
	v_mfma_f32_16x16x32_bf16 v[106:109], v[138:141], v[180:183], v[106:109]
	v_mfma_f32_16x16x32_bf16 v[98:101], v[130:133], v[214:217], v[98:101]
	v_mfma_f32_16x16x32_bf16 v[90:93], v[138:141], v[214:217], v[90:93]
	v_mfma_f32_16x16x32_bf16 v[82:85], v[130:133], v[222:225], v[82:85]
	v_mfma_f32_16x16x32_bf16 v[74:77], v[138:141], v[222:225], v[74:77]
	v_mfma_f32_16x16x32_bf16 v[126:129], v[134:137], v[150:153], v[126:129]
	v_mfma_f32_16x16x32_bf16 v[122:125], v[142:145], v[150:153], v[122:125]
	v_mfma_f32_16x16x32_bf16 v[110:113], v[134:137], v[210:213], v[110:113]
	v_mfma_f32_16x16x32_bf16 v[106:109], v[142:145], v[210:213], v[106:109]
	v_mfma_f32_16x16x32_bf16 v[98:101], v[134:137], v[218:221], v[98:101]
	v_mfma_f32_16x16x32_bf16 v[90:93], v[142:145], v[218:221], v[90:93]
	v_mfma_f32_16x16x32_bf16 v[82:85], v[134:137], v[226:229], v[82:85]
	v_mfma_f32_16x16x32_bf16 v[74:77], v[142:145], v[226:229], v[74:77]
	s_setprio 0
	s_barrier
	s_add_i32 s8, 0, 0x1c000
	s_add_i32 s9, s68, s27
	v_add_u32_e32 v164, s8, v202
	v_lshl_add_u64 v[246:247], v[246:247], 0, s[18:19]
	s_mov_b32 m0, s9
	ds_read_b128 v[230:233], v164
	ds_read_b128 v[234:237], v164 offset:1024
	ds_read_b128 v[238:241], v164 offset:2048
	ds_read_b128 v[242:245], v164 offset:3072
	global_load_lds_dwordx4 v[246:247], off
	v_lshl_add_u64 v[246:247], v[248:249], 0, s[18:19]
	s_add_i32 m0, s9, 0x2000
	s_nop 0
	global_load_lds_dwordx4 v[246:247], off
	s_barrier
	s_waitcnt lgkmcnt(0)
	s_setprio 1
	s_waitcnt lgkmcnt(0)
	v_mfma_f32_16x16x32_bf16 v[118:121], v[230:233], v[146:149], v[118:121]
	v_mfma_f32_16x16x32_bf16 v[114:117], v[238:241], v[146:149], v[114:117]
	v_mfma_f32_16x16x32_bf16 v[102:105], v[230:233], v[180:183], v[102:105]
	v_mfma_f32_16x16x32_bf16 v[94:97], v[238:241], v[180:183], v[94:97]
	v_mfma_f32_16x16x32_bf16 v[86:89], v[230:233], v[214:217], v[86:89]
	v_mfma_f32_16x16x32_bf16 v[78:81], v[238:241], v[214:217], v[78:81]
	v_mfma_f32_16x16x32_bf16 v[70:73], v[230:233], v[222:225], v[70:73]
	v_mfma_f32_16x16x32_bf16 v[66:69], v[238:241], v[222:225], v[66:69]
	v_mfma_f32_16x16x32_bf16 v[118:121], v[234:237], v[150:153], v[118:121]
	v_mfma_f32_16x16x32_bf16 v[114:117], v[242:245], v[150:153], v[114:117]
	v_mfma_f32_16x16x32_bf16 v[102:105], v[234:237], v[210:213], v[102:105]
	v_mfma_f32_16x16x32_bf16 v[94:97], v[242:245], v[210:213], v[94:97]
	v_mfma_f32_16x16x32_bf16 v[86:89], v[234:237], v[218:221], v[86:89]
	v_mfma_f32_16x16x32_bf16 v[78:81], v[242:245], v[218:221], v[78:81]
	v_mfma_f32_16x16x32_bf16 v[70:73], v[234:237], v[226:229], v[70:73]
	v_mfma_f32_16x16x32_bf16 v[66:69], v[242:245], v[226:229], v[66:69]
	s_setprio 0
	s_mov_b32 m0, s43
	v_lshl_add_u64 v[246:247], v[250:251], 0, s[18:19]
	s_barrier
	ds_read_b128 v[146:149], v204 offset:49152
	ds_read_b128 v[150:153], v204 offset:50176
	ds_read_b128 v[180:183], v204 offset:51200
	ds_read_b128 v[210:213], v204 offset:52224
	ds_read_b128 v[214:217], v204 offset:53248
	ds_read_b128 v[218:221], v204 offset:54272
	ds_read_b128 v[222:225], v204 offset:55296
	ds_read_b128 v[226:229], v204 offset:56320
	global_load_lds_dwordx4 v[246:247], off
	v_lshl_add_u64 v[246:247], v[252:253], 0, s[18:19]
	s_mov_b32 m0, s46
	s_nop 0
	global_load_lds_dwordx4 v[246:247], off
	s_barrier
	s_waitcnt lgkmcnt(0)
	s_setprio 1
	s_waitcnt lgkmcnt(0)
	v_mfma_f32_16x16x32_bf16 v[62:65], v[130:133], v[146:149], v[62:65]
	v_mfma_f32_16x16x32_bf16 v[58:61], v[138:141], v[146:149], v[58:61]
	v_mfma_f32_16x16x32_bf16 v[46:49], v[130:133], v[180:183], v[46:49]
	v_mfma_f32_16x16x32_bf16 v[42:45], v[138:141], v[180:183], v[42:45]
	v_mfma_f32_16x16x32_bf16 v[30:33], v[130:133], v[214:217], v[30:33]
	v_mfma_f32_16x16x32_bf16 v[26:29], v[138:141], v[214:217], v[26:29]
	v_mfma_f32_16x16x32_bf16 v[14:17], v[130:133], v[222:225], v[14:17]
	v_mfma_f32_16x16x32_bf16 v[10:13], v[138:141], v[222:225], v[10:13]
	v_mfma_f32_16x16x32_bf16 v[62:65], v[134:137], v[150:153], v[62:65]
	v_mfma_f32_16x16x32_bf16 v[58:61], v[142:145], v[150:153], v[58:61]
	v_mfma_f32_16x16x32_bf16 v[46:49], v[134:137], v[210:213], v[46:49]
	v_mfma_f32_16x16x32_bf16 v[42:45], v[142:145], v[210:213], v[42:45]
	v_mfma_f32_16x16x32_bf16 v[30:33], v[134:137], v[218:221], v[30:33]
	v_mfma_f32_16x16x32_bf16 v[26:29], v[142:145], v[218:221], v[26:29]
	v_mfma_f32_16x16x32_bf16 v[14:17], v[134:137], v[226:229], v[14:17]
	v_mfma_f32_16x16x32_bf16 v[10:13], v[142:145], v[226:229], v[10:13]
	s_setprio 0
	s_barrier
	s_add_u32 s6, s6, 0x30080
	s_addc_u32 s7, s7, 0
	s_add_i32 s8, s8, s27
	v_lshl_add_u64 v[130:131], s[6:7], 0, v[156:157]
	s_mov_b32 m0, s8
	s_nop 0
	global_load_lds_dwordx4 v[130:131], off
	v_lshl_add_u64 v[130:131], s[6:7], 0, v[162:163]
	s_add_i32 m0, s8, 0x2000
	s_nop 0
	global_load_lds_dwordx4 v[130:131], off
	s_waitcnt vmcnt(6)
	s_barrier
	s_setprio 1
	v_mfma_f32_16x16x32_bf16 v[54:57], v[230:233], v[146:149], v[54:57]
	v_mfma_f32_16x16x32_bf16 v[50:53], v[238:241], v[146:149], v[50:53]
	v_mfma_f32_16x16x32_bf16 v[38:41], v[230:233], v[180:183], v[38:41]
	v_mfma_f32_16x16x32_bf16 v[34:37], v[238:241], v[180:183], v[34:37]
	v_mfma_f32_16x16x32_bf16 v[22:25], v[230:233], v[214:217], v[22:25]
	v_mfma_f32_16x16x32_bf16 v[18:21], v[238:241], v[214:217], v[18:21]
	v_mfma_f32_16x16x32_bf16 v[6:9], v[230:233], v[222:225], v[6:9]
	v_mfma_f32_16x16x32_bf16 v[2:5], v[238:241], v[222:225], v[2:5]
	v_mfma_f32_16x16x32_bf16 v[54:57], v[234:237], v[150:153], v[54:57]
	v_mfma_f32_16x16x32_bf16 v[50:53], v[242:245], v[150:153], v[50:53]
	v_mfma_f32_16x16x32_bf16 v[38:41], v[234:237], v[210:213], v[38:41]
	v_mfma_f32_16x16x32_bf16 v[34:37], v[242:245], v[210:213], v[34:37]
	v_mfma_f32_16x16x32_bf16 v[22:25], v[234:237], v[218:221], v[22:25]
	v_mfma_f32_16x16x32_bf16 v[18:21], v[242:245], v[218:221], v[18:21]
	v_mfma_f32_16x16x32_bf16 v[6:9], v[234:237], v[226:229], v[6:9]
	v_mfma_f32_16x16x32_bf16 v[2:5], v[242:245], v[226:229], v[2:5]
	s_setprio 0
	s_add_i32 s67, s67, 2
	s_add_u32 s4, s4, 0x100
	s_addc_u32 s5, s5, 0
	s_add_u32 s23, s23, 0x100
	s_addc_u32 s66, s66, 0
	s_cmp_gt_u32 s67, 9
	s_barrier
	s_cbranch_scc0 .LBB0_443
	v_readfirstlane_b32 s99, v0
	s_cmpk_gt_u32 s99, 0xff
	s_cbranch_scc1 .Lxb_p2a_a
	s_barrier
.Lxb_p2a_a:
	s_lshl_b32 s66, s22, 8
	s_add_i32 s66, s66, s42
	v_or_b32_e32 v180, s66, v190
	v_ashrrev_i32_e32 v181, 31, v180
	v_lshl_add_u64 v[130:131], v[180:181], 2, s[16:17]
	global_load_dword v132, v[130:131], off
	global_load_dword v133, v[130:131], off offset:64
	global_load_dword v134, v[130:131], off offset:128
	global_load_dword v135, v[130:131], off offset:192
	global_load_dword v136, v[130:131], off offset:512
	global_load_dword v137, v[130:131], off offset:576
	global_load_dword v138, v[130:131], off offset:640
	s_nop 0
	global_load_dword v130, v[130:131], off offset:704
	v_add_u32_e32 v131, 0x80, v180
	v_and_b32_e32 v222, 0xfcf, v180
	s_mov_b64 s[22:23], -1
	s_cmp_lt_i32 s57, 2
	v_or_b32_e32 v219, 16, v222
	v_or_b32_e32 v216, 32, v222
	v_or_b32_e32 v215, 48, v222
	v_and_b32_e32 v209, 0xfcf, v131
	v_ashrrev_i32_e32 v213, 9, v131
	s_waitcnt vmcnt(0)
	v_fmamk_f32 v225, v132, 0x3aaaaaab, v206
	v_fmamk_f32 v223, v133, 0x3aaaaaab, v206
	v_fmamk_f32 v220, v134, 0x3aaaaaab, v206
	v_fmamk_f32 v217, v135, 0x3aaaaaab, v206
	v_fmamk_f32 v214, v136, 0x3aaaaaab, v206
	v_fmamk_f32 v212, v137, 0x3aaaaaab, v206
	v_fmamk_f32 v211, v138, 0x3aaaaaab, v206
	v_cmp_gt_f32_e64 s[8:9], s53, v225
	v_mul_f32_e32 v226, 0x4b800000, v225
	v_cmp_gt_f32_e64 s[6:7], s53, v223
	v_mul_f32_e32 v224, 0x4b800000, v223
	v_cmp_gt_f32_e64 s[4:5], s53, v220
	v_mul_f32_e32 v221, 0x4b800000, v220
	v_cmp_gt_f32_e32 vcc, s53, v217
	v_mul_f32_e32 v218, 0x4b800000, v217
	v_fmamk_f32 v210, v130, 0x3aaaaaab, v206
	s_cbranch_scc1 .LBB0_446
	v_lshlrev_b32_e32 v130, 6, v180
	v_and_b32_e32 v164, 0x3f3c0, v130
	v_lshl_add_u64 v[130:131], v[166:167], 0, v[164:165]
	global_load_dwordx4 v[228:231], v[130:131], off
	v_lshl_add_u64 v[134:135], v[168:169], 0, v[164:165]
	global_load_dwordx4 v[232:235], v[134:135], off
	global_load_dwordx4 v[146:149], v[130:131], off offset:1024
	global_load_dwordx4 v[150:153], v[134:135], off offset:1024
	global_load_dwordx4 v[138:141], v[130:131], off offset:2048
	global_load_dwordx4 v[142:145], v[134:135], off offset:2048
	s_nop 0
	global_load_dwordx4 v[130:133], v[130:131], off offset:3072
	s_nop 0
	global_load_dwordx4 v[134:137], v[134:135], off offset:3072
	v_cndmask_b32_e64 v164, v225, v226, s[8:9]
	v_rsq_f32_e32 v164, v164
	s_ashr_i32 s22, s66, 9
	s_and_b32 s22, s22, -8
	s_or_b32 s68, s22, s41
	v_mul_f32_e32 v181, 0x45800000, v164
	v_cndmask_b32_e64 v164, v164, v181, s[8:9]
	v_mul_f32_e32 v164, 0x3e16c740, v164
	s_ashr_i32 s69, s68, 31
	s_lshl_b64 s[22:23], s[68:69], 12
	v_or_b32_e32 v181, s22, v222
	s_waitcnt vmcnt(0)
	v_pk_mul_f32 v[182:183], v[122:123], v[232:233]
	v_pk_mul_f32 v[236:237], v[124:125], v[234:235]
	v_pk_mul_f32 v[238:239], v[128:129], v[234:235]
	v_pk_fma_f32 v[182:183], v[126:127], v[228:229], v[182:183] neg_lo:[0,0,1] neg_hi:[0,0,1]
	v_pk_fma_f32 v[236:237], v[128:129], v[230:231], v[236:237] neg_lo:[0,0,1] neg_hi:[0,0,1]
	v_pk_mul_f32 v[182:183], v[164:165], v[182:183] op_sel_hi:[0,1]
	v_pk_mul_f32 v[236:237], v[164:165], v[236:237] op_sel_hi:[0,1]
	v_cvt_pk_bf16_f32 v182, v182, v183
	v_cvt_pk_bf16_f32 v183, v236, v237
	v_pk_mul_f32 v[236:237], v[126:127], v[232:233]
	v_pk_fma_f32 v[238:239], v[124:125], v[230:231], v[238:239]
	v_pk_fma_f32 v[236:237], v[122:123], v[228:229], v[236:237]
	v_pk_mul_f32 v[238:239], v[164:165], v[238:239] op_sel_hi:[0,1]
	v_pk_mul_f32 v[236:237], v[164:165], v[236:237] op_sel_hi:[0,1]
	v_cvt_pk_bf16_f32 v236, v236, v237
	v_cvt_pk_bf16_f32 v237, v238, v239
	v_mad_u64_u32 v[238:239], s[8:9], v181, s54, v[172:173]
	v_mad_i32_i24 v239, s23, v207, v239
	global_store_dwordx2 v[238:239], v[182:183], off offset:128
	global_store_dwordx2 v[238:239], v[236:237], off offset:160
	v_pk_mul_f32 v[182:183], v[114:115], v[232:233]
	v_pk_mul_f32 v[232:233], v[118:119], v[232:233]
	s_or_b32 s8, s68, 4
	v_pk_fma_f32 v[182:183], v[118:119], v[228:229], v[182:183] neg_lo:[0,0,1] neg_hi:[0,0,1]
	v_pk_mul_f32 v[236:237], v[116:117], v[234:235]
	v_pk_fma_f32 v[228:229], v[114:115], v[228:229], v[232:233]
	v_pk_mul_f32 v[232:233], v[120:121], v[234:235]
	s_ashr_i32 s9, s8, 31
	v_pk_fma_f32 v[236:237], v[120:121], v[230:231], v[236:237] neg_lo:[0,0,1] neg_hi:[0,0,1]
	v_pk_fma_f32 v[230:231], v[116:117], v[230:231], v[232:233]
	s_lshl_b64 s[8:9], s[8:9], 12
	v_pk_mul_f32 v[182:183], v[164:165], v[182:183] op_sel_hi:[0,1]
	v_pk_mul_f32 v[236:237], v[164:165], v[236:237] op_sel_hi:[0,1]
	v_pk_mul_f32 v[228:229], v[164:165], v[228:229] op_sel_hi:[0,1]
	v_pk_mul_f32 v[230:231], v[164:165], v[230:231] op_sel_hi:[0,1]
	v_or_b32_e32 v164, s8, v222
	v_cvt_pk_bf16_f32 v228, v228, v229
	v_cvt_pk_bf16_f32 v229, v230, v231
	v_mad_u64_u32 v[230:231], s[68:69], v164, s54, v[172:173]
	v_cndmask_b32_e64 v164, v223, v224, s[6:7]
	v_rsq_f32_e32 v164, v164
	v_cvt_pk_bf16_f32 v182, v182, v183
	v_cvt_pk_bf16_f32 v183, v236, v237
	v_mad_i32_i24 v231, s9, v207, v231
	v_mul_f32_e32 v181, 0x45800000, v164
	global_store_dwordx2 v[230:231], v[182:183], off offset:128
	global_store_dwordx2 v[230:231], v[228:229], off offset:160
	v_cndmask_b32_e64 v164, v164, v181, s[6:7]
	v_pk_mul_f32 v[182:183], v[106:107], v[150:151]
	v_pk_mul_f32 v[228:229], v[108:109], v[152:153]
	v_mul_f32_e32 v164, 0x3e16c740, v164
	v_pk_fma_f32 v[182:183], v[110:111], v[146:147], v[182:183] neg_lo:[0,0,1] neg_hi:[0,0,1]
	v_pk_fma_f32 v[228:229], v[112:113], v[148:149], v[228:229] neg_lo:[0,0,1] neg_hi:[0,0,1]
	v_pk_mul_f32 v[182:183], v[164:165], v[182:183] op_sel_hi:[0,1]
	v_pk_mul_f32 v[228:229], v[164:165], v[228:229] op_sel_hi:[0,1]
	v_cvt_pk_bf16_f32 v182, v182, v183
	v_cvt_pk_bf16_f32 v183, v228, v229
	v_pk_mul_f32 v[228:229], v[110:111], v[150:151]
	v_pk_mul_f32 v[230:231], v[112:113], v[152:153]
	v_pk_fma_f32 v[228:229], v[106:107], v[146:147], v[228:229]
	v_pk_fma_f32 v[230:231], v[108:109], v[148:149], v[230:231]
	v_pk_mul_f32 v[228:229], v[164:165], v[228:229] op_sel_hi:[0,1]
	v_pk_mul_f32 v[230:231], v[164:165], v[230:231] op_sel_hi:[0,1]
	v_or_b32_e32 v181, s22, v219
	v_cvt_pk_bf16_f32 v228, v228, v229
	v_cvt_pk_bf16_f32 v229, v230, v231
	v_mad_u64_u32 v[230:231], s[6:7], v181, s54, v[172:173]
	v_mad_i32_i24 v231, s23, v207, v231
	global_store_dwordx2 v[230:231], v[182:183], off offset:128
	global_store_dwordx2 v[230:231], v[228:229], off offset:160
	v_pk_mul_f32 v[182:183], v[94:95], v[150:151]
	v_pk_mul_f32 v[150:151], v[102:103], v[150:151]
	v_pk_fma_f32 v[182:183], v[102:103], v[146:147], v[182:183] neg_lo:[0,0,1] neg_hi:[0,0,1]
	v_pk_mul_f32 v[228:229], v[96:97], v[152:153]
	v_pk_fma_f32 v[146:147], v[94:95], v[146:147], v[150:151]
	v_pk_mul_f32 v[150:151], v[104:105], v[152:153]
	v_pk_fma_f32 v[228:229], v[104:105], v[148:149], v[228:229] neg_lo:[0,0,1] neg_hi:[0,0,1]
	v_pk_fma_f32 v[148:149], v[96:97], v[148:149], v[150:151]
	v_pk_mul_f32 v[146:147], v[164:165], v[146:147] op_sel_hi:[0,1]
	v_pk_mul_f32 v[148:149], v[164:165], v[148:149] op_sel_hi:[0,1]
	v_cvt_pk_bf16_f32 v146, v146, v147
	v_cvt_pk_bf16_f32 v147, v148, v149
	v_or_b32_e32 v148, s8, v219
	v_pk_mul_f32 v[182:183], v[164:165], v[182:183] op_sel_hi:[0,1]
	v_pk_mul_f32 v[228:229], v[164:165], v[228:229] op_sel_hi:[0,1]
	v_mad_u64_u32 v[148:149], s[6:7], v148, s54, v[172:173]
	v_cvt_pk_bf16_f32 v182, v182, v183
	v_cvt_pk_bf16_f32 v183, v228, v229
	v_mad_i32_i24 v149, s9, v207, v149
	global_store_dwordx2 v[148:149], v[182:183], off offset:128
	global_store_dwordx2 v[148:149], v[146:147], off offset:160
	v_cndmask_b32_e64 v146, v220, v221, s[4:5]
	v_rsq_f32_e32 v146, v146
	v_pk_mul_f32 v[148:149], v[90:91], v[142:143]
	v_pk_mul_f32 v[150:151], v[92:93], v[144:145]
	v_pk_fma_f32 v[148:149], v[98:99], v[138:139], v[148:149] neg_lo:[0,0,1] neg_hi:[0,0,1]
	v_mul_f32_e32 v147, 0x45800000, v146
	v_cndmask_b32_e64 v146, v146, v147, s[4:5]
	v_mul_f32_e32 v146, 0x3e16c740, v146
	v_pk_fma_f32 v[150:151], v[100:101], v[140:141], v[150:151] neg_lo:[0,0,1] neg_hi:[0,0,1]
	v_pk_mul_f32 v[148:149], v[146:147], v[148:149] op_sel_hi:[0,1]
	v_pk_mul_f32 v[150:151], v[146:147], v[150:151] op_sel_hi:[0,1]
	v_cvt_pk_bf16_f32 v148, v148, v149
	v_cvt_pk_bf16_f32 v149, v150, v151
	v_pk_mul_f32 v[150:151], v[98:99], v[142:143]
	v_pk_mul_f32 v[152:153], v[100:101], v[144:145]
	v_pk_fma_f32 v[150:151], v[90:91], v[138:139], v[150:151]
	v_pk_fma_f32 v[152:153], v[92:93], v[140:141], v[152:153]
	v_pk_mul_f32 v[150:151], v[146:147], v[150:151] op_sel_hi:[0,1]
	v_pk_mul_f32 v[152:153], v[146:147], v[152:153] op_sel_hi:[0,1]
	v_or_b32_e32 v147, s22, v216
	v_cvt_pk_bf16_f32 v150, v150, v151
	v_cvt_pk_bf16_f32 v151, v152, v153
	v_mad_u64_u32 v[152:153], s[4:5], v147, s54, v[172:173]
	v_mad_i32_i24 v153, s23, v207, v153
	global_store_dwordx2 v[152:153], v[148:149], off offset:128
	global_store_dwordx2 v[152:153], v[150:151], off offset:160
	v_pk_mul_f32 v[148:149], v[78:79], v[142:143]
	v_pk_mul_f32 v[142:143], v[86:87], v[142:143]
	v_pk_fma_f32 v[148:149], v[86:87], v[138:139], v[148:149] neg_lo:[0,0,1] neg_hi:[0,0,1]
	v_pk_mul_f32 v[150:151], v[80:81], v[144:145]
	v_pk_fma_f32 v[138:139], v[78:79], v[138:139], v[142:143]
	v_pk_mul_f32 v[142:143], v[88:89], v[144:145]
	v_pk_fma_f32 v[150:151], v[88:89], v[140:141], v[150:151] neg_lo:[0,0,1] neg_hi:[0,0,1]
	v_pk_fma_f32 v[140:141], v[80:81], v[140:141], v[142:143]
	v_pk_mul_f32 v[138:139], v[146:147], v[138:139] op_sel_hi:[0,1]
	v_pk_mul_f32 v[140:141], v[146:147], v[140:141] op_sel_hi:[0,1]
	v_cvt_pk_bf16_f32 v138, v138, v139
	v_cvt_pk_bf16_f32 v139, v140, v141
	v_or_b32_e32 v140, s8, v216
	v_pk_mul_f32 v[148:149], v[146:147], v[148:149] op_sel_hi:[0,1]
	v_pk_mul_f32 v[150:151], v[146:147], v[150:151] op_sel_hi:[0,1]
	v_mad_u64_u32 v[140:141], s[4:5], v140, s54, v[172:173]
	v_cvt_pk_bf16_f32 v148, v148, v149
	v_cvt_pk_bf16_f32 v149, v150, v151
	v_mad_i32_i24 v141, s9, v207, v141
	global_store_dwordx2 v[140:141], v[148:149], off offset:128
	global_store_dwordx2 v[140:141], v[138:139], off offset:160
	v_cndmask_b32_e32 v138, v217, v218, vcc
	v_rsq_f32_e32 v138, v138
	v_pk_mul_f32 v[140:141], v[74:75], v[134:135]
	v_pk_mul_f32 v[142:143], v[76:77], v[136:137]
	v_pk_fma_f32 v[140:141], v[82:83], v[130:131], v[140:141] neg_lo:[0,0,1] neg_hi:[0,0,1]
	v_mul_f32_e32 v139, 0x45800000, v138
	v_cndmask_b32_e32 v138, v138, v139, vcc
	v_mul_f32_e32 v138, 0x3e16c740, v138
	v_pk_fma_f32 v[142:143], v[84:85], v[132:133], v[142:143] neg_lo:[0,0,1] neg_hi:[0,0,1]
	v_pk_mul_f32 v[140:141], v[138:139], v[140:141] op_sel_hi:[0,1]
	v_pk_mul_f32 v[142:143], v[138:139], v[142:143] op_sel_hi:[0,1]
	v_cvt_pk_bf16_f32 v140, v140, v141
	v_cvt_pk_bf16_f32 v141, v142, v143
	v_pk_mul_f32 v[142:143], v[82:83], v[134:135]
	v_pk_mul_f32 v[144:145], v[84:85], v[136:137]
	v_pk_fma_f32 v[142:143], v[74:75], v[130:131], v[142:143]
	v_pk_fma_f32 v[144:145], v[76:77], v[132:133], v[144:145]
	v_pk_mul_f32 v[142:143], v[138:139], v[142:143] op_sel_hi:[0,1]
	v_pk_mul_f32 v[144:145], v[138:139], v[144:145] op_sel_hi:[0,1]
	v_or_b32_e32 v139, s22, v215
	v_cvt_pk_bf16_f32 v142, v142, v143
	v_cvt_pk_bf16_f32 v143, v144, v145
	v_mad_u64_u32 v[144:145], s[4:5], v139, s54, v[172:173]
	v_mad_i32_i24 v145, s23, v207, v145
	global_store_dwordx2 v[144:145], v[140:141], off offset:128
	global_store_dwordx2 v[144:145], v[142:143], off offset:160
	v_pk_mul_f32 v[140:141], v[66:67], v[134:135]
	v_pk_mul_f32 v[134:135], v[70:71], v[134:135]
	v_pk_fma_f32 v[140:141], v[70:71], v[130:131], v[140:141] neg_lo:[0,0,1] neg_hi:[0,0,1]
	v_pk_mul_f32 v[142:143], v[68:69], v[136:137]
	v_pk_fma_f32 v[130:131], v[66:67], v[130:131], v[134:135]
	v_pk_mul_f32 v[134:135], v[72:73], v[136:137]
	v_pk_fma_f32 v[142:143], v[72:73], v[132:133], v[142:143] neg_lo:[0,0,1] neg_hi:[0,0,1]
	v_pk_fma_f32 v[132:133], v[68:69], v[132:133], v[134:135]
	v_pk_mul_f32 v[130:131], v[138:139], v[130:131] op_sel_hi:[0,1]
	v_pk_mul_f32 v[132:133], v[138:139], v[132:133] op_sel_hi:[0,1]
	v_cvt_pk_bf16_f32 v130, v130, v131
	v_cvt_pk_bf16_f32 v131, v132, v133
	v_or_b32_e32 v132, s8, v215
	v_pk_mul_f32 v[140:141], v[138:139], v[140:141] op_sel_hi:[0,1]
	v_pk_mul_f32 v[142:143], v[138:139], v[142:143] op_sel_hi:[0,1]
	v_mad_u64_u32 v[132:133], s[4:5], v132, s54, v[172:173]
	v_cvt_pk_bf16_f32 v140, v140, v141
	v_cvt_pk_bf16_f32 v141, v142, v143
	v_mad_i32_i24 v133, s9, v207, v133
	global_store_dwordx2 v[132:133], v[140:141], off offset:128
	global_store_dwordx2 v[132:133], v[130:131], off offset:160
	v_lshl_add_u32 v130, v180, 4, v208
	v_and_b32_e32 v130, 0xfcf0, v130
	v_lshlrev_b32_e32 v164, 2, v130
	v_lshl_add_u64 v[130:131], v[166:167], 0, v[164:165]
	global_load_dwordx4 v[228:231], v[130:131], off
	v_lshl_add_u64 v[134:135], v[168:169], 0, v[164:165]
	global_load_dwordx4 v[232:235], v[134:135], off
	global_load_dwordx4 v[146:149], v[130:131], off offset:1024
	global_load_dwordx4 v[150:153], v[134:135], off offset:1024
	global_load_dwordx4 v[138:141], v[130:131], off offset:2048
	global_load_dwordx4 v[142:145], v[134:135], off offset:2048
	s_nop 0
	global_load_dwordx4 v[130:133], v[130:131], off offset:3072
	s_nop 0
	global_load_dwordx4 v[134:137], v[134:135], off offset:3072
	v_cmp_gt_f32_e32 vcc, s53, v214
	v_mul_f32_e32 v164, 0x4b800000, v214
	v_and_or_b32 v180, v213, -8, s41
	v_cndmask_b32_e32 v164, v214, v164, vcc
	v_rsq_f32_e32 v164, v164
	v_or_b32_e32 v227, 16, v209
	v_mul_f32_e32 v181, 0x45800000, v164
	v_cndmask_b32_e32 v164, v164, v181, vcc
	v_mul_f32_e32 v164, 0x3e16c740, v164
	v_ashrrev_i32_e32 v181, 31, v180
	v_cmp_gt_f32_e32 vcc, s53, v212
	s_waitcnt vmcnt(0)
	v_pk_mul_f32 v[182:183], v[58:59], v[232:233]
	s_nop 0
	v_pk_fma_f32 v[182:183], v[62:63], v[228:229], v[182:183] neg_lo:[0,0,1] neg_hi:[0,0,1]
	s_nop 0
	v_pk_mul_f32 v[182:183], v[164:165], v[182:183] op_sel_hi:[0,1]
	v_cvt_pk_bf16_f32 v236, v182, v183
	v_pk_mul_f32 v[182:183], v[60:61], v[234:235]
	s_nop 0
	v_pk_fma_f32 v[182:183], v[64:65], v[230:231], v[182:183] neg_lo:[0,0,1] neg_hi:[0,0,1]
	s_nop 0
	v_pk_mul_f32 v[182:183], v[164:165], v[182:183] op_sel_hi:[0,1]
	v_cvt_pk_bf16_f32 v237, v182, v183
	v_pk_mul_f32 v[182:183], v[62:63], v[232:233]
	s_nop 0
	v_pk_fma_f32 v[182:183], v[58:59], v[228:229], v[182:183]
	s_nop 0
	v_pk_mul_f32 v[182:183], v[164:165], v[182:183] op_sel_hi:[0,1]
	v_cvt_pk_bf16_f32 v238, v182, v183
	v_pk_mul_f32 v[182:183], v[64:65], v[234:235]
	s_nop 0
	v_pk_fma_f32 v[182:183], v[60:61], v[230:231], v[182:183]
	s_nop 0
	v_pk_mul_f32 v[182:183], v[164:165], v[182:183] op_sel_hi:[0,1]
	v_cvt_pk_bf16_f32 v239, v182, v183
	v_lshlrev_b64 v[182:183], 12, v[180:181]
	v_or_b32_e32 v181, v182, v209
	v_mad_u64_u32 v[240:241], s[4:5], v181, s54, v[172:173]
	v_mad_i32_i24 v241, v183, s54, v241
	global_store_dwordx2 v[240:241], v[236:237], off offset:128
	global_store_dwordx2 v[240:241], v[238:239], off offset:160
	v_pk_mul_f32 v[236:237], v[50:51], v[232:233]
	v_pk_mul_f32 v[232:233], v[54:55], v[232:233]
	v_or_b32_e32 v180, 4, v180
	v_pk_fma_f32 v[236:237], v[54:55], v[228:229], v[236:237] neg_lo:[0,0,1] neg_hi:[0,0,1]
	v_pk_mul_f32 v[238:239], v[52:53], v[234:235]
	v_pk_fma_f32 v[228:229], v[50:51], v[228:229], v[232:233]
	v_pk_mul_f32 v[232:233], v[56:57], v[234:235]
	v_ashrrev_i32_e32 v181, 31, v180
	v_pk_fma_f32 v[238:239], v[56:57], v[230:231], v[238:239] neg_lo:[0,0,1] neg_hi:[0,0,1]
	v_pk_fma_f32 v[230:231], v[52:53], v[230:231], v[232:233]
	v_lshlrev_b64 v[180:181], 12, v[180:181]
	v_pk_mul_f32 v[236:237], v[164:165], v[236:237] op_sel_hi:[0,1]
	v_pk_mul_f32 v[238:239], v[164:165], v[238:239] op_sel_hi:[0,1]
	v_pk_mul_f32 v[228:229], v[164:165], v[228:229] op_sel_hi:[0,1]
	v_pk_mul_f32 v[230:231], v[164:165], v[230:231] op_sel_hi:[0,1]
	v_or_b32_e32 v164, v180, v209
	v_cvt_pk_bf16_f32 v228, v228, v229
	v_cvt_pk_bf16_f32 v229, v230, v231
	v_mad_u64_u32 v[230:231], s[4:5], v164, s54, v[172:173]
	v_mul_f32_e32 v164, 0x4b800000, v212
	v_cndmask_b32_e32 v164, v212, v164, vcc
	v_rsq_f32_e32 v164, v164
	v_cvt_pk_bf16_f32 v236, v236, v237
	v_cvt_pk_bf16_f32 v237, v238, v239
	v_mad_i32_i24 v231, v181, s54, v231
	global_store_dwordx2 v[230:231], v[236:237], off offset:128
	global_store_dwordx2 v[230:231], v[228:229], off offset:160
	v_mul_f32_e32 v228, 0x45800000, v164
	v_cndmask_b32_e32 v164, v164, v228, vcc
	v_pk_mul_f32 v[228:229], v[42:43], v[150:151]
	v_pk_mul_f32 v[230:231], v[44:45], v[152:153]
	v_mul_f32_e32 v164, 0x3e16c740, v164
	v_pk_fma_f32 v[228:229], v[46:47], v[146:147], v[228:229] neg_lo:[0,0,1] neg_hi:[0,0,1]
	v_pk_fma_f32 v[230:231], v[48:49], v[148:149], v[230:231] neg_lo:[0,0,1] neg_hi:[0,0,1]
	v_pk_mul_f32 v[228:229], v[164:165], v[228:229] op_sel_hi:[0,1]
	v_pk_mul_f32 v[230:231], v[164:165], v[230:231] op_sel_hi:[0,1]
	v_cvt_pk_bf16_f32 v228, v228, v229
	v_cvt_pk_bf16_f32 v229, v230, v231
	v_pk_mul_f32 v[230:231], v[46:47], v[150:151]
	v_pk_mul_f32 v[232:233], v[48:49], v[152:153]
	v_pk_fma_f32 v[230:231], v[42:43], v[146:147], v[230:231]
	v_pk_fma_f32 v[232:233], v[44:45], v[148:149], v[232:233]
	v_pk_mul_f32 v[230:231], v[164:165], v[230:231] op_sel_hi:[0,1]
	v_pk_mul_f32 v[232:233], v[164:165], v[232:233] op_sel_hi:[0,1]
	v_cvt_pk_bf16_f32 v230, v230, v231
	v_cvt_pk_bf16_f32 v231, v232, v233
	v_or_b32_e32 v232, v182, v227
	v_mad_u64_u32 v[232:233], s[4:5], v232, s54, v[172:173]
	v_mad_i32_i24 v233, v183, s54, v233
	global_store_dwordx2 v[232:233], v[228:229], off offset:128
	global_store_dwordx2 v[232:233], v[230:231], off offset:160
	v_pk_mul_f32 v[228:229], v[34:35], v[150:151]
	v_pk_mul_f32 v[150:151], v[38:39], v[150:151]
	v_pk_fma_f32 v[228:229], v[38:39], v[146:147], v[228:229] neg_lo:[0,0,1] neg_hi:[0,0,1]
	v_pk_mul_f32 v[230:231], v[36:37], v[152:153]
	v_pk_fma_f32 v[146:147], v[34:35], v[146:147], v[150:151]
	v_pk_mul_f32 v[150:151], v[40:41], v[152:153]
	v_pk_fma_f32 v[230:231], v[40:41], v[148:149], v[230:231] neg_lo:[0,0,1] neg_hi:[0,0,1]
	v_pk_fma_f32 v[148:149], v[36:37], v[148:149], v[150:151]
	v_pk_mul_f32 v[146:147], v[164:165], v[146:147] op_sel_hi:[0,1]
	v_pk_mul_f32 v[148:149], v[164:165], v[148:149] op_sel_hi:[0,1]
	v_cvt_pk_bf16_f32 v146, v146, v147
	v_cvt_pk_bf16_f32 v147, v148, v149
	v_or_b32_e32 v148, v180, v227
	v_pk_mul_f32 v[228:229], v[164:165], v[228:229] op_sel_hi:[0,1]
	v_pk_mul_f32 v[230:231], v[164:165], v[230:231] op_sel_hi:[0,1]
	v_mad_u64_u32 v[148:149], s[4:5], v148, s54, v[172:173]
	v_cvt_pk_bf16_f32 v228, v228, v229
	v_cvt_pk_bf16_f32 v229, v230, v231
	v_mad_i32_i24 v149, v181, s54, v149
	global_store_dwordx2 v[148:149], v[228:229], off offset:128
	global_store_dwordx2 v[148:149], v[146:147], off offset:160
	v_cmp_gt_f32_e32 vcc, s53, v211
	v_mul_f32_e32 v146, 0x4b800000, v211
	v_pk_mul_f32 v[150:151], v[28:29], v[144:145]
	v_cndmask_b32_e32 v146, v211, v146, vcc
	v_rsq_f32_e32 v146, v146
	v_or_b32_e32 v147, 32, v209
	v_pk_fma_f32 v[150:151], v[32:33], v[140:141], v[150:151] neg_lo:[0,0,1] neg_hi:[0,0,1]
	v_pk_mul_f32 v[152:153], v[32:33], v[144:145]
	v_mul_f32_e32 v148, 0x45800000, v146
	v_cndmask_b32_e32 v146, v146, v148, vcc
	v_pk_mul_f32 v[148:149], v[26:27], v[142:143]
	v_mul_f32_e32 v146, 0x3e16c740, v146
	v_pk_fma_f32 v[148:149], v[30:31], v[138:139], v[148:149] neg_lo:[0,0,1] neg_hi:[0,0,1]
	v_pk_mul_f32 v[150:151], v[146:147], v[150:151] op_sel_hi:[0,1]
	v_pk_mul_f32 v[148:149], v[146:147], v[148:149] op_sel_hi:[0,1]
	v_cvt_pk_bf16_f32 v148, v148, v149
	v_cvt_pk_bf16_f32 v149, v150, v151
	v_pk_mul_f32 v[150:151], v[30:31], v[142:143]
	v_pk_fma_f32 v[152:153], v[28:29], v[140:141], v[152:153]
	v_pk_fma_f32 v[150:151], v[26:27], v[138:139], v[150:151]
	v_pk_mul_f32 v[152:153], v[146:147], v[152:153] op_sel_hi:[0,1]
	v_pk_mul_f32 v[150:151], v[146:147], v[150:151] op_sel_hi:[0,1]
	v_cvt_pk_bf16_f32 v150, v150, v151
	v_cvt_pk_bf16_f32 v151, v152, v153
	v_or_b32_e32 v152, v182, v147
	v_mad_u64_u32 v[152:153], s[4:5], v152, s54, v[172:173]
	v_mad_i32_i24 v153, v183, s54, v153
	global_store_dwordx2 v[152:153], v[148:149], off offset:128
	global_store_dwordx2 v[152:153], v[150:151], off offset:160
	v_pk_mul_f32 v[148:149], v[18:19], v[142:143]
	v_pk_mul_f32 v[142:143], v[22:23], v[142:143]
	v_pk_fma_f32 v[148:149], v[22:23], v[138:139], v[148:149] neg_lo:[0,0,1] neg_hi:[0,0,1]
	v_pk_mul_f32 v[150:151], v[20:21], v[144:145]
	v_pk_fma_f32 v[138:139], v[18:19], v[138:139], v[142:143]
	v_pk_mul_f32 v[142:143], v[24:25], v[144:145]
	v_pk_fma_f32 v[150:151], v[24:25], v[140:141], v[150:151] neg_lo:[0,0,1] neg_hi:[0,0,1]
	v_pk_fma_f32 v[140:141], v[20:21], v[140:141], v[142:143]
	v_pk_mul_f32 v[138:139], v[146:147], v[138:139] op_sel_hi:[0,1]
	v_pk_mul_f32 v[140:141], v[146:147], v[140:141] op_sel_hi:[0,1]
	v_cvt_pk_bf16_f32 v138, v138, v139
	v_cvt_pk_bf16_f32 v139, v140, v141
	v_or_b32_e32 v140, v180, v147
	v_pk_mul_f32 v[148:149], v[146:147], v[148:149] op_sel_hi:[0,1]
	v_pk_mul_f32 v[150:151], v[146:147], v[150:151] op_sel_hi:[0,1]
	v_mad_u64_u32 v[140:141], s[4:5], v140, s54, v[172:173]
	v_cvt_pk_bf16_f32 v148, v148, v149
	v_cvt_pk_bf16_f32 v149, v150, v151
	v_mad_i32_i24 v141, v181, s54, v141
	global_store_dwordx2 v[140:141], v[148:149], off offset:128
	global_store_dwordx2 v[140:141], v[138:139], off offset:160
	v_cmp_gt_f32_e32 vcc, s53, v210
	v_mul_f32_e32 v138, 0x4b800000, v210
	v_pk_mul_f32 v[142:143], v[12:13], v[136:137]
	v_cndmask_b32_e32 v138, v210, v138, vcc
	v_rsq_f32_e32 v138, v138
	v_or_b32_e32 v139, 48, v209
	v_pk_fma_f32 v[142:143], v[16:17], v[132:133], v[142:143] neg_lo:[0,0,1] neg_hi:[0,0,1]
	v_pk_mul_f32 v[144:145], v[16:17], v[136:137]
	v_mul_f32_e32 v140, 0x45800000, v138
	v_cndmask_b32_e32 v138, v138, v140, vcc
	v_pk_mul_f32 v[140:141], v[10:11], v[134:135]
	v_mul_f32_e32 v138, 0x3e16c740, v138
	v_pk_fma_f32 v[140:141], v[14:15], v[130:131], v[140:141] neg_lo:[0,0,1] neg_hi:[0,0,1]
	v_pk_mul_f32 v[142:143], v[138:139], v[142:143] op_sel_hi:[0,1]
	v_pk_mul_f32 v[140:141], v[138:139], v[140:141] op_sel_hi:[0,1]
	v_cvt_pk_bf16_f32 v140, v140, v141
	v_cvt_pk_bf16_f32 v141, v142, v143
	v_pk_mul_f32 v[142:143], v[14:15], v[134:135]
	v_pk_fma_f32 v[144:145], v[12:13], v[132:133], v[144:145]
	v_pk_fma_f32 v[142:143], v[10:11], v[130:131], v[142:143]
	v_pk_mul_f32 v[144:145], v[138:139], v[144:145] op_sel_hi:[0,1]
	v_pk_mul_f32 v[142:143], v[138:139], v[142:143] op_sel_hi:[0,1]
	v_cvt_pk_bf16_f32 v142, v142, v143
	v_cvt_pk_bf16_f32 v143, v144, v145
	v_or_b32_e32 v144, v182, v139
	v_mad_u64_u32 v[144:145], s[4:5], v144, s54, v[172:173]
	v_mad_i32_i24 v145, v183, s54, v145
	global_store_dwordx2 v[144:145], v[140:141], off offset:128
	global_store_dwordx2 v[144:145], v[142:143], off offset:160
	v_pk_mul_f32 v[140:141], v[2:3], v[134:135]
	v_pk_mul_f32 v[134:135], v[6:7], v[134:135]
	v_pk_fma_f32 v[140:141], v[6:7], v[130:131], v[140:141] neg_lo:[0,0,1] neg_hi:[0,0,1]
	v_pk_mul_f32 v[142:143], v[4:5], v[136:137]
	v_pk_fma_f32 v[130:131], v[2:3], v[130:131], v[134:135]
	v_pk_mul_f32 v[134:135], v[8:9], v[136:137]
	v_pk_fma_f32 v[142:143], v[8:9], v[132:133], v[142:143] neg_lo:[0,0,1] neg_hi:[0,0,1]
	v_pk_fma_f32 v[132:133], v[4:5], v[132:133], v[134:135]
	v_pk_mul_f32 v[130:131], v[138:139], v[130:131] op_sel_hi:[0,1]
	v_pk_mul_f32 v[132:133], v[138:139], v[132:133] op_sel_hi:[0,1]
	v_cvt_pk_bf16_f32 v130, v130, v131
	v_cvt_pk_bf16_f32 v131, v132, v133
	v_or_b32_e32 v132, v180, v139
	v_pk_mul_f32 v[140:141], v[138:139], v[140:141] op_sel_hi:[0,1]
	v_pk_mul_f32 v[142:143], v[138:139], v[142:143] op_sel_hi:[0,1]
	v_mad_u64_u32 v[132:133], s[4:5], v132, s54, v[172:173]
	v_cvt_pk_bf16_f32 v140, v140, v141
	v_cvt_pk_bf16_f32 v141, v142, v143
	v_mad_i32_i24 v133, v181, s54, v133
	global_store_dwordx2 v[132:133], v[140:141], off offset:128
	global_store_dwordx2 v[132:133], v[130:131], off offset:160
	s_mov_b64 s[22:23], 0

.LBB0_731:
	ds_read_b128 v[150:153], v161
	ds_read_b128 v[164:167], v161 offset:1024
	ds_read_b128 v[168:171], v161 offset:2048
	ds_read_b128 v[172:175], v161 offset:3072
	s_add_u32 s24, s22, 0xfffe0080
	s_addc_u32 s25, s23, -1
	s_cmp_eq_u32 s55, 4
	s_cselect_b32 s27, s15, s25
	s_cselect_b32 s26, s51, s24
	s_cselect_b32 s25, s13, s54
	s_cselect_b32 s24, s52, s53
	v_lshl_add_u64 v[208:209], s[22:23], 0, v[142:143]
	s_add_i32 m0, s21, 0xc000
	ds_read_b128 v[176:179], v162
	ds_read_b128 v[180:183], v162 offset:1024
	ds_read_b128 v[184:187], v162 offset:2048
	ds_read_b128 v[188:191], v162 offset:3072
	ds_read_b128 v[192:195], v162 offset:4096
	ds_read_b128 v[196:199], v162 offset:5120
	ds_read_b128 v[200:203], v162 offset:6144
	ds_read_b128 v[204:207], v162 offset:7168
	global_load_lds_dwordx4 v[208:209], off
	v_lshl_add_u64 v[208:209], s[22:23], 0, v[144:145]
	s_add_i32 m0, s21, 0xe000
	s_nop 0
	global_load_lds_dwordx4 v[208:209], off
	s_waitcnt lgkmcnt(8)
	s_barrier
	s_waitcnt lgkmcnt(0)
	s_setprio 1
	s_waitcnt lgkmcnt(0)
	v_mfma_f32_16x16x32_bf16 v[126:129], v[150:153], v[176:179], v[126:129]
	v_mfma_f32_16x16x32_bf16 v[122:125], v[168:171], v[176:179], v[122:125]
	v_mfma_f32_16x16x32_bf16 v[118:121], v[150:153], v[184:187], v[118:121]
	v_mfma_f32_16x16x32_bf16 v[114:117], v[168:171], v[184:187], v[114:117]
	v_mfma_f32_16x16x32_bf16 v[94:97], v[150:153], v[192:195], v[94:97]
	v_mfma_f32_16x16x32_bf16 v[90:93], v[168:171], v[192:195], v[90:93]
	v_mfma_f32_16x16x32_bf16 v[86:89], v[150:153], v[200:203], v[86:89]
	v_mfma_f32_16x16x32_bf16 v[82:85], v[168:171], v[200:203], v[82:85]
	v_mfma_f32_16x16x32_bf16 v[126:129], v[164:167], v[180:183], v[126:129]
	v_mfma_f32_16x16x32_bf16 v[122:125], v[172:175], v[180:183], v[122:125]
	v_mfma_f32_16x16x32_bf16 v[118:121], v[164:167], v[188:191], v[118:121]
	v_mfma_f32_16x16x32_bf16 v[114:117], v[172:175], v[188:191], v[114:117]
	v_mfma_f32_16x16x32_bf16 v[94:97], v[164:167], v[196:199], v[94:97]
	v_mfma_f32_16x16x32_bf16 v[90:93], v[172:175], v[196:199], v[90:93]
	v_mfma_f32_16x16x32_bf16 v[86:89], v[164:167], v[204:207], v[86:89]
	v_mfma_f32_16x16x32_bf16 v[82:85], v[172:175], v[204:207], v[82:85]
	s_setprio 0
	s_barrier
	s_add_i32 s56, s46, s36
	v_lshl_add_u64 v[224:225], s[24:25], 0, v[132:133]
	s_mov_b32 m0, s56
	ds_read_b128 v[208:211], v163
	ds_read_b128 v[212:215], v163 offset:1024
	ds_read_b128 v[216:219], v163 offset:2048
	ds_read_b128 v[220:223], v163 offset:3072
	global_load_lds_dwordx4 v[224:225], off
	v_lshl_add_u64 v[226:227], s[24:25], 0, v[136:137]
	s_add_i32 m0, s56, 0x2000
	s_nop 0
	global_load_lds_dwordx4 v[226:227], off
	s_barrier
	s_waitcnt lgkmcnt(0)
	s_setprio 1
	s_waitcnt lgkmcnt(0)
	v_mfma_f32_16x16x32_bf16 v[110:113], v[208:211], v[176:179], v[110:113]
	v_mfma_f32_16x16x32_bf16 v[106:109], v[216:219], v[176:179], v[106:109]
	v_mfma_f32_16x16x32_bf16 v[102:105], v[208:211], v[184:187], v[102:105]
	v_mfma_f32_16x16x32_bf16 v[98:101], v[216:219], v[184:187], v[98:101]
	v_mfma_f32_16x16x32_bf16 v[78:81], v[208:211], v[192:195], v[78:81]
	v_mfma_f32_16x16x32_bf16 v[74:77], v[216:219], v[192:195], v[74:77]
	v_mfma_f32_16x16x32_bf16 v[70:73], v[208:211], v[200:203], v[70:73]
	v_mfma_f32_16x16x32_bf16 v[66:69], v[216:219], v[200:203], v[66:69]
	v_mfma_f32_16x16x32_bf16 v[110:113], v[212:215], v[180:183], v[110:113]
	v_mfma_f32_16x16x32_bf16 v[106:109], v[220:223], v[180:183], v[106:109]
	v_mfma_f32_16x16x32_bf16 v[102:105], v[212:215], v[188:191], v[102:105]
	v_mfma_f32_16x16x32_bf16 v[98:101], v[220:223], v[188:191], v[98:101]
	v_mfma_f32_16x16x32_bf16 v[78:81], v[212:215], v[196:199], v[78:81]
	v_mfma_f32_16x16x32_bf16 v[74:77], v[220:223], v[196:199], v[74:77]
	v_mfma_f32_16x16x32_bf16 v[70:73], v[212:215], v[204:207], v[70:73]
	v_mfma_f32_16x16x32_bf16 v[66:69], v[220:223], v[204:207], v[66:69]
	s_setprio 0
	s_mov_b32 m0, s21
	v_lshl_add_u64 v[228:229], s[26:27], 0, v[130:131]
	s_barrier
	ds_read_b128 v[176:179], v162 offset:16384
	ds_read_b128 v[180:183], v162 offset:17408
	ds_read_b128 v[184:187], v162 offset:18432
	ds_read_b128 v[188:191], v162 offset:19456
	ds_read_b128 v[192:195], v162 offset:20480
	ds_read_b128 v[196:199], v162 offset:21504
	ds_read_b128 v[200:203], v162 offset:22528
	ds_read_b128 v[204:207], v162 offset:23552
	global_load_lds_dwordx4 v[228:229], off
	v_lshl_add_u64 v[230:231], s[26:27], 0, v[134:135]
	s_mov_b32 m0, s37
	s_nop 0
	global_load_lds_dwordx4 v[230:231], off
	s_barrier
	s_waitcnt lgkmcnt(0)
	s_setprio 1
	s_waitcnt lgkmcnt(0)
	v_mfma_f32_16x16x32_bf16 v[62:65], v[150:153], v[176:179], v[62:65]
	v_mfma_f32_16x16x32_bf16 v[58:61], v[168:171], v[176:179], v[58:61]
	v_mfma_f32_16x16x32_bf16 v[54:57], v[150:153], v[184:187], v[54:57]
	v_mfma_f32_16x16x32_bf16 v[50:53], v[168:171], v[184:187], v[50:53]
	v_mfma_f32_16x16x32_bf16 v[30:33], v[150:153], v[192:195], v[30:33]
	v_mfma_f32_16x16x32_bf16 v[26:29], v[168:171], v[192:195], v[26:29]
	v_mfma_f32_16x16x32_bf16 v[22:25], v[150:153], v[200:203], v[22:25]
	v_mfma_f32_16x16x32_bf16 v[18:21], v[168:171], v[200:203], v[18:21]
	v_mfma_f32_16x16x32_bf16 v[62:65], v[164:167], v[180:183], v[62:65]
	v_mfma_f32_16x16x32_bf16 v[58:61], v[172:175], v[180:183], v[58:61]
	v_mfma_f32_16x16x32_bf16 v[54:57], v[164:167], v[188:191], v[54:57]
	v_mfma_f32_16x16x32_bf16 v[50:53], v[172:175], v[188:191], v[50:53]
	v_mfma_f32_16x16x32_bf16 v[30:33], v[164:167], v[196:199], v[30:33]
	v_mfma_f32_16x16x32_bf16 v[26:29], v[172:175], v[196:199], v[26:29]
	v_mfma_f32_16x16x32_bf16 v[22:25], v[164:167], v[204:207], v[22:25]
	v_mfma_f32_16x16x32_bf16 v[18:21], v[172:175], v[204:207], v[18:21]
	s_setprio 0
	s_barrier
	s_add_u32 s56, s24, 0x20000
	s_addc_u32 s57, s25, 0
	s_add_i32 s66, s47, s36
	v_lshl_add_u64 v[150:151], s[56:57], 0, v[132:133]
	s_mov_b32 m0, s66
	s_nop 0
	global_load_lds_dwordx4 v[150:151], off
	v_lshl_add_u64 v[150:151], s[56:57], 0, v[136:137]
	s_add_i32 m0, s66, 0x2000
	s_nop 0
	global_load_lds_dwordx4 v[150:151], off
	s_waitcnt vmcnt(6)
	s_barrier
	s_setprio 1
	v_mfma_f32_16x16x32_bf16 v[46:49], v[208:211], v[176:179], v[46:49]
	v_mfma_f32_16x16x32_bf16 v[42:45], v[216:219], v[176:179], v[42:45]
	v_mfma_f32_16x16x32_bf16 v[38:41], v[208:211], v[184:187], v[38:41]
	v_mfma_f32_16x16x32_bf16 v[34:37], v[216:219], v[184:187], v[34:37]
	v_mfma_f32_16x16x32_bf16 v[14:17], v[208:211], v[192:195], v[14:17]
	v_mfma_f32_16x16x32_bf16 v[10:13], v[216:219], v[192:195], v[10:13]
	v_mfma_f32_16x16x32_bf16 v[6:9], v[208:211], v[200:203], v[6:9]
	v_mfma_f32_16x16x32_bf16 v[2:5], v[216:219], v[200:203], v[2:5]
	v_mfma_f32_16x16x32_bf16 v[46:49], v[212:215], v[180:183], v[46:49]
	v_mfma_f32_16x16x32_bf16 v[42:45], v[220:223], v[180:183], v[42:45]
	v_mfma_f32_16x16x32_bf16 v[38:41], v[212:215], v[188:191], v[38:41]
	v_mfma_f32_16x16x32_bf16 v[34:37], v[220:223], v[188:191], v[34:37]
	v_mfma_f32_16x16x32_bf16 v[14:17], v[212:215], v[196:199], v[14:17]
	v_mfma_f32_16x16x32_bf16 v[10:13], v[220:223], v[196:199], v[10:13]
	v_mfma_f32_16x16x32_bf16 v[6:9], v[212:215], v[204:207], v[6:9]
	v_mfma_f32_16x16x32_bf16 v[2:5], v[220:223], v[204:207], v[2:5]
	s_setprio 0
	s_add_i32 s56, 0, 0x18000
	v_add_u32_e32 v172, s56, v160
	s_barrier
	ds_read_b128 v[150:153], v172
	ds_read_b128 v[164:167], v172 offset:1024
	ds_read_b128 v[168:171], v172 offset:2048
	ds_read_b128 v[172:175], v172 offset:3072
	s_add_u32 s26, s26, 0x20000
	s_addc_u32 s27, s27, 0
	s_mov_b32 m0, s38
	v_lshl_add_u64 v[208:209], s[26:27], 0, v[130:131]
	ds_read_b128 v[176:179], v162 offset:32768
	ds_read_b128 v[180:183], v162 offset:33792
	ds_read_b128 v[184:187], v162 offset:34816
	ds_read_b128 v[188:191], v162 offset:35840
	ds_read_b128 v[192:195], v162 offset:36864
	ds_read_b128 v[196:199], v162 offset:37888
	ds_read_b128 v[200:203], v162 offset:38912
	ds_read_b128 v[204:207], v162 offset:39936
	global_load_lds_dwordx4 v[208:209], off
	v_lshl_add_u64 v[208:209], s[26:27], 0, v[134:135]
	s_mov_b32 m0, s39
	s_nop 0
	global_load_lds_dwordx4 v[208:209], off
	s_waitcnt lgkmcnt(8)
	s_barrier
	s_waitcnt lgkmcnt(0)
	s_setprio 1
	s_waitcnt lgkmcnt(0)
	v_mfma_f32_16x16x32_bf16 v[126:129], v[150:153], v[176:179], v[126:129]
	v_mfma_f32_16x16x32_bf16 v[122:125], v[168:171], v[176:179], v[122:125]
	v_mfma_f32_16x16x32_bf16 v[118:121], v[150:153], v[184:187], v[118:121]
	v_mfma_f32_16x16x32_bf16 v[114:117], v[168:171], v[184:187], v[114:117]
	v_mfma_f32_16x16x32_bf16 v[94:97], v[150:153], v[192:195], v[94:97]
	v_mfma_f32_16x16x32_bf16 v[90:93], v[168:171], v[192:195], v[90:93]
	v_mfma_f32_16x16x32_bf16 v[86:89], v[150:153], v[200:203], v[86:89]
	v_mfma_f32_16x16x32_bf16 v[82:85], v[168:171], v[200:203], v[82:85]
	v_mfma_f32_16x16x32_bf16 v[126:129], v[164:167], v[180:183], v[126:129]
	v_mfma_f32_16x16x32_bf16 v[122:125], v[172:175], v[180:183], v[122:125]
	v_mfma_f32_16x16x32_bf16 v[118:121], v[164:167], v[188:191], v[118:121]
	v_mfma_f32_16x16x32_bf16 v[114:117], v[172:175], v[188:191], v[114:117]
	v_mfma_f32_16x16x32_bf16 v[94:97], v[164:167], v[196:199], v[94:97]
	v_mfma_f32_16x16x32_bf16 v[90:93], v[172:175], v[196:199], v[90:93]
	v_mfma_f32_16x16x32_bf16 v[86:89], v[164:167], v[204:207], v[86:89]
	v_mfma_f32_16x16x32_bf16 v[82:85], v[172:175], v[204:207], v[82:85]
	s_setprio 0
	s_barrier
	s_add_i32 s26, 0, 0x1c000
	s_add_i32 s27, s56, s36
	v_add_u32_e32 v220, s26, v160
	v_lshl_add_u64 v[224:225], v[224:225], 0, s[10:11]
	s_mov_b32 m0, s27
	ds_read_b128 v[208:211], v220
	ds_read_b128 v[212:215], v220 offset:1024
	ds_read_b128 v[216:219], v220 offset:2048
	ds_read_b128 v[220:223], v220 offset:3072
	global_load_lds_dwordx4 v[224:225], off
	v_lshl_add_u64 v[224:225], v[226:227], 0, s[10:11]
	s_add_i32 m0, s27, 0x2000
	s_nop 0
	global_load_lds_dwordx4 v[224:225], off
	s_barrier
	s_waitcnt lgkmcnt(0)
	s_setprio 1
	s_waitcnt lgkmcnt(0)
	v_mfma_f32_16x16x32_bf16 v[110:113], v[208:211], v[176:179], v[110:113]
	v_mfma_f32_16x16x32_bf16 v[106:109], v[216:219], v[176:179], v[106:109]
	v_mfma_f32_16x16x32_bf16 v[102:105], v[208:211], v[184:187], v[102:105]
	v_mfma_f32_16x16x32_bf16 v[98:101], v[216:219], v[184:187], v[98:101]
	v_mfma_f32_16x16x32_bf16 v[78:81], v[208:211], v[192:195], v[78:81]
	v_mfma_f32_16x16x32_bf16 v[74:77], v[216:219], v[192:195], v[74:77]
	v_mfma_f32_16x16x32_bf16 v[70:73], v[208:211], v[200:203], v[70:73]
	v_mfma_f32_16x16x32_bf16 v[66:69], v[216:219], v[200:203], v[66:69]
	v_mfma_f32_16x16x32_bf16 v[110:113], v[212:215], v[180:183], v[110:113]
	v_mfma_f32_16x16x32_bf16 v[106:109], v[220:223], v[180:183], v[106:109]
	v_mfma_f32_16x16x32_bf16 v[102:105], v[212:215], v[188:191], v[102:105]
	v_mfma_f32_16x16x32_bf16 v[98:101], v[220:223], v[188:191], v[98:101]
	v_mfma_f32_16x16x32_bf16 v[78:81], v[212:215], v[196:199], v[78:81]
	v_mfma_f32_16x16x32_bf16 v[74:77], v[220:223], v[196:199], v[74:77]
	v_mfma_f32_16x16x32_bf16 v[70:73], v[212:215], v[204:207], v[70:73]
	v_mfma_f32_16x16x32_bf16 v[66:69], v[220:223], v[204:207], v[66:69]
	s_setprio 0
	s_mov_b32 m0, s41
	v_lshl_add_u64 v[224:225], v[228:229], 0, s[10:11]
	s_barrier
	ds_read_b128 v[176:179], v162 offset:49152
	ds_read_b128 v[180:183], v162 offset:50176
	ds_read_b128 v[184:187], v162 offset:51200
	ds_read_b128 v[188:191], v162 offset:52224
	ds_read_b128 v[192:195], v162 offset:53248
	ds_read_b128 v[196:199], v162 offset:54272
	ds_read_b128 v[200:203], v162 offset:55296
	ds_read_b128 v[204:207], v162 offset:56320
	global_load_lds_dwordx4 v[224:225], off
	v_lshl_add_u64 v[224:225], v[230:231], 0, s[10:11]
	s_mov_b32 m0, s42
	s_nop 0
	global_load_lds_dwordx4 v[224:225], off
	s_barrier
	s_waitcnt lgkmcnt(0)
	s_setprio 1
	s_waitcnt lgkmcnt(0)
	v_mfma_f32_16x16x32_bf16 v[62:65], v[150:153], v[176:179], v[62:65]
	v_mfma_f32_16x16x32_bf16 v[58:61], v[168:171], v[176:179], v[58:61]
	v_mfma_f32_16x16x32_bf16 v[54:57], v[150:153], v[184:187], v[54:57]
	v_mfma_f32_16x16x32_bf16 v[50:53], v[168:171], v[184:187], v[50:53]
	v_mfma_f32_16x16x32_bf16 v[30:33], v[150:153], v[192:195], v[30:33]
	v_mfma_f32_16x16x32_bf16 v[26:29], v[168:171], v[192:195], v[26:29]
	v_mfma_f32_16x16x32_bf16 v[22:25], v[150:153], v[200:203], v[22:25]
	v_mfma_f32_16x16x32_bf16 v[18:21], v[168:171], v[200:203], v[18:21]
	v_mfma_f32_16x16x32_bf16 v[62:65], v[164:167], v[180:183], v[62:65]
	v_mfma_f32_16x16x32_bf16 v[58:61], v[172:175], v[180:183], v[58:61]
	v_mfma_f32_16x16x32_bf16 v[54:57], v[164:167], v[188:191], v[54:57]
	v_mfma_f32_16x16x32_bf16 v[50:53], v[172:175], v[188:191], v[50:53]
	v_mfma_f32_16x16x32_bf16 v[30:33], v[164:167], v[196:199], v[30:33]
	v_mfma_f32_16x16x32_bf16 v[26:29], v[172:175], v[196:199], v[26:29]
	v_mfma_f32_16x16x32_bf16 v[22:25], v[164:167], v[204:207], v[22:25]
	v_mfma_f32_16x16x32_bf16 v[18:21], v[172:175], v[204:207], v[18:21]
	s_setprio 0
	s_barrier
	s_add_u32 s24, s24, 0x20080
	s_addc_u32 s25, s25, 0
	s_add_i32 s26, s26, s36
	v_lshl_add_u64 v[150:151], s[24:25], 0, v[132:133]
	s_mov_b32 m0, s26
	s_nop 0
	global_load_lds_dwordx4 v[150:151], off
	v_lshl_add_u64 v[150:151], s[24:25], 0, v[136:137]
	s_add_i32 m0, s26, 0x2000
	s_nop 0
	global_load_lds_dwordx4 v[150:151], off
	s_waitcnt vmcnt(6)
	s_barrier
	s_setprio 1
	v_mfma_f32_16x16x32_bf16 v[46:49], v[208:211], v[176:179], v[46:49]
	v_mfma_f32_16x16x32_bf16 v[42:45], v[216:219], v[176:179], v[42:45]
	v_mfma_f32_16x16x32_bf16 v[38:41], v[208:211], v[184:187], v[38:41]
	v_mfma_f32_16x16x32_bf16 v[34:37], v[216:219], v[184:187], v[34:37]
	v_mfma_f32_16x16x32_bf16 v[14:17], v[208:211], v[192:195], v[14:17]
	v_mfma_f32_16x16x32_bf16 v[10:13], v[216:219], v[192:195], v[10:13]
	v_mfma_f32_16x16x32_bf16 v[6:9], v[208:211], v[200:203], v[6:9]
	v_mfma_f32_16x16x32_bf16 v[2:5], v[216:219], v[200:203], v[2:5]
	v_mfma_f32_16x16x32_bf16 v[46:49], v[212:215], v[180:183], v[46:49]
	v_mfma_f32_16x16x32_bf16 v[42:45], v[220:223], v[180:183], v[42:45]
	v_mfma_f32_16x16x32_bf16 v[38:41], v[212:215], v[188:191], v[38:41]
	v_mfma_f32_16x16x32_bf16 v[34:37], v[220:223], v[188:191], v[34:37]
	v_mfma_f32_16x16x32_bf16 v[14:17], v[212:215], v[196:199], v[14:17]
	v_mfma_f32_16x16x32_bf16 v[10:13], v[220:223], v[196:199], v[10:13]
	v_mfma_f32_16x16x32_bf16 v[6:9], v[212:215], v[204:207], v[6:9]
	v_mfma_f32_16x16x32_bf16 v[2:5], v[220:223], v[204:207], v[2:5]
	s_setprio 0
	s_add_i32 s55, s55, 2
	s_add_u32 s22, s22, 0x100
	s_addc_u32 s23, s23, 0
	s_add_u32 s53, s53, 0x100
	s_addc_u32 s54, s54, 0
	s_cmp_gt_u32 s55, 5
	s_barrier
	s_cbranch_scc0 .LBB0_731
	v_readfirstlane_b32 s99, v0
	s_cmpk_gt_u32 s99, 0xff
	s_cbranch_scc1 .Lxb_p5a_a
	s_barrier
.Lxb_p5a_a:
	s_lshl_b32 s13, s20, 3
	s_add_i32 s22, s13, s50
	s_ashr_i32 s23, s22, 31
	s_lshl_b64 s[24:25], s[22:23], 17
	v_lshl_add_u64 v[150:151], v[138:139], 0, s[24:25]
	global_load_dwordx4 v[164:167], v[150:151], off
	global_load_dwordx4 v[168:171], v[150:151], off offset:1024
	global_load_dwordx4 v[172:175], v[150:151], off offset:2048
	global_load_dwordx4 v[176:179], v[150:151], off offset:3072
	s_lshl_b32 s13, s20, 2
	s_sub_i32 s22, s22, s13
	s_ashr_i32 s23, s22, 31
	s_lshl_b64 s[22:23], s[22:23], 17
	v_lshl_add_u64 v[152:153], v[140:141], 0, s[22:23]
	s_waitcnt vmcnt(0)
	v_lshlrev_b32_e32 v180, 16, v164
	v_and_b32_e32 v181, 0xffff0000, v164
	v_lshlrev_b32_e32 v164, 16, v165
	v_and_b32_e32 v165, 0xffff0000, v165
	v_lshlrev_b32_e32 v182, 16, v166
	v_and_b32_e32 v183, 0xffff0000, v166
	v_lshlrev_b32_e32 v166, 16, v167
	v_and_b32_e32 v167, 0xffff0000, v167
	v_lshlrev_b32_e32 v184, 16, v168
	v_and_b32_e32 v185, 0xffff0000, v168
	v_lshlrev_b32_e32 v168, 16, v169
	v_and_b32_e32 v169, 0xffff0000, v169
	v_lshlrev_b32_e32 v186, 16, v170
	v_and_b32_e32 v187, 0xffff0000, v170
	v_lshlrev_b32_e32 v170, 16, v171
	v_and_b32_e32 v171, 0xffff0000, v171
	v_lshlrev_b32_e32 v188, 16, v172
	v_and_b32_e32 v189, 0xffff0000, v172
	v_lshlrev_b32_e32 v172, 16, v173
	v_and_b32_e32 v173, 0xffff0000, v173
	v_lshlrev_b32_e32 v190, 16, v174
	v_and_b32_e32 v191, 0xffff0000, v174
	v_lshlrev_b32_e32 v174, 16, v175
	v_and_b32_e32 v175, 0xffff0000, v175
	v_lshlrev_b32_e32 v192, 16, v176
	v_and_b32_e32 v193, 0xffff0000, v176
	v_lshlrev_b32_e32 v176, 16, v177
	v_and_b32_e32 v177, 0xffff0000, v177
	v_lshlrev_b32_e32 v194, 16, v178
	v_and_b32_e32 v195, 0xffff0000, v178
	v_lshlrev_b32_e32 v178, 16, v179
	v_and_b32_e32 v179, 0xffff0000, v179
	v_pk_mul_f32 v[126:127], v[126:127], v[180:181]
	v_pk_mul_f32 v[128:129], v[128:129], v[164:165]
	v_pk_mul_f32 v[122:123], v[122:123], v[182:183]
	v_pk_mul_f32 v[124:125], v[124:125], v[166:167]
	v_pk_mul_f32 v[110:111], v[110:111], v[184:185]
	v_pk_mul_f32 v[112:113], v[112:113], v[168:169]
	v_pk_mul_f32 v[106:107], v[106:107], v[186:187]
	v_pk_mul_f32 v[108:109], v[108:109], v[170:171]
	v_pk_mul_f32 v[118:119], v[118:119], v[188:189]
	v_pk_mul_f32 v[120:121], v[120:121], v[172:173]
	v_pk_mul_f32 v[114:115], v[114:115], v[190:191]
	v_pk_mul_f32 v[116:117], v[116:117], v[174:175]
	v_pk_mul_f32 v[164:165], v[102:103], v[192:193]
	v_pk_mul_f32 v[166:167], v[104:105], v[176:177]
	v_pk_mul_f32 v[168:169], v[98:99], v[194:195]
	v_pk_mul_f32 v[170:171], v[100:101], v[178:179]
	v_cvt_pk_bf16_f32 v98, v126, v127
	v_cvt_pk_bf16_f32 v99, v128, v129
	v_cvt_pk_bf16_f32 v100, v122, v123
	v_cvt_pk_bf16_f32 v101, v124, v125
	v_cvt_pk_bf16_f32 v102, v110, v111
	v_cvt_pk_bf16_f32 v103, v112, v113
	v_cvt_pk_bf16_f32 v104, v106, v107
	v_cvt_pk_bf16_f32 v105, v108, v109
	v_cvt_pk_bf16_f32 v106, v118, v119
	v_cvt_pk_bf16_f32 v107, v120, v121
	v_cvt_pk_bf16_f32 v108, v114, v115
	v_cvt_pk_bf16_f32 v109, v116, v117
	v_cvt_pk_bf16_f32 v110, v164, v165
	v_cvt_pk_bf16_f32 v111, v166, v167
	v_cvt_pk_bf16_f32 v112, v168, v169
	v_cvt_pk_bf16_f32 v113, v170, v171
	global_store_dwordx4 v[152:153], v[98:101], off
	global_store_dwordx4 v[152:153], v[102:105], off offset:1024
	global_store_dwordx4 v[152:153], v[106:109], off offset:2048
	global_store_dwordx4 v[152:153], v[110:113], off offset:3072
	v_add_co_u32_e32 v116, vcc, s40, v150
	s_nop 1
	v_addc_co_u32_e32 v117, vcc, 0, v151, vcc
	v_add_co_u32_e32 v98, vcc, s48, v150
	global_load_dwordx4 v[100:103], v[116:117], off offset:-4096
	s_nop 0
	v_addc_co_u32_e32 v99, vcc, 0, v151, vcc
	global_load_dwordx4 v[104:107], v[98:99], off offset:1024
	global_load_dwordx4 v[108:111], v[98:99], off offset:2048
	global_load_dwordx4 v[112:115], v[98:99], off offset:3072
	v_add_co_u32_e32 v118, vcc, s48, v152
	s_waitcnt vmcnt(0)
	v_lshlrev_b32_e32 v120, 16, v100
	v_addc_co_u32_e32 v119, vcc, 0, v153, vcc
	v_and_b32_e32 v121, 0xffff0000, v100
	v_lshlrev_b32_e32 v100, 16, v101
	v_and_b32_e32 v101, 0xffff0000, v101
	v_lshlrev_b32_e32 v122, 16, v102
	v_and_b32_e32 v123, 0xffff0000, v102
	v_lshlrev_b32_e32 v102, 16, v103
	v_and_b32_e32 v103, 0xffff0000, v103
	v_lshlrev_b32_e32 v124, 16, v104
	v_and_b32_e32 v125, 0xffff0000, v104
	v_lshlrev_b32_e32 v104, 16, v105
	v_and_b32_e32 v105, 0xffff0000, v105
	v_lshlrev_b32_e32 v126, 16, v106
	v_and_b32_e32 v127, 0xffff0000, v106
	v_lshlrev_b32_e32 v106, 16, v107
	v_and_b32_e32 v107, 0xffff0000, v107
	v_lshlrev_b32_e32 v166, 16, v112
	v_and_b32_e32 v167, 0xffff0000, v112
	v_lshlrev_b32_e32 v112, 16, v113
	v_and_b32_e32 v113, 0xffff0000, v113
	v_lshlrev_b32_e32 v168, 16, v114
	v_and_b32_e32 v169, 0xffff0000, v114
	v_lshlrev_b32_e32 v114, 16, v115
	v_and_b32_e32 v115, 0xffff0000, v115
	v_add_co_u32_e32 v98, vcc, s40, v152
	v_lshlrev_b32_e32 v128, 16, v108
	v_and_b32_e32 v129, 0xffff0000, v108
	v_lshlrev_b32_e32 v108, 16, v109
	v_and_b32_e32 v109, 0xffff0000, v109
	v_lshlrev_b32_e32 v164, 16, v110
	v_and_b32_e32 v165, 0xffff0000, v110
	v_lshlrev_b32_e32 v110, 16, v111
	v_and_b32_e32 v111, 0xffff0000, v111
	v_pk_mul_f32 v[94:95], v[94:95], v[120:121]
	v_pk_mul_f32 v[96:97], v[96:97], v[100:101]
	v_pk_mul_f32 v[90:91], v[90:91], v[122:123]
	v_pk_mul_f32 v[92:93], v[92:93], v[102:103]
	v_pk_mul_f32 v[78:79], v[78:79], v[124:125]
	v_pk_mul_f32 v[80:81], v[80:81], v[104:105]
	v_pk_mul_f32 v[76:77], v[76:77], v[106:107]
	v_pk_mul_f32 v[100:101], v[70:71], v[166:167]
	v_pk_mul_f32 v[102:103], v[72:73], v[112:113]
	v_pk_mul_f32 v[104:105], v[66:67], v[168:169]
	v_pk_mul_f32 v[106:107], v[68:69], v[114:115]
	v_addc_co_u32_e32 v99, vcc, 0, v153, vcc
	v_pk_mul_f32 v[74:75], v[74:75], v[126:127]
	v_pk_mul_f32 v[86:87], v[86:87], v[128:129]
	v_pk_mul_f32 v[88:89], v[88:89], v[108:109]
	v_pk_mul_f32 v[82:83], v[82:83], v[164:165]
	v_pk_mul_f32 v[84:85], v[84:85], v[110:111]
	v_cvt_pk_bf16_f32 v66, v94, v95
	v_cvt_pk_bf16_f32 v67, v96, v97
	v_cvt_pk_bf16_f32 v68, v90, v91
	v_cvt_pk_bf16_f32 v69, v92, v93
	v_cvt_pk_bf16_f32 v70, v78, v79
	v_cvt_pk_bf16_f32 v71, v80, v81
	v_cvt_pk_bf16_f32 v78, v100, v101
	v_cvt_pk_bf16_f32 v79, v102, v103
	v_cvt_pk_bf16_f32 v80, v104, v105
	v_cvt_pk_bf16_f32 v81, v106, v107
	v_cvt_pk_bf16_f32 v72, v74, v75
	v_cvt_pk_bf16_f32 v73, v76, v77
	v_cvt_pk_bf16_f32 v74, v86, v87
	v_cvt_pk_bf16_f32 v75, v88, v89
	v_cvt_pk_bf16_f32 v76, v82, v83
	v_cvt_pk_bf16_f32 v77, v84, v85
	global_store_dwordx4 v[98:99], v[66:69], off offset:-4096
	global_store_dwordx4 v[118:119], v[70:73], off offset:1024
	global_store_dwordx4 v[118:119], v[74:77], off offset:2048
	global_store_dwordx4 v[118:119], v[78:81], off offset:3072
	global_load_dwordx4 v[66:69], v[116:117], off
	s_nop 0
	global_load_dwordx4 v[70:73], v[116:117], off offset:1024
	global_load_dwordx4 v[74:77], v[116:117], off offset:2048
	global_load_dwordx4 v[78:81], v[116:117], off offset:3072
	s_waitcnt vmcnt(0)
	v_lshlrev_b32_e32 v82, 16, v66
	v_and_b32_e32 v83, 0xffff0000, v66
	v_lshlrev_b32_e32 v66, 16, v67
	v_and_b32_e32 v67, 0xffff0000, v67
	v_lshlrev_b32_e32 v84, 16, v68
	v_and_b32_e32 v85, 0xffff0000, v68
	v_lshlrev_b32_e32 v68, 16, v69
	v_and_b32_e32 v69, 0xffff0000, v69
	v_lshlrev_b32_e32 v86, 16, v70
	v_and_b32_e32 v87, 0xffff0000, v70
	v_lshlrev_b32_e32 v70, 16, v71
	v_and_b32_e32 v71, 0xffff0000, v71
	v_lshlrev_b32_e32 v88, 16, v72
	v_and_b32_e32 v89, 0xffff0000, v72
	v_lshlrev_b32_e32 v72, 16, v73
	v_and_b32_e32 v73, 0xffff0000, v73
	v_lshlrev_b32_e32 v90, 16, v74
	v_and_b32_e32 v91, 0xffff0000, v74
	v_lshlrev_b32_e32 v74, 16, v75
	v_and_b32_e32 v75, 0xffff0000, v75
	v_lshlrev_b32_e32 v92, 16, v76
	v_and_b32_e32 v93, 0xffff0000, v76
	v_lshlrev_b32_e32 v76, 16, v77
	v_and_b32_e32 v77, 0xffff0000, v77
	v_lshlrev_b32_e32 v94, 16, v78
	v_and_b32_e32 v95, 0xffff0000, v78
	v_lshlrev_b32_e32 v78, 16, v79
	v_and_b32_e32 v79, 0xffff0000, v79
	v_lshlrev_b32_e32 v96, 16, v80
	v_and_b32_e32 v97, 0xffff0000, v80
	v_lshlrev_b32_e32 v80, 16, v81
	v_and_b32_e32 v81, 0xffff0000, v81
	v_pk_mul_f32 v[62:63], v[62:63], v[82:83]
	v_pk_mul_f32 v[64:65], v[64:65], v[66:67]
	v_pk_mul_f32 v[58:59], v[58:59], v[84:85]
	v_pk_mul_f32 v[60:61], v[60:61], v[68:69]
	v_pk_mul_f32 v[46:47], v[46:47], v[86:87]
	v_pk_mul_f32 v[48:49], v[48:49], v[70:71]
	v_pk_mul_f32 v[42:43], v[42:43], v[88:89]
	v_pk_mul_f32 v[44:45], v[44:45], v[72:73]
	v_pk_mul_f32 v[54:55], v[54:55], v[90:91]
	v_pk_mul_f32 v[56:57], v[56:57], v[74:75]
	v_pk_mul_f32 v[50:51], v[50:51], v[92:93]
	v_pk_mul_f32 v[52:53], v[52:53], v[76:77]
	v_pk_mul_f32 v[66:67], v[38:39], v[94:95]
	v_pk_mul_f32 v[68:69], v[40:41], v[78:79]
	v_pk_mul_f32 v[70:71], v[34:35], v[96:97]
	v_pk_mul_f32 v[72:73], v[36:37], v[80:81]
	v_cvt_pk_bf16_f32 v34, v62, v63
	v_cvt_pk_bf16_f32 v35, v64, v65
	v_cvt_pk_bf16_f32 v36, v58, v59
	v_cvt_pk_bf16_f32 v37, v60, v61
	v_cvt_pk_bf16_f32 v38, v46, v47
	v_cvt_pk_bf16_f32 v39, v48, v49
	v_cvt_pk_bf16_f32 v40, v42, v43
	v_cvt_pk_bf16_f32 v41, v44, v45
	v_cvt_pk_bf16_f32 v42, v54, v55
	v_cvt_pk_bf16_f32 v43, v56, v57
	v_cvt_pk_bf16_f32 v44, v50, v51
	v_cvt_pk_bf16_f32 v45, v52, v53
	v_cvt_pk_bf16_f32 v46, v66, v67
	v_cvt_pk_bf16_f32 v47, v68, v69
	v_cvt_pk_bf16_f32 v48, v70, v71
	v_cvt_pk_bf16_f32 v49, v72, v73
	global_store_dwordx4 v[98:99], v[34:37], off
	global_store_dwordx4 v[98:99], v[38:41], off offset:1024
	global_store_dwordx4 v[98:99], v[42:45], off offset:2048
	global_store_dwordx4 v[98:99], v[46:49], off offset:3072
	s_nop 1
	v_add_co_u32_e32 v46, vcc, s49, v150
	s_nop 1
	v_addc_co_u32_e32 v47, vcc, 0, v151, vcc
	global_load_dwordx4 v[34:37], v[46:47], off
	global_load_dwordx4 v[38:41], v[46:47], off offset:1024
	global_load_dwordx4 v[42:45], v[46:47], off offset:2048
	s_nop 0
	global_load_dwordx4 v[46:49], v[46:47], off offset:3072
	v_add_co_u32_e32 v50, vcc, s49, v152
	s_waitcnt vmcnt(0)
	v_lshlrev_b32_e32 v52, 16, v34
	v_and_b32_e32 v53, 0xffff0000, v34
	v_lshlrev_b32_e32 v34, 16, v35
	v_and_b32_e32 v35, 0xffff0000, v35
	v_lshlrev_b32_e32 v54, 16, v36
	v_and_b32_e32 v55, 0xffff0000, v36
	v_lshlrev_b32_e32 v36, 16, v37
	v_and_b32_e32 v37, 0xffff0000, v37
	v_lshlrev_b32_e32 v56, 16, v38
	v_and_b32_e32 v57, 0xffff0000, v38
	v_lshlrev_b32_e32 v38, 16, v39
	v_and_b32_e32 v39, 0xffff0000, v39
	v_lshlrev_b32_e32 v58, 16, v40
	v_and_b32_e32 v59, 0xffff0000, v40
	v_lshlrev_b32_e32 v40, 16, v41
	v_and_b32_e32 v41, 0xffff0000, v41
	v_lshlrev_b32_e32 v60, 16, v42
	v_and_b32_e32 v61, 0xffff0000, v42
	v_lshlrev_b32_e32 v42, 16, v43
	v_and_b32_e32 v43, 0xffff0000, v43
	v_lshlrev_b32_e32 v62, 16, v44
	v_and_b32_e32 v63, 0xffff0000, v44
	v_lshlrev_b32_e32 v44, 16, v45
	v_and_b32_e32 v45, 0xffff0000, v45
	v_lshlrev_b32_e32 v64, 16, v46
	v_and_b32_e32 v65, 0xffff0000, v46
	v_lshlrev_b32_e32 v46, 16, v47
	v_and_b32_e32 v47, 0xffff0000, v47
	v_lshlrev_b32_e32 v66, 16, v48
	v_and_b32_e32 v67, 0xffff0000, v48
	v_lshlrev_b32_e32 v48, 16, v49
	v_and_b32_e32 v49, 0xffff0000, v49
	v_pk_mul_f32 v[30:31], v[30:31], v[52:53]
	v_pk_mul_f32 v[32:33], v[32:33], v[34:35]
	v_pk_mul_f32 v[26:27], v[26:27], v[54:55]
	v_pk_mul_f32 v[28:29], v[28:29], v[36:37]
	v_addc_co_u32_e32 v51, vcc, 0, v153, vcc
	v_pk_mul_f32 v[14:15], v[14:15], v[56:57]
	v_pk_mul_f32 v[16:17], v[16:17], v[38:39]
	v_pk_mul_f32 v[10:11], v[10:11], v[58:59]
	v_pk_mul_f32 v[12:13], v[12:13], v[40:41]
	v_pk_mul_f32 v[22:23], v[22:23], v[60:61]
	v_pk_mul_f32 v[24:25], v[24:25], v[42:43]
	v_pk_mul_f32 v[18:19], v[18:19], v[62:63]
	v_pk_mul_f32 v[20:21], v[20:21], v[44:45]
	v_pk_mul_f32 v[34:35], v[6:7], v[64:65]
	v_pk_mul_f32 v[36:37], v[8:9], v[46:47]
	v_pk_mul_f32 v[38:39], v[2:3], v[66:67]
	v_pk_mul_f32 v[40:41], v[4:5], v[48:49]
	v_cvt_pk_bf16_f32 v2, v30, v31
	v_cvt_pk_bf16_f32 v3, v32, v33
	v_cvt_pk_bf16_f32 v4, v26, v27
	v_cvt_pk_bf16_f32 v5, v28, v29
	v_cvt_pk_bf16_f32 v6, v14, v15
	v_cvt_pk_bf16_f32 v7, v16, v17
	v_cvt_pk_bf16_f32 v8, v10, v11
	v_cvt_pk_bf16_f32 v9, v12, v13
	v_cvt_pk_bf16_f32 v10, v22, v23
	v_cvt_pk_bf16_f32 v11, v24, v25
	v_cvt_pk_bf16_f32 v12, v18, v19
	v_cvt_pk_bf16_f32 v13, v20, v21
	v_cvt_pk_bf16_f32 v14, v34, v35
	v_cvt_pk_bf16_f32 v15, v36, v37
	v_cvt_pk_bf16_f32 v16, v38, v39
	v_cvt_pk_bf16_f32 v17, v40, v41
	global_store_dwordx4 v[50:51], v[2:5], off
	global_store_dwordx4 v[50:51], v[6:9], off offset:1024
	global_store_dwordx4 v[50:51], v[10:13], off offset:2048
	global_store_dwordx4 v[50:51], v[14:17], off offset:3072
	v_readfirstlane_b32 s99, v0
	s_cmpk_lt_u32 s99, 0x100
	s_cbranch_scc1 .Lxb_p5a_b
	s_barrier
.Lxb_p5a_b:
	s_and_b64 vcc, exec, s[2:3]
	s_mov_b32 s50, s12
	s_mov_b32 s20, s14
	s_mov_b64 s[24:25], s[18:19]
	s_mov_b64 s[22:23], s[16:17]
	s_cbranch_vccz .LBB0_724
	s_waitcnt vmcnt(0)
	s_cmpk_gt_u32 s28, 0xff
	s_cbranch_scc1 .LBB0_735
	s_barrier

.LBB0_751:
	ds_read_b128 v[150:153], v1
	ds_read_b128 v[154:157], v1 offset:1024
	ds_read_b128 v[166:169], v1 offset:2048
	ds_read_b128 v[170:173], v1 offset:3072
	s_add_u32 s30, s28, 0xfffe0080
	s_addc_u32 s31, s29, -1
	s_cmp_eq_u32 s73, 4
	s_cselect_b32 s35, s21, s31
	s_cselect_b32 s34, s69, s30
	s_cselect_b32 s31, s19, s72
	s_cselect_b32 s30, s70, s71
	v_lshl_add_u64 v[158:159], s[28:29], 0, v[142:143]
	s_add_i32 m0, s27, 0xc000
	ds_read_b128 v[174:177], v163
	ds_read_b128 v[178:181], v163 offset:1024
	ds_read_b128 v[182:185], v163 offset:2048
	ds_read_b128 v[186:189], v163 offset:3072
	ds_read_b128 v[190:193], v163 offset:4096
	ds_read_b128 v[194:197], v163 offset:5120
	ds_read_b128 v[198:201], v163 offset:6144
	ds_read_b128 v[202:205], v163 offset:7168
	global_load_lds_dwordx4 v[158:159], off
	v_lshl_add_u64 v[158:159], s[28:29], 0, v[144:145]
	s_add_i32 m0, s27, 0xe000
	s_nop 0
	global_load_lds_dwordx4 v[158:159], off
	s_waitcnt lgkmcnt(8)
	s_barrier
	s_waitcnt lgkmcnt(0)
	s_setprio 1
	s_waitcnt lgkmcnt(0)
	v_mfma_f32_16x16x32_bf16 v[126:129], v[150:153], v[174:177], v[126:129]
	v_mfma_f32_16x16x32_bf16 v[122:125], v[166:169], v[174:177], v[122:125]
	v_mfma_f32_16x16x32_bf16 v[118:121], v[150:153], v[182:185], v[118:121]
	v_mfma_f32_16x16x32_bf16 v[106:109], v[166:169], v[182:185], v[106:109]
	v_mfma_f32_16x16x32_bf16 v[94:97], v[150:153], v[190:193], v[94:97]
	v_mfma_f32_16x16x32_bf16 v[90:93], v[166:169], v[190:193], v[90:93]
	v_mfma_f32_16x16x32_bf16 v[82:85], v[150:153], v[198:201], v[82:85]
	v_mfma_f32_16x16x32_bf16 v[74:77], v[166:169], v[198:201], v[74:77]
	v_mfma_f32_16x16x32_bf16 v[126:129], v[154:157], v[178:181], v[126:129]
	v_mfma_f32_16x16x32_bf16 v[122:125], v[170:173], v[178:181], v[122:125]
	v_mfma_f32_16x16x32_bf16 v[118:121], v[154:157], v[186:189], v[118:121]
	v_mfma_f32_16x16x32_bf16 v[106:109], v[170:173], v[186:189], v[106:109]
	v_mfma_f32_16x16x32_bf16 v[94:97], v[154:157], v[194:197], v[94:97]
	v_mfma_f32_16x16x32_bf16 v[90:93], v[170:173], v[194:197], v[90:93]
	v_mfma_f32_16x16x32_bf16 v[82:85], v[154:157], v[202:205], v[82:85]
	v_mfma_f32_16x16x32_bf16 v[74:77], v[170:173], v[202:205], v[74:77]
	s_setprio 0
	s_barrier
	s_add_i32 s74, s52, s42
	v_lshl_add_u64 v[158:159], s[30:31], 0, v[132:133]
	s_mov_b32 m0, s74
	ds_read_b128 v[206:209], v164
	ds_read_b128 v[210:213], v164 offset:1024
	ds_read_b128 v[214:217], v164 offset:2048
	ds_read_b128 v[218:221], v164 offset:3072
	global_load_lds_dwordx4 v[158:159], off
	v_lshl_add_u64 v[222:223], s[30:31], 0, v[136:137]
	s_add_i32 m0, s74, 0x2000
	s_nop 0
	global_load_lds_dwordx4 v[222:223], off
	s_barrier
	s_waitcnt lgkmcnt(0)
	s_setprio 1
	s_waitcnt lgkmcnt(0)
	v_mfma_f32_16x16x32_bf16 v[114:117], v[206:209], v[174:177], v[114:117]
	v_mfma_f32_16x16x32_bf16 v[110:113], v[214:217], v[174:177], v[110:113]
	v_mfma_f32_16x16x32_bf16 v[102:105], v[206:209], v[182:185], v[102:105]
	v_mfma_f32_16x16x32_bf16 v[98:101], v[214:217], v[182:185], v[98:101]
	v_mfma_f32_16x16x32_bf16 v[86:89], v[206:209], v[190:193], v[86:89]
	v_mfma_f32_16x16x32_bf16 v[78:81], v[214:217], v[190:193], v[78:81]
	v_mfma_f32_16x16x32_bf16 v[70:73], v[206:209], v[198:201], v[70:73]
	v_mfma_f32_16x16x32_bf16 v[66:69], v[214:217], v[198:201], v[66:69]
	v_mfma_f32_16x16x32_bf16 v[114:117], v[210:213], v[178:181], v[114:117]
	v_mfma_f32_16x16x32_bf16 v[110:113], v[218:221], v[178:181], v[110:113]
	v_mfma_f32_16x16x32_bf16 v[102:105], v[210:213], v[186:189], v[102:105]
	v_mfma_f32_16x16x32_bf16 v[98:101], v[218:221], v[186:189], v[98:101]
	v_mfma_f32_16x16x32_bf16 v[86:89], v[210:213], v[194:197], v[86:89]
	v_mfma_f32_16x16x32_bf16 v[78:81], v[218:221], v[194:197], v[78:81]
	v_mfma_f32_16x16x32_bf16 v[70:73], v[210:213], v[202:205], v[70:73]
	v_mfma_f32_16x16x32_bf16 v[66:69], v[218:221], v[202:205], v[66:69]
	s_setprio 0
	s_mov_b32 m0, s27
	v_lshl_add_u64 v[224:225], s[34:35], 0, v[130:131]
	s_barrier
	ds_read_b128 v[174:177], v163 offset:16384
	ds_read_b128 v[178:181], v163 offset:17408
	ds_read_b128 v[182:185], v163 offset:18432
	ds_read_b128 v[186:189], v163 offset:19456
	ds_read_b128 v[190:193], v163 offset:20480
	ds_read_b128 v[194:197], v163 offset:21504
	ds_read_b128 v[198:201], v163 offset:22528
	ds_read_b128 v[202:205], v163 offset:23552
	global_load_lds_dwordx4 v[224:225], off
	v_lshl_add_u64 v[226:227], s[34:35], 0, v[134:135]
	s_mov_b32 m0, s43
	s_nop 0
	global_load_lds_dwordx4 v[226:227], off
	s_barrier
	s_waitcnt lgkmcnt(0)
	s_setprio 1
	s_waitcnt lgkmcnt(0)
	v_mfma_f32_16x16x32_bf16 v[62:65], v[150:153], v[174:177], v[62:65]
	v_mfma_f32_16x16x32_bf16 v[58:61], v[166:169], v[174:177], v[58:61]
	v_mfma_f32_16x16x32_bf16 v[54:57], v[150:153], v[182:185], v[54:57]
	v_mfma_f32_16x16x32_bf16 v[50:53], v[166:169], v[182:185], v[50:53]
	v_mfma_f32_16x16x32_bf16 v[30:33], v[150:153], v[190:193], v[30:33]
	v_mfma_f32_16x16x32_bf16 v[26:29], v[166:169], v[190:193], v[26:29]
	v_mfma_f32_16x16x32_bf16 v[22:25], v[150:153], v[198:201], v[22:25]
	v_mfma_f32_16x16x32_bf16 v[10:13], v[166:169], v[198:201], v[10:13]
	v_mfma_f32_16x16x32_bf16 v[62:65], v[154:157], v[178:181], v[62:65]
	v_mfma_f32_16x16x32_bf16 v[58:61], v[170:173], v[178:181], v[58:61]
	v_mfma_f32_16x16x32_bf16 v[54:57], v[154:157], v[186:189], v[54:57]
	v_mfma_f32_16x16x32_bf16 v[50:53], v[170:173], v[186:189], v[50:53]
	v_mfma_f32_16x16x32_bf16 v[30:33], v[154:157], v[194:197], v[30:33]
	v_mfma_f32_16x16x32_bf16 v[26:29], v[170:173], v[194:197], v[26:29]
	v_mfma_f32_16x16x32_bf16 v[22:25], v[154:157], v[202:205], v[22:25]
	v_mfma_f32_16x16x32_bf16 v[10:13], v[170:173], v[202:205], v[10:13]
	s_setprio 0
	s_barrier
	s_add_u32 s74, s30, 0x20000
	s_addc_u32 s75, s31, 0
	s_add_i32 s76, s53, s42
	v_lshl_add_u64 v[150:151], s[74:75], 0, v[132:133]
	s_mov_b32 m0, s76
	s_nop 0
	global_load_lds_dwordx4 v[150:151], off
	v_lshl_add_u64 v[150:151], s[74:75], 0, v[136:137]
	s_add_i32 m0, s76, 0x2000
	s_nop 0
	global_load_lds_dwordx4 v[150:151], off
	s_waitcnt vmcnt(6)
	s_barrier
	s_setprio 1
	v_mfma_f32_16x16x32_bf16 v[46:49], v[206:209], v[174:177], v[46:49]
	v_mfma_f32_16x16x32_bf16 v[42:45], v[214:217], v[174:177], v[42:45]
	v_mfma_f32_16x16x32_bf16 v[38:41], v[206:209], v[182:185], v[38:41]
	v_mfma_f32_16x16x32_bf16 v[34:37], v[214:217], v[182:185], v[34:37]
	v_mfma_f32_16x16x32_bf16 v[18:21], v[206:209], v[190:193], v[18:21]
	v_mfma_f32_16x16x32_bf16 v[14:17], v[214:217], v[190:193], v[14:17]
	v_mfma_f32_16x16x32_bf16 v[6:9], v[206:209], v[198:201], v[6:9]
	v_mfma_f32_16x16x32_bf16 v[2:5], v[214:217], v[198:201], v[2:5]
	v_mfma_f32_16x16x32_bf16 v[46:49], v[210:213], v[178:181], v[46:49]
	v_mfma_f32_16x16x32_bf16 v[42:45], v[218:221], v[178:181], v[42:45]
	v_mfma_f32_16x16x32_bf16 v[38:41], v[210:213], v[186:189], v[38:41]
	v_mfma_f32_16x16x32_bf16 v[34:37], v[218:221], v[186:189], v[34:37]
	v_mfma_f32_16x16x32_bf16 v[18:21], v[210:213], v[194:197], v[18:21]
	v_mfma_f32_16x16x32_bf16 v[14:17], v[218:221], v[194:197], v[14:17]
	v_mfma_f32_16x16x32_bf16 v[6:9], v[210:213], v[202:205], v[6:9]
	v_mfma_f32_16x16x32_bf16 v[2:5], v[218:221], v[202:205], v[2:5]
	s_setprio 0
	s_add_i32 s74, 0, 0x18000
	v_add_u32_e32 v165, s74, v161
	s_barrier
	ds_read_b128 v[150:153], v165
	ds_read_b128 v[154:157], v165 offset:1024
	ds_read_b128 v[166:169], v165 offset:2048
	ds_read_b128 v[170:173], v165 offset:3072
	s_add_u32 s34, s34, 0x20000
	s_addc_u32 s35, s35, 0
	s_mov_b32 m0, s46
	v_lshl_add_u64 v[206:207], s[34:35], 0, v[130:131]
	ds_read_b128 v[174:177], v163 offset:32768
	ds_read_b128 v[178:181], v163 offset:33792
	ds_read_b128 v[182:185], v163 offset:34816
	ds_read_b128 v[186:189], v163 offset:35840
	ds_read_b128 v[190:193], v163 offset:36864
	ds_read_b128 v[194:197], v163 offset:37888
	ds_read_b128 v[198:201], v163 offset:38912
	ds_read_b128 v[202:205], v163 offset:39936
	global_load_lds_dwordx4 v[206:207], off
	v_lshl_add_u64 v[206:207], s[34:35], 0, v[134:135]
	s_mov_b32 m0, s47
	s_nop 0
	global_load_lds_dwordx4 v[206:207], off
	s_waitcnt lgkmcnt(8)
	s_barrier
	s_waitcnt lgkmcnt(0)
	s_setprio 1
	s_waitcnt lgkmcnt(0)
	v_mfma_f32_16x16x32_bf16 v[126:129], v[150:153], v[174:177], v[126:129]
	v_mfma_f32_16x16x32_bf16 v[122:125], v[166:169], v[174:177], v[122:125]
	v_mfma_f32_16x16x32_bf16 v[118:121], v[150:153], v[182:185], v[118:121]
	v_mfma_f32_16x16x32_bf16 v[106:109], v[166:169], v[182:185], v[106:109]
	v_mfma_f32_16x16x32_bf16 v[94:97], v[150:153], v[190:193], v[94:97]
	v_mfma_f32_16x16x32_bf16 v[90:93], v[166:169], v[190:193], v[90:93]
	v_mfma_f32_16x16x32_bf16 v[82:85], v[150:153], v[198:201], v[82:85]
	v_mfma_f32_16x16x32_bf16 v[74:77], v[166:169], v[198:201], v[74:77]
	v_mfma_f32_16x16x32_bf16 v[126:129], v[154:157], v[178:181], v[126:129]
	v_mfma_f32_16x16x32_bf16 v[122:125], v[170:173], v[178:181], v[122:125]
	v_mfma_f32_16x16x32_bf16 v[118:121], v[154:157], v[186:189], v[118:121]
	v_mfma_f32_16x16x32_bf16 v[106:109], v[170:173], v[186:189], v[106:109]
	v_mfma_f32_16x16x32_bf16 v[94:97], v[154:157], v[194:197], v[94:97]
	v_mfma_f32_16x16x32_bf16 v[90:93], v[170:173], v[194:197], v[90:93]
	v_mfma_f32_16x16x32_bf16 v[82:85], v[154:157], v[202:205], v[82:85]
	v_mfma_f32_16x16x32_bf16 v[74:77], v[170:173], v[202:205], v[74:77]
	s_setprio 0
	s_barrier
	s_add_i32 s34, 0, 0x1c000
	s_add_i32 s35, s74, s42
	v_add_u32_e32 v165, s34, v161
	v_lshl_add_u64 v[158:159], v[158:159], 0, s[10:11]
	s_mov_b32 m0, s35
	ds_read_b128 v[206:209], v165
	ds_read_b128 v[210:213], v165 offset:1024
	ds_read_b128 v[214:217], v165 offset:2048
	ds_read_b128 v[218:221], v165 offset:3072
	global_load_lds_dwordx4 v[158:159], off
	v_lshl_add_u64 v[158:159], v[222:223], 0, s[10:11]
	s_add_i32 m0, s35, 0x2000
	s_nop 0
	global_load_lds_dwordx4 v[158:159], off
	s_barrier
	s_waitcnt lgkmcnt(0)
	s_setprio 1
	s_waitcnt lgkmcnt(0)
	v_mfma_f32_16x16x32_bf16 v[114:117], v[206:209], v[174:177], v[114:117]
	v_mfma_f32_16x16x32_bf16 v[110:113], v[214:217], v[174:177], v[110:113]
	v_mfma_f32_16x16x32_bf16 v[102:105], v[206:209], v[182:185], v[102:105]
	v_mfma_f32_16x16x32_bf16 v[98:101], v[214:217], v[182:185], v[98:101]
	v_mfma_f32_16x16x32_bf16 v[86:89], v[206:209], v[190:193], v[86:89]
	v_mfma_f32_16x16x32_bf16 v[78:81], v[214:217], v[190:193], v[78:81]
	v_mfma_f32_16x16x32_bf16 v[70:73], v[206:209], v[198:201], v[70:73]
	v_mfma_f32_16x16x32_bf16 v[66:69], v[214:217], v[198:201], v[66:69]
	v_mfma_f32_16x16x32_bf16 v[114:117], v[210:213], v[178:181], v[114:117]
	v_mfma_f32_16x16x32_bf16 v[110:113], v[218:221], v[178:181], v[110:113]
	v_mfma_f32_16x16x32_bf16 v[102:105], v[210:213], v[186:189], v[102:105]
	v_mfma_f32_16x16x32_bf16 v[98:101], v[218:221], v[186:189], v[98:101]
	v_mfma_f32_16x16x32_bf16 v[86:89], v[210:213], v[194:197], v[86:89]
	v_mfma_f32_16x16x32_bf16 v[78:81], v[218:221], v[194:197], v[78:81]
	v_mfma_f32_16x16x32_bf16 v[70:73], v[210:213], v[202:205], v[70:73]
	v_mfma_f32_16x16x32_bf16 v[66:69], v[218:221], v[202:205], v[66:69]
	s_setprio 0
	s_mov_b32 m0, s49
	v_lshl_add_u64 v[158:159], v[224:225], 0, s[10:11]
	s_barrier
	ds_read_b128 v[174:177], v163 offset:49152
	ds_read_b128 v[178:181], v163 offset:50176
	ds_read_b128 v[182:185], v163 offset:51200
	ds_read_b128 v[186:189], v163 offset:52224
	ds_read_b128 v[190:193], v163 offset:53248
	ds_read_b128 v[194:197], v163 offset:54272
	ds_read_b128 v[198:201], v163 offset:55296
	ds_read_b128 v[202:205], v163 offset:56320
	global_load_lds_dwordx4 v[158:159], off
	v_lshl_add_u64 v[158:159], v[226:227], 0, s[10:11]
	s_mov_b32 m0, s50
	s_nop 0
	global_load_lds_dwordx4 v[158:159], off
	s_barrier
	s_waitcnt lgkmcnt(0)
	s_setprio 1
	s_waitcnt lgkmcnt(0)
	v_mfma_f32_16x16x32_bf16 v[62:65], v[150:153], v[174:177], v[62:65]
	v_mfma_f32_16x16x32_bf16 v[58:61], v[166:169], v[174:177], v[58:61]
	v_mfma_f32_16x16x32_bf16 v[54:57], v[150:153], v[182:185], v[54:57]
	v_mfma_f32_16x16x32_bf16 v[50:53], v[166:169], v[182:185], v[50:53]
	v_mfma_f32_16x16x32_bf16 v[30:33], v[150:153], v[190:193], v[30:33]
	v_mfma_f32_16x16x32_bf16 v[26:29], v[166:169], v[190:193], v[26:29]
	v_mfma_f32_16x16x32_bf16 v[22:25], v[150:153], v[198:201], v[22:25]
	v_mfma_f32_16x16x32_bf16 v[10:13], v[166:169], v[198:201], v[10:13]
	v_mfma_f32_16x16x32_bf16 v[62:65], v[154:157], v[178:181], v[62:65]
	v_mfma_f32_16x16x32_bf16 v[58:61], v[170:173], v[178:181], v[58:61]
	v_mfma_f32_16x16x32_bf16 v[54:57], v[154:157], v[186:189], v[54:57]
	v_mfma_f32_16x16x32_bf16 v[50:53], v[170:173], v[186:189], v[50:53]
	v_mfma_f32_16x16x32_bf16 v[30:33], v[154:157], v[194:197], v[30:33]
	v_mfma_f32_16x16x32_bf16 v[26:29], v[170:173], v[194:197], v[26:29]
	v_mfma_f32_16x16x32_bf16 v[22:25], v[154:157], v[202:205], v[22:25]
	v_mfma_f32_16x16x32_bf16 v[10:13], v[170:173], v[202:205], v[10:13]
	s_setprio 0
	s_barrier
	s_add_u32 s30, s30, 0x20080
	s_addc_u32 s31, s31, 0
	s_add_i32 s34, s34, s42
	v_lshl_add_u64 v[150:151], s[30:31], 0, v[132:133]
	s_mov_b32 m0, s34
	s_nop 0
	global_load_lds_dwordx4 v[150:151], off
	v_lshl_add_u64 v[150:151], s[30:31], 0, v[136:137]
	s_add_i32 m0, s34, 0x2000
	s_nop 0
	global_load_lds_dwordx4 v[150:151], off
	s_waitcnt vmcnt(6)
	s_barrier
	s_setprio 1
	v_mfma_f32_16x16x32_bf16 v[46:49], v[206:209], v[174:177], v[46:49]
	v_mfma_f32_16x16x32_bf16 v[42:45], v[214:217], v[174:177], v[42:45]
	v_mfma_f32_16x16x32_bf16 v[38:41], v[206:209], v[182:185], v[38:41]
	v_mfma_f32_16x16x32_bf16 v[34:37], v[214:217], v[182:185], v[34:37]
	v_mfma_f32_16x16x32_bf16 v[18:21], v[206:209], v[190:193], v[18:21]
	v_mfma_f32_16x16x32_bf16 v[14:17], v[214:217], v[190:193], v[14:17]
	v_mfma_f32_16x16x32_bf16 v[6:9], v[206:209], v[198:201], v[6:9]
	v_mfma_f32_16x16x32_bf16 v[2:5], v[214:217], v[198:201], v[2:5]
	v_mfma_f32_16x16x32_bf16 v[46:49], v[210:213], v[178:181], v[46:49]
	v_mfma_f32_16x16x32_bf16 v[42:45], v[218:221], v[178:181], v[42:45]
	v_mfma_f32_16x16x32_bf16 v[38:41], v[210:213], v[186:189], v[38:41]
	v_mfma_f32_16x16x32_bf16 v[34:37], v[218:221], v[186:189], v[34:37]
	v_mfma_f32_16x16x32_bf16 v[18:21], v[210:213], v[194:197], v[18:21]
	v_mfma_f32_16x16x32_bf16 v[14:17], v[218:221], v[194:197], v[14:17]
	v_mfma_f32_16x16x32_bf16 v[6:9], v[210:213], v[202:205], v[6:9]
	v_mfma_f32_16x16x32_bf16 v[2:5], v[218:221], v[202:205], v[2:5]
	s_setprio 0
	s_add_i32 s73, s73, 2
	s_add_u32 s28, s28, 0x100
	s_addc_u32 s29, s29, 0
	s_add_u32 s71, s71, 0x100
	s_addc_u32 s72, s72, 0
	s_cmp_gt_u32 s73, 5
	s_barrier
	s_cbranch_scc0 .LBB0_751
	v_readfirstlane_b32 s99, v0
	s_cmpk_gt_u32 s99, 0xff
	s_cbranch_scc1 .Lxb_p5b_a
	s_barrier
.Lxb_p5b_a:
	s_lshl_b32 s19, s26, 2
	s_add_i32 s28, s19, s68
	s_ashr_i32 s29, s28, 31
	s_lshl_b32 s19, s26, 3
	s_lshl_b64 s[28:29], s[28:29], 17
	s_add_i32 s19, s68, s19
	v_lshl_add_u64 v[152:153], v[140:141], 0, s[28:29]
	s_add_i32 s28, s19, 4
	s_ashr_i32 s29, s28, 31
	s_lshl_b64 s[28:29], s[28:29], 17
	global_load_dwordx4 v[166:169], v[152:153], off
	global_load_dwordx4 v[170:173], v[152:153], off offset:1024
	v_lshl_add_u64 v[154:155], v[138:139], 0, s[28:29]
	global_load_dwordx4 v[174:177], v[152:153], off offset:2048
	global_load_dwordx4 v[178:181], v[154:155], off
	global_load_dwordx4 v[182:185], v[154:155], off offset:1024
	global_load_dwordx4 v[186:189], v[154:155], off offset:2048
	v_lshl_add_u32 v156, s26, 8, v160
	v_lshl_or_b32 v150, s68, 8, v162
	v_ashrrev_i32_e32 v157, 31, v156
	v_ashrrev_i32_e32 v151, 31, v150
	v_lshlrev_b64 v[190:191], 11, v[156:157]
	v_lshlrev_b64 v[158:159], 1, v[150:151]
	v_lshl_add_u64 v[150:151], s[8:9], 0, v[190:191]
	global_load_dwordx4 v[190:193], v[152:153], off offset:3072
	global_load_dwordx4 v[194:197], v[154:155], off offset:3072
	v_lshl_add_u64 v[150:151], v[150:151], 0, v[158:159]
	v_or_b32_e32 v198, 16, v156
	v_ashrrev_i32_e32 v199, 31, v198
	s_waitcnt vmcnt(0)
	v_lshlrev_b32_e32 v200, 16, v166
	v_and_b32_e32 v201, 0xffff0000, v166
	v_lshlrev_b32_e32 v166, 16, v167
	v_and_b32_e32 v167, 0xffff0000, v167
	v_lshlrev_b32_e32 v202, 16, v168
	v_and_b32_e32 v203, 0xffff0000, v168
	v_lshlrev_b32_e32 v168, 16, v169
	v_and_b32_e32 v169, 0xffff0000, v169
	v_lshlrev_b32_e32 v210, 16, v178
	v_and_b32_e32 v211, 0xffff0000, v178
	v_lshlrev_b32_e32 v178, 16, v179
	v_and_b32_e32 v179, 0xffff0000, v179
	v_lshlrev_b32_e32 v212, 16, v180
	v_and_b32_e32 v213, 0xffff0000, v180
	v_lshlrev_b32_e32 v180, 16, v181
	v_and_b32_e32 v181, 0xffff0000, v181
	v_lshlrev_b32_e32 v204, 16, v170
	v_and_b32_e32 v205, 0xffff0000, v170
	v_lshlrev_b32_e32 v170, 16, v171
	v_and_b32_e32 v171, 0xffff0000, v171
	v_lshlrev_b32_e32 v206, 16, v172
	v_and_b32_e32 v207, 0xffff0000, v172
	v_lshlrev_b32_e32 v172, 16, v173
	v_and_b32_e32 v173, 0xffff0000, v173
	v_lshlrev_b32_e32 v214, 16, v182
	v_and_b32_e32 v215, 0xffff0000, v182
	v_lshlrev_b32_e32 v182, 16, v183
	v_and_b32_e32 v183, 0xffff0000, v183
	v_lshlrev_b32_e32 v216, 16, v184
	v_and_b32_e32 v217, 0xffff0000, v184
	v_lshlrev_b32_e32 v184, 16, v185
	v_and_b32_e32 v185, 0xffff0000, v185
	v_pk_fma_f32 v[126:127], v[126:127], v[210:211], v[200:201]
	v_pk_fma_f32 v[128:129], v[128:129], v[178:179], v[166:167]
	v_pk_fma_f32 v[122:123], v[122:123], v[212:213], v[202:203]
	v_pk_fma_f32 v[124:125], v[124:125], v[180:181], v[168:169]
	v_pk_fma_f32 v[114:115], v[114:115], v[214:215], v[204:205]
	v_pk_fma_f32 v[116:117], v[116:117], v[182:183], v[170:171]
	v_pk_fma_f32 v[166:167], v[110:111], v[216:217], v[206:207]
	v_pk_fma_f32 v[168:169], v[112:113], v[184:185], v[172:173]
	v_cvt_pk_bf16_f32 v110, v126, v127
	v_cvt_pk_bf16_f32 v111, v128, v129
	v_cvt_pk_bf16_f32 v112, v122, v123
	v_cvt_pk_bf16_f32 v113, v124, v125
	v_lshlrev_b32_e32 v220, 16, v188
	v_and_b32_e32 v221, 0xffff0000, v188
	v_cvt_pk_bf16_f32 v114, v114, v115
	v_cvt_pk_bf16_f32 v115, v116, v117
	v_cvt_pk_bf16_f32 v116, v166, v167
	v_cvt_pk_bf16_f32 v117, v168, v169
	global_store_dwordx4 v[150:151], v[110:113], off
	global_store_dwordx4 v[150:151], v[114:117], off offset:256
	v_lshlrev_b32_e32 v208, 16, v174
	v_lshlrev_b32_e32 v110, 16, v176
	v_and_b32_e32 v111, 0xffff0000, v176
	v_pk_fma_f32 v[110:111], v[106:107], v[220:221], v[110:111]
	v_lshlrev_b32_e32 v106, 16, v189
	v_and_b32_e32 v107, 0xffff0000, v189
	v_lshlrev_b32_e32 v112, 16, v177
	v_and_b32_e32 v113, 0xffff0000, v177
	v_and_b32_e32 v209, 0xffff0000, v174
	v_lshlrev_b32_e32 v174, 16, v175
	v_and_b32_e32 v175, 0xffff0000, v175
	v_lshlrev_b32_e32 v218, 16, v186
	v_and_b32_e32 v219, 0xffff0000, v186
	v_lshlrev_b32_e32 v186, 16, v187
	v_and_b32_e32 v187, 0xffff0000, v187
	v_pk_fma_f32 v[112:113], v[108:109], v[106:107], v[112:113]
	v_cvt_pk_bf16_f32 v108, v110, v111
	v_lshlrev_b64 v[110:111], 11, v[198:199]
	v_pk_fma_f32 v[118:119], v[118:119], v[218:219], v[208:209]
	v_pk_fma_f32 v[120:121], v[120:121], v[186:187], v[174:175]
	v_lshl_add_u64 v[110:111], s[8:9], 0, v[110:111]
	v_cvt_pk_bf16_f32 v106, v118, v119
	v_cvt_pk_bf16_f32 v107, v120, v121
	v_cvt_pk_bf16_f32 v109, v112, v113
	v_lshl_add_u64 v[110:111], v[110:111], 0, v[158:159]
	global_store_dwordx4 v[110:111], v[106:109], off
	s_nop 1
	v_lshlrev_b32_e32 v106, 16, v194
	v_and_b32_e32 v107, 0xffff0000, v194
	v_lshlrev_b32_e32 v108, 16, v190
	v_and_b32_e32 v109, 0xffff0000, v190
	v_pk_fma_f32 v[102:103], v[102:103], v[106:107], v[108:109]
	v_lshlrev_b32_e32 v106, 16, v195
	v_and_b32_e32 v107, 0xffff0000, v195
	v_lshlrev_b32_e32 v108, 16, v191
	v_and_b32_e32 v109, 0xffff0000, v191
	v_pk_fma_f32 v[104:105], v[104:105], v[106:107], v[108:109]
	v_lshlrev_b32_e32 v106, 16, v196
	v_and_b32_e32 v107, 0xffff0000, v196
	v_lshlrev_b32_e32 v108, 16, v192
	v_and_b32_e32 v109, 0xffff0000, v192
	v_pk_fma_f32 v[106:107], v[98:99], v[106:107], v[108:109]
	v_lshlrev_b32_e32 v98, 16, v197
	v_and_b32_e32 v99, 0xffff0000, v197
	v_lshlrev_b32_e32 v108, 16, v193
	v_and_b32_e32 v109, 0xffff0000, v193
	v_pk_fma_f32 v[108:109], v[100:101], v[98:99], v[108:109]
	v_cvt_pk_bf16_f32 v98, v102, v103
	v_cvt_pk_bf16_f32 v99, v104, v105
	v_cvt_pk_bf16_f32 v100, v106, v107
	v_cvt_pk_bf16_f32 v101, v108, v109
	global_store_dwordx4 v[110:111], v[98:101], off offset:256
	s_nop 1
	v_add_co_u32_e32 v98, vcc, s48, v154
	v_or_b32_e32 v170, 32, v156
	s_nop 0
	v_addc_co_u32_e32 v99, vcc, 0, v155, vcc
	v_add_co_u32_e32 v100, vcc, s48, v152
	global_load_dwordx4 v[102:105], v[98:99], off offset:-4096
	s_nop 0
	v_addc_co_u32_e32 v101, vcc, 0, v153, vcc
	v_add_co_u32_e32 v126, vcc, s54, v154
	global_load_dwordx4 v[106:109], v[100:101], off offset:-4096
	s_nop 0
	v_addc_co_u32_e32 v127, vcc, 0, v155, vcc
	global_load_dwordx4 v[110:113], v[126:127], off offset:1024
	v_add_co_u32_e32 v166, vcc, s54, v152
	v_ashrrev_i32_e32 v171, 31, v170
	s_nop 0
	v_addc_co_u32_e32 v167, vcc, 0, v153, vcc
	global_load_dwordx4 v[114:117], v[166:167], off offset:1024
	global_load_dwordx4 v[118:121], v[126:127], off offset:2048
	global_load_dwordx4 v[122:125], v[166:167], off offset:2048
	s_nop 0
	global_load_dwordx4 v[126:129], v[126:127], off offset:3072
	s_nop 0
	global_load_dwordx4 v[166:169], v[166:167], off offset:3072
	v_lshlrev_b64 v[170:171], 11, v[170:171]
	v_lshl_add_u64 v[170:171], s[8:9], 0, v[170:171]
	v_lshl_add_u64 v[170:171], v[170:171], 0, v[158:159]
	v_or_b32_e32 v156, 48, v156
	v_ashrrev_i32_e32 v157, 31, v156
	s_waitcnt vmcnt(0)
	v_lshlrev_b32_e32 v172, 16, v102
	v_and_b32_e32 v173, 0xffff0000, v102
	v_lshlrev_b32_e32 v102, 16, v103
	v_and_b32_e32 v103, 0xffff0000, v103
	v_lshlrev_b32_e32 v176, 16, v104
	v_lshlrev_b32_e32 v174, 16, v106
	v_and_b32_e32 v175, 0xffff0000, v106
	v_lshlrev_b32_e32 v106, 16, v107
	v_and_b32_e32 v107, 0xffff0000, v107
	v_and_b32_e32 v177, 0xffff0000, v104
	v_lshlrev_b32_e32 v178, 16, v108
	v_and_b32_e32 v179, 0xffff0000, v108
	v_lshlrev_b32_e32 v104, 16, v105
	v_and_b32_e32 v105, 0xffff0000, v105
	v_lshlrev_b32_e32 v108, 16, v109
	v_and_b32_e32 v109, 0xffff0000, v109
	v_lshlrev_b32_e32 v180, 16, v110
	v_and_b32_e32 v181, 0xffff0000, v110
	v_lshlrev_b32_e32 v182, 16, v114
	v_and_b32_e32 v183, 0xffff0000, v114
	v_lshlrev_b32_e32 v110, 16, v111
	v_and_b32_e32 v111, 0xffff0000, v111
	v_lshlrev_b32_e32 v114, 16, v115
	v_and_b32_e32 v115, 0xffff0000, v115
	v_lshlrev_b32_e32 v184, 16, v112
	v_and_b32_e32 v185, 0xffff0000, v112
	v_lshlrev_b32_e32 v186, 16, v116
	v_and_b32_e32 v187, 0xffff0000, v116
	v_lshlrev_b32_e32 v112, 16, v113
	v_and_b32_e32 v113, 0xffff0000, v113
	v_lshlrev_b32_e32 v116, 16, v117
	v_and_b32_e32 v117, 0xffff0000, v117
	v_pk_fma_f32 v[94:95], v[94:95], v[172:173], v[174:175]
	v_pk_fma_f32 v[96:97], v[96:97], v[102:103], v[106:107]
	v_pk_fma_f32 v[90:91], v[90:91], v[176:177], v[178:179]
	v_pk_fma_f32 v[92:93], v[92:93], v[104:105], v[108:109]
	v_pk_fma_f32 v[86:87], v[86:87], v[180:181], v[182:183]
	v_pk_fma_f32 v[88:89], v[88:89], v[110:111], v[114:115]
	v_pk_fma_f32 v[102:103], v[78:79], v[184:185], v[186:187]
	v_pk_fma_f32 v[104:105], v[80:81], v[112:113], v[116:117]
	v_cvt_pk_bf16_f32 v78, v94, v95
	v_cvt_pk_bf16_f32 v79, v96, v97
	v_cvt_pk_bf16_f32 v80, v90, v91
	v_cvt_pk_bf16_f32 v81, v92, v93
	v_cvt_pk_bf16_f32 v86, v86, v87
	v_cvt_pk_bf16_f32 v87, v88, v89
	v_cvt_pk_bf16_f32 v88, v102, v103
	v_cvt_pk_bf16_f32 v89, v104, v105
	global_store_dwordx4 v[170:171], v[78:81], off
	global_store_dwordx4 v[170:171], v[86:89], off offset:256
	v_lshlrev_b32_e32 v188, 16, v118
	v_lshlrev_b32_e32 v78, 16, v119
	v_and_b32_e32 v79, 0xffff0000, v119
	v_lshlrev_b32_e32 v80, 16, v123
	v_and_b32_e32 v81, 0xffff0000, v123
	v_pk_fma_f32 v[78:79], v[84:85], v[78:79], v[80:81]
	v_lshlrev_b32_e32 v80, 16, v120
	v_and_b32_e32 v81, 0xffff0000, v120
	v_lshlrev_b32_e32 v84, 16, v124
	v_and_b32_e32 v85, 0xffff0000, v124
	v_pk_fma_f32 v[80:81], v[74:75], v[80:81], v[84:85]
	v_lshlrev_b32_e32 v74, 16, v121
	v_and_b32_e32 v75, 0xffff0000, v121
	v_lshlrev_b32_e32 v84, 16, v125
	v_and_b32_e32 v85, 0xffff0000, v125
	v_and_b32_e32 v189, 0xffff0000, v118
	v_lshlrev_b32_e32 v190, 16, v122
	v_and_b32_e32 v191, 0xffff0000, v122
	v_pk_fma_f32 v[84:85], v[76:77], v[74:75], v[84:85]
	v_cvt_pk_bf16_f32 v75, v78, v79
	v_lshlrev_b64 v[78:79], 11, v[156:157]
	v_pk_fma_f32 v[82:83], v[82:83], v[188:189], v[190:191]
	v_lshl_add_u64 v[78:79], s[8:9], 0, v[78:79]
	v_cvt_pk_bf16_f32 v74, v82, v83
	v_cvt_pk_bf16_f32 v76, v80, v81
	v_cvt_pk_bf16_f32 v77, v84, v85
	v_lshl_add_u64 v[78:79], v[78:79], 0, v[158:159]
	global_store_dwordx4 v[78:79], v[74:77], off
	s_nop 1
	v_lshlrev_b32_e32 v74, 16, v126
	v_and_b32_e32 v75, 0xffff0000, v126
	v_lshlrev_b32_e32 v76, 16, v166
	v_and_b32_e32 v77, 0xffff0000, v166
	v_pk_fma_f32 v[70:71], v[70:71], v[74:75], v[76:77]
	v_lshlrev_b32_e32 v74, 16, v127
	v_and_b32_e32 v75, 0xffff0000, v127
	v_lshlrev_b32_e32 v76, 16, v167
	v_and_b32_e32 v77, 0xffff0000, v167
	v_pk_fma_f32 v[72:73], v[72:73], v[74:75], v[76:77]
	v_lshlrev_b32_e32 v74, 16, v128
	v_and_b32_e32 v75, 0xffff0000, v128
	v_lshlrev_b32_e32 v76, 16, v168
	v_and_b32_e32 v77, 0xffff0000, v168
	v_pk_fma_f32 v[74:75], v[66:67], v[74:75], v[76:77]
	v_lshlrev_b32_e32 v66, 16, v129
	v_and_b32_e32 v67, 0xffff0000, v129
	v_lshlrev_b32_e32 v76, 16, v169
	v_and_b32_e32 v77, 0xffff0000, v169
	v_pk_fma_f32 v[76:77], v[68:69], v[66:67], v[76:77]
	v_cvt_pk_bf16_f32 v66, v70, v71
	v_cvt_pk_bf16_f32 v67, v72, v73
	v_cvt_pk_bf16_f32 v68, v74, v75
	v_cvt_pk_bf16_f32 v69, v76, v77
	global_store_dwordx4 v[78:79], v[66:69], off offset:256
	global_load_dwordx4 v[66:69], v[98:99], off
	s_nop 0
	global_load_dwordx4 v[70:73], v[100:101], off
	global_load_dwordx4 v[74:77], v[98:99], off offset:1024
	global_load_dwordx4 v[78:81], v[100:101], off offset:1024
	global_load_dwordx4 v[82:85], v[98:99], off offset:2048
	global_load_dwordx4 v[86:89], v[100:101], off offset:2048
	global_load_dwordx4 v[90:93], v[98:99], off offset:3072
	global_load_dwordx4 v[94:97], v[100:101], off offset:3072
	v_add_co_u32_e32 v100, vcc, s55, v150
	v_lshl_add_u64 v[98:99], v[150:151], 0, s[6:7]
	s_nop 0
	v_addc_co_u32_e32 v101, vcc, 0, v151, vcc
	s_waitcnt vmcnt(0)
	v_lshlrev_b32_e32 v102, 16, v66
	v_and_b32_e32 v103, 0xffff0000, v66
	v_lshlrev_b32_e32 v104, 16, v70
	v_and_b32_e32 v105, 0xffff0000, v70
	v_lshlrev_b32_e32 v66, 16, v67
	v_and_b32_e32 v67, 0xffff0000, v67
	v_lshlrev_b32_e32 v70, 16, v71
	v_and_b32_e32 v71, 0xffff0000, v71
	v_lshlrev_b32_e32 v106, 16, v68
	v_and_b32_e32 v107, 0xffff0000, v68
	v_lshlrev_b32_e32 v108, 16, v72
	v_and_b32_e32 v109, 0xffff0000, v72
	v_lshlrev_b32_e32 v68, 16, v69
	v_and_b32_e32 v69, 0xffff0000, v69
	v_lshlrev_b32_e32 v72, 16, v73
	v_and_b32_e32 v73, 0xffff0000, v73
	v_lshlrev_b32_e32 v110, 16, v74
	v_and_b32_e32 v111, 0xffff0000, v74
	v_lshlrev_b32_e32 v112, 16, v78
	v_and_b32_e32 v113, 0xffff0000, v78
	v_lshlrev_b32_e32 v74, 16, v75
	v_and_b32_e32 v75, 0xffff0000, v75
	v_lshlrev_b32_e32 v78, 16, v79
	v_and_b32_e32 v79, 0xffff0000, v79
	v_lshlrev_b32_e32 v114, 16, v76
	v_and_b32_e32 v115, 0xffff0000, v76
	v_lshlrev_b32_e32 v116, 16, v80
	v_and_b32_e32 v117, 0xffff0000, v80
	v_lshlrev_b32_e32 v76, 16, v77
	v_and_b32_e32 v77, 0xffff0000, v77
	v_lshlrev_b32_e32 v80, 16, v81
	v_and_b32_e32 v81, 0xffff0000, v81
	v_pk_fma_f32 v[62:63], v[62:63], v[102:103], v[104:105]
	v_pk_fma_f32 v[64:65], v[64:65], v[66:67], v[70:71]
	v_pk_fma_f32 v[58:59], v[58:59], v[106:107], v[108:109]
	v_pk_fma_f32 v[60:61], v[60:61], v[68:69], v[72:73]
	v_lshlrev_b32_e32 v118, 16, v82
	v_and_b32_e32 v119, 0xffff0000, v82
	v_lshlrev_b32_e32 v120, 16, v86
	v_and_b32_e32 v121, 0xffff0000, v86
	v_lshlrev_b32_e32 v82, 16, v83
	v_and_b32_e32 v83, 0xffff0000, v83
	v_lshlrev_b32_e32 v86, 16, v87
	v_and_b32_e32 v87, 0xffff0000, v87
	v_lshlrev_b32_e32 v122, 16, v84
	v_and_b32_e32 v123, 0xffff0000, v84
	v_lshlrev_b32_e32 v124, 16, v88
	v_and_b32_e32 v125, 0xffff0000, v88
	v_lshlrev_b32_e32 v84, 16, v85
	v_and_b32_e32 v85, 0xffff0000, v85
	v_lshlrev_b32_e32 v88, 16, v89
	v_and_b32_e32 v89, 0xffff0000, v89
	v_pk_fma_f32 v[46:47], v[46:47], v[110:111], v[112:113]
	v_pk_fma_f32 v[48:49], v[48:49], v[74:75], v[78:79]
	v_pk_fma_f32 v[66:67], v[42:43], v[114:115], v[116:117]
	v_pk_fma_f32 v[68:69], v[44:45], v[76:77], v[80:81]
	v_cvt_pk_bf16_f32 v42, v62, v63
	v_cvt_pk_bf16_f32 v43, v64, v65
	v_cvt_pk_bf16_f32 v44, v58, v59
	v_cvt_pk_bf16_f32 v45, v60, v61
	v_pk_fma_f32 v[54:55], v[54:55], v[118:119], v[120:121]
	v_pk_fma_f32 v[56:57], v[56:57], v[82:83], v[86:87]
	v_pk_fma_f32 v[70:71], v[50:51], v[122:123], v[124:125]
	v_pk_fma_f32 v[72:73], v[52:53], v[84:85], v[88:89]
	v_cvt_pk_bf16_f32 v46, v46, v47
	v_cvt_pk_bf16_f32 v47, v48, v49
	v_cvt_pk_bf16_f32 v48, v66, v67
	v_cvt_pk_bf16_f32 v49, v68, v69
	global_store_dwordx4 v[100:101], v[42:45], off
	global_store_dwordx4 v[98:99], v[46:49], off offset:256
	v_cvt_pk_bf16_f32 v50, v54, v55
	v_add_co_u32_e32 v44, vcc, s56, v150
	v_cvt_pk_bf16_f32 v51, v56, v57
	v_cvt_pk_bf16_f32 v52, v70, v71
	v_cvt_pk_bf16_f32 v53, v72, v73
	v_addc_co_u32_e32 v45, vcc, 0, v151, vcc
	global_store_dwordx4 v[44:45], v[50:53], off
	v_lshlrev_b32_e32 v44, 16, v90
	v_and_b32_e32 v45, 0xffff0000, v90
	v_lshlrev_b32_e32 v46, 16, v94
	v_and_b32_e32 v47, 0xffff0000, v94
	v_pk_fma_f32 v[38:39], v[38:39], v[44:45], v[46:47]
	v_lshlrev_b32_e32 v44, 16, v91
	v_and_b32_e32 v45, 0xffff0000, v91
	v_lshlrev_b32_e32 v46, 16, v95
	v_and_b32_e32 v47, 0xffff0000, v95
	v_pk_fma_f32 v[40:41], v[40:41], v[44:45], v[46:47]
	v_lshlrev_b32_e32 v44, 16, v92
	v_and_b32_e32 v45, 0xffff0000, v92
	v_lshlrev_b32_e32 v46, 16, v96
	v_and_b32_e32 v47, 0xffff0000, v96
	v_pk_fma_f32 v[44:45], v[34:35], v[44:45], v[46:47]
	v_lshlrev_b32_e32 v34, 16, v93
	v_and_b32_e32 v35, 0xffff0000, v93
	v_lshlrev_b32_e32 v46, 16, v97
	v_and_b32_e32 v47, 0xffff0000, v97
	v_pk_fma_f32 v[46:47], v[36:37], v[34:35], v[46:47]
	v_lshl_add_u64 v[42:43], v[150:151], 0, s[12:13]
	v_cvt_pk_bf16_f32 v34, v38, v39
	v_cvt_pk_bf16_f32 v35, v40, v41
	v_cvt_pk_bf16_f32 v36, v44, v45
	v_cvt_pk_bf16_f32 v37, v46, v47
	global_store_dwordx4 v[42:43], v[34:37], off offset:256
	v_add_co_u32_e32 v58, vcc, s57, v154
	v_lshl_add_u64 v[66:67], v[150:151], 0, s[14:15]
	s_nop 0
	v_addc_co_u32_e32 v59, vcc, 0, v155, vcc
	global_load_dwordx4 v[34:37], v[58:59], off
	v_add_co_u32_e32 v62, vcc, s57, v152
	s_waitcnt vmcnt(0)
	v_lshlrev_b32_e32 v70, 16, v34
	v_addc_co_u32_e32 v63, vcc, 0, v153, vcc
	global_load_dwordx4 v[38:41], v[62:63], off
	global_load_dwordx4 v[42:45], v[58:59], off offset:1024
	global_load_dwordx4 v[46:49], v[62:63], off offset:1024
	global_load_dwordx4 v[50:53], v[58:59], off offset:2048
	global_load_dwordx4 v[54:57], v[62:63], off offset:2048
	s_nop 0
	global_load_dwordx4 v[58:61], v[58:59], off offset:3072
	s_nop 0
	global_load_dwordx4 v[62:65], v[62:63], off offset:3072
	v_and_b32_e32 v71, 0xffff0000, v34
	v_lshlrev_b32_e32 v34, 16, v35
	v_and_b32_e32 v35, 0xffff0000, v35
	v_lshlrev_b32_e32 v74, 16, v36
	v_and_b32_e32 v75, 0xffff0000, v36
	v_lshlrev_b32_e32 v36, 16, v37
	v_and_b32_e32 v37, 0xffff0000, v37
	v_add_co_u32_e32 v68, vcc, s66, v150
	s_waitcnt vmcnt(0)
	v_lshlrev_b32_e32 v72, 16, v38
	v_and_b32_e32 v73, 0xffff0000, v38
	v_lshlrev_b32_e32 v38, 16, v39
	v_and_b32_e32 v39, 0xffff0000, v39
	v_lshlrev_b32_e32 v76, 16, v40
	v_and_b32_e32 v77, 0xffff0000, v40
	v_lshlrev_b32_e32 v40, 16, v41
	v_and_b32_e32 v41, 0xffff0000, v41
	v_lshlrev_b32_e32 v78, 16, v42
	v_and_b32_e32 v79, 0xffff0000, v42
	v_lshlrev_b32_e32 v80, 16, v46
	v_and_b32_e32 v81, 0xffff0000, v46
	v_lshlrev_b32_e32 v42, 16, v43
	v_and_b32_e32 v43, 0xffff0000, v43
	v_lshlrev_b32_e32 v46, 16, v47
	v_and_b32_e32 v47, 0xffff0000, v47
	v_lshlrev_b32_e32 v82, 16, v44
	v_and_b32_e32 v83, 0xffff0000, v44
	v_lshlrev_b32_e32 v84, 16, v48
	v_and_b32_e32 v85, 0xffff0000, v48
	v_lshlrev_b32_e32 v44, 16, v45
	v_and_b32_e32 v45, 0xffff0000, v45
	v_lshlrev_b32_e32 v48, 16, v49
	v_and_b32_e32 v49, 0xffff0000, v49
	v_pk_fma_f32 v[30:31], v[30:31], v[70:71], v[72:73]
	v_pk_fma_f32 v[32:33], v[32:33], v[34:35], v[38:39]
	v_pk_fma_f32 v[26:27], v[26:27], v[74:75], v[76:77]
	v_pk_fma_f32 v[28:29], v[28:29], v[36:37], v[40:41]
	v_addc_co_u32_e32 v69, vcc, 0, v151, vcc
	v_lshlrev_b32_e32 v90, 16, v52
	v_and_b32_e32 v91, 0xffff0000, v52
	v_lshlrev_b32_e32 v92, 16, v56
	v_and_b32_e32 v93, 0xffff0000, v56
	v_pk_fma_f32 v[18:19], v[18:19], v[78:79], v[80:81]
	v_pk_fma_f32 v[20:21], v[20:21], v[42:43], v[46:47]
	v_pk_fma_f32 v[34:35], v[14:15], v[82:83], v[84:85]
	v_pk_fma_f32 v[36:37], v[16:17], v[44:45], v[48:49]
	v_cvt_pk_bf16_f32 v14, v30, v31
	v_cvt_pk_bf16_f32 v15, v32, v33
	v_cvt_pk_bf16_f32 v16, v26, v27
	v_cvt_pk_bf16_f32 v17, v28, v29
	v_cvt_pk_bf16_f32 v18, v18, v19
	v_cvt_pk_bf16_f32 v19, v20, v21
	v_cvt_pk_bf16_f32 v20, v34, v35
	v_cvt_pk_bf16_f32 v21, v36, v37
	global_store_dwordx4 v[68:69], v[14:17], off
	global_store_dwordx4 v[66:67], v[18:21], off offset:256
	v_lshlrev_b32_e32 v86, 16, v50
	v_pk_fma_f32 v[14:15], v[10:11], v[90:91], v[92:93]
	v_lshlrev_b32_e32 v10, 16, v53
	v_and_b32_e32 v11, 0xffff0000, v53
	v_lshlrev_b32_e32 v16, 16, v57
	v_and_b32_e32 v17, 0xffff0000, v57
	v_and_b32_e32 v87, 0xffff0000, v50
	v_lshlrev_b32_e32 v88, 16, v54
	v_and_b32_e32 v89, 0xffff0000, v54
	v_lshlrev_b32_e32 v50, 16, v51
	v_and_b32_e32 v51, 0xffff0000, v51
	v_lshlrev_b32_e32 v54, 16, v55
	v_and_b32_e32 v55, 0xffff0000, v55
	v_pk_fma_f32 v[16:17], v[12:13], v[10:11], v[16:17]
	v_pk_fma_f32 v[22:23], v[22:23], v[86:87], v[88:89]
	v_pk_fma_f32 v[24:25], v[24:25], v[50:51], v[54:55]
	v_cvt_pk_bf16_f32 v13, v16, v17
	v_add_co_u32_e32 v16, vcc, s67, v150
	v_cvt_pk_bf16_f32 v10, v22, v23
	v_cvt_pk_bf16_f32 v11, v24, v25
	v_cvt_pk_bf16_f32 v12, v14, v15
	v_addc_co_u32_e32 v17, vcc, 0, v151, vcc
	global_store_dwordx4 v[16:17], v[10:13], off
	v_lshl_add_u64 v[14:15], v[150:151], 0, s[16:17]
	s_nop 0
	v_lshlrev_b32_e32 v10, 16, v58
	v_and_b32_e32 v11, 0xffff0000, v58
	v_lshlrev_b32_e32 v12, 16, v62
	v_and_b32_e32 v13, 0xffff0000, v62
	v_pk_fma_f32 v[6:7], v[6:7], v[10:11], v[12:13]
	v_lshlrev_b32_e32 v10, 16, v59
	v_and_b32_e32 v11, 0xffff0000, v59
	v_lshlrev_b32_e32 v12, 16, v63
	v_and_b32_e32 v13, 0xffff0000, v63
	v_pk_fma_f32 v[8:9], v[8:9], v[10:11], v[12:13]
	v_lshlrev_b32_e32 v10, 16, v60
	v_and_b32_e32 v11, 0xffff0000, v60
	v_lshlrev_b32_e32 v12, 16, v64
	v_and_b32_e32 v13, 0xffff0000, v64
	v_pk_fma_f32 v[10:11], v[2:3], v[10:11], v[12:13]
	v_lshlrev_b32_e32 v2, 16, v61
	v_and_b32_e32 v3, 0xffff0000, v61
	v_lshlrev_b32_e32 v12, 16, v65
	v_and_b32_e32 v13, 0xffff0000, v65
	v_pk_fma_f32 v[12:13], v[4:5], v[2:3], v[12:13]
	v_cvt_pk_bf16_f32 v2, v6, v7
	v_cvt_pk_bf16_f32 v3, v8, v9
	v_cvt_pk_bf16_f32 v4, v10, v11
	v_cvt_pk_bf16_f32 v5, v12, v13
	global_store_dwordx4 v[14:15], v[2:5], off offset:256
	v_readfirstlane_b32 s99, v0
	s_cmpk_lt_u32 s99, 0x100
	s_cbranch_scc1 .Lxb_p5b_b
	s_barrier
.Lxb_p5b_b:
	s_and_b64 vcc, exec, s[2:3]
	s_mov_b32 s68, s18
	s_mov_b32 s26, s20
	s_mov_b64 s[30:31], s[24:25]
	s_mov_b64 s[28:29], s[22:23]
	s_cbranch_vccz .LBB0_744
	s_waitcnt vmcnt(0)
	s_cmpk_gt_u32 s36, 0xff
	s_cbranch_scc1 .LBB0_755
	s_barrier

.LBB0_829:
	ds_read_b128 v[146:149], v152
	ds_read_b128 v[156:159], v152 offset:1024
	ds_read_b128 v[160:163], v152 offset:2048
	ds_read_b128 v[164:167], v152 offset:3072
	s_add_u32 s26, s24, 0xfffc0080
	s_addc_u32 s27, s25, -1
	s_cmp_eq_u32 s54, 12
	s_cselect_b32 s29, s15, s27
	s_cselect_b32 s28, s21, s26
	s_cselect_b32 s27, s13, s53
	s_cselect_b32 s26, s51, s52
	v_lshl_add_u64 v[200:201], s[24:25], 0, v[138:139]
	s_add_i32 m0, s23, 0xc000
	ds_read_b128 v[168:171], v153
	ds_read_b128 v[172:175], v153 offset:1024
	ds_read_b128 v[176:179], v153 offset:2048
	ds_read_b128 v[180:183], v153 offset:3072
	ds_read_b128 v[184:187], v153 offset:4096
	ds_read_b128 v[188:191], v153 offset:5120
	ds_read_b128 v[192:195], v153 offset:6144
	ds_read_b128 v[196:199], v153 offset:7168
	global_load_lds_dwordx4 v[200:201], off
	v_lshl_add_u64 v[200:201], s[24:25], 0, v[140:141]
	s_add_i32 m0, s23, 0xe000
	s_nop 0
	global_load_lds_dwordx4 v[200:201], off
	s_waitcnt lgkmcnt(8)
	s_barrier
	s_waitcnt lgkmcnt(0)
	s_setprio 1
	s_waitcnt lgkmcnt(0)
	v_mfma_f32_16x16x32_bf16 v[126:129], v[146:149], v[168:171], v[126:129]
	v_mfma_f32_16x16x32_bf16 v[122:125], v[160:163], v[168:171], v[122:125]
	v_mfma_f32_16x16x32_bf16 v[110:113], v[146:149], v[176:179], v[110:113]
	v_mfma_f32_16x16x32_bf16 v[106:109], v[160:163], v[176:179], v[106:109]
	v_mfma_f32_16x16x32_bf16 v[94:97], v[146:149], v[184:187], v[94:97]
	v_mfma_f32_16x16x32_bf16 v[90:93], v[160:163], v[184:187], v[90:93]
	v_mfma_f32_16x16x32_bf16 v[78:81], v[146:149], v[192:195], v[78:81]
	v_mfma_f32_16x16x32_bf16 v[74:77], v[160:163], v[192:195], v[74:77]
	v_mfma_f32_16x16x32_bf16 v[126:129], v[156:159], v[172:175], v[126:129]
	v_mfma_f32_16x16x32_bf16 v[122:125], v[164:167], v[172:175], v[122:125]
	v_mfma_f32_16x16x32_bf16 v[110:113], v[156:159], v[180:183], v[110:113]
	v_mfma_f32_16x16x32_bf16 v[106:109], v[164:167], v[180:183], v[106:109]
	v_mfma_f32_16x16x32_bf16 v[94:97], v[156:159], v[188:191], v[94:97]
	v_mfma_f32_16x16x32_bf16 v[90:93], v[164:167], v[188:191], v[90:93]
	v_mfma_f32_16x16x32_bf16 v[78:81], v[156:159], v[196:199], v[78:81]
	v_mfma_f32_16x16x32_bf16 v[74:77], v[164:167], v[196:199], v[74:77]
	s_setprio 0
	s_barrier
	s_add_i32 s55, s49, s37
	v_lshl_add_u64 v[216:217], s[26:27], 0, v[132:133]
	s_mov_b32 m0, s55
	ds_read_b128 v[200:203], v154
	ds_read_b128 v[204:207], v154 offset:1024
	ds_read_b128 v[208:211], v154 offset:2048
	ds_read_b128 v[212:215], v154 offset:3072
	global_load_lds_dwordx4 v[216:217], off
	v_lshl_add_u64 v[218:219], s[26:27], 0, v[136:137]
	s_add_i32 m0, s55, 0x2000
	s_nop 0
	global_load_lds_dwordx4 v[218:219], off
	s_barrier
	s_waitcnt lgkmcnt(0)
	s_setprio 1
	s_waitcnt lgkmcnt(0)
	v_mfma_f32_16x16x32_bf16 v[118:121], v[200:203], v[168:171], v[118:121]
	v_mfma_f32_16x16x32_bf16 v[114:117], v[208:211], v[168:171], v[114:117]
	v_mfma_f32_16x16x32_bf16 v[102:105], v[200:203], v[176:179], v[102:105]
	v_mfma_f32_16x16x32_bf16 v[98:101], v[208:211], v[176:179], v[98:101]
	v_mfma_f32_16x16x32_bf16 v[86:89], v[200:203], v[184:187], v[86:89]
	v_mfma_f32_16x16x32_bf16 v[82:85], v[208:211], v[184:187], v[82:85]
	v_mfma_f32_16x16x32_bf16 v[70:73], v[200:203], v[192:195], v[70:73]
	v_mfma_f32_16x16x32_bf16 v[66:69], v[208:211], v[192:195], v[66:69]
	v_mfma_f32_16x16x32_bf16 v[118:121], v[204:207], v[172:175], v[118:121]
	v_mfma_f32_16x16x32_bf16 v[114:117], v[212:215], v[172:175], v[114:117]
	v_mfma_f32_16x16x32_bf16 v[102:105], v[204:207], v[180:183], v[102:105]
	v_mfma_f32_16x16x32_bf16 v[98:101], v[212:215], v[180:183], v[98:101]
	v_mfma_f32_16x16x32_bf16 v[86:89], v[204:207], v[188:191], v[86:89]
	v_mfma_f32_16x16x32_bf16 v[82:85], v[212:215], v[188:191], v[82:85]
	v_mfma_f32_16x16x32_bf16 v[70:73], v[204:207], v[196:199], v[70:73]
	v_mfma_f32_16x16x32_bf16 v[66:69], v[212:215], v[196:199], v[66:69]
	s_setprio 0
	s_mov_b32 m0, s23
	v_lshl_add_u64 v[220:221], s[28:29], 0, v[130:131]
	s_barrier
	ds_read_b128 v[168:171], v153 offset:16384
	ds_read_b128 v[172:175], v153 offset:17408
	ds_read_b128 v[176:179], v153 offset:18432
	ds_read_b128 v[180:183], v153 offset:19456
	ds_read_b128 v[184:187], v153 offset:20480
	ds_read_b128 v[188:191], v153 offset:21504
	ds_read_b128 v[192:195], v153 offset:22528
	ds_read_b128 v[196:199], v153 offset:23552
	global_load_lds_dwordx4 v[220:221], off
	v_lshl_add_u64 v[222:223], s[28:29], 0, v[134:135]
	s_mov_b32 m0, s38
	s_nop 0
	global_load_lds_dwordx4 v[222:223], off
	s_barrier
	s_waitcnt lgkmcnt(0)
	s_setprio 1
	s_waitcnt lgkmcnt(0)
	v_mfma_f32_16x16x32_bf16 v[62:65], v[146:149], v[168:171], v[62:65]
	v_mfma_f32_16x16x32_bf16 v[58:61], v[160:163], v[168:171], v[58:61]
	v_mfma_f32_16x16x32_bf16 v[46:49], v[146:149], v[176:179], v[46:49]
	v_mfma_f32_16x16x32_bf16 v[42:45], v[160:163], v[176:179], v[42:45]
	v_mfma_f32_16x16x32_bf16 v[30:33], v[146:149], v[184:187], v[30:33]
	v_mfma_f32_16x16x32_bf16 v[26:29], v[160:163], v[184:187], v[26:29]
	v_mfma_f32_16x16x32_bf16 v[14:17], v[146:149], v[192:195], v[14:17]
	v_mfma_f32_16x16x32_bf16 v[10:13], v[160:163], v[192:195], v[10:13]
	v_mfma_f32_16x16x32_bf16 v[62:65], v[156:159], v[172:175], v[62:65]
	v_mfma_f32_16x16x32_bf16 v[58:61], v[164:167], v[172:175], v[58:61]
	v_mfma_f32_16x16x32_bf16 v[46:49], v[156:159], v[180:183], v[46:49]
	v_mfma_f32_16x16x32_bf16 v[42:45], v[164:167], v[180:183], v[42:45]
	v_mfma_f32_16x16x32_bf16 v[30:33], v[156:159], v[188:191], v[30:33]
	v_mfma_f32_16x16x32_bf16 v[26:29], v[164:167], v[188:191], v[26:29]
	v_mfma_f32_16x16x32_bf16 v[14:17], v[156:159], v[196:199], v[14:17]
	v_mfma_f32_16x16x32_bf16 v[10:13], v[164:167], v[196:199], v[10:13]
	s_setprio 0
	s_barrier
	s_add_u32 s56, s26, 0x40000
	s_addc_u32 s57, s27, 0
	s_add_i32 s55, s50, s37
	v_lshl_add_u64 v[146:147], s[56:57], 0, v[132:133]
	s_mov_b32 m0, s55
	s_nop 0
	global_load_lds_dwordx4 v[146:147], off
	v_lshl_add_u64 v[146:147], s[56:57], 0, v[136:137]
	s_add_i32 m0, s55, 0x2000
	s_nop 0
	global_load_lds_dwordx4 v[146:147], off
	s_waitcnt vmcnt(6)
	s_barrier
	s_setprio 1
	v_mfma_f32_16x16x32_bf16 v[54:57], v[200:203], v[168:171], v[54:57]
	v_mfma_f32_16x16x32_bf16 v[50:53], v[208:211], v[168:171], v[50:53]
	v_mfma_f32_16x16x32_bf16 v[38:41], v[200:203], v[176:179], v[38:41]
	v_mfma_f32_16x16x32_bf16 v[34:37], v[208:211], v[176:179], v[34:37]
	v_mfma_f32_16x16x32_bf16 v[22:25], v[200:203], v[184:187], v[22:25]
	v_mfma_f32_16x16x32_bf16 v[18:21], v[208:211], v[184:187], v[18:21]
	v_mfma_f32_16x16x32_bf16 v[6:9], v[200:203], v[192:195], v[6:9]
	v_mfma_f32_16x16x32_bf16 v[2:5], v[208:211], v[192:195], v[2:5]
	v_mfma_f32_16x16x32_bf16 v[54:57], v[204:207], v[172:175], v[54:57]
	v_mfma_f32_16x16x32_bf16 v[50:53], v[212:215], v[172:175], v[50:53]
	v_mfma_f32_16x16x32_bf16 v[38:41], v[204:207], v[180:183], v[38:41]
	v_mfma_f32_16x16x32_bf16 v[34:37], v[212:215], v[180:183], v[34:37]
	v_mfma_f32_16x16x32_bf16 v[22:25], v[204:207], v[188:191], v[22:25]
	v_mfma_f32_16x16x32_bf16 v[18:21], v[212:215], v[188:191], v[18:21]
	v_mfma_f32_16x16x32_bf16 v[6:9], v[204:207], v[196:199], v[6:9]
	v_mfma_f32_16x16x32_bf16 v[2:5], v[212:215], v[196:199], v[2:5]
	s_setprio 0
	s_add_i32 s55, 0, 0x18000
	v_add_u32_e32 v155, s55, v150
	s_barrier
	ds_read_b128 v[146:149], v155
	ds_read_b128 v[156:159], v155 offset:1024
	ds_read_b128 v[160:163], v155 offset:2048
	ds_read_b128 v[164:167], v155 offset:3072
	s_add_u32 s28, s28, 0x40000
	s_addc_u32 s29, s29, 0
	s_mov_b32 m0, s39
	v_lshl_add_u64 v[200:201], s[28:29], 0, v[130:131]
	ds_read_b128 v[168:171], v153 offset:32768
	ds_read_b128 v[172:175], v153 offset:33792
	ds_read_b128 v[176:179], v153 offset:34816
	ds_read_b128 v[180:183], v153 offset:35840
	ds_read_b128 v[184:187], v153 offset:36864
	ds_read_b128 v[188:191], v153 offset:37888
	ds_read_b128 v[192:195], v153 offset:38912
	ds_read_b128 v[196:199], v153 offset:39936
	global_load_lds_dwordx4 v[200:201], off
	v_lshl_add_u64 v[200:201], s[28:29], 0, v[134:135]
	s_mov_b32 m0, s40
	s_nop 0
	global_load_lds_dwordx4 v[200:201], off
	s_waitcnt lgkmcnt(8)
	s_barrier
	s_waitcnt lgkmcnt(0)
	s_setprio 1
	s_waitcnt lgkmcnt(0)
	v_mfma_f32_16x16x32_bf16 v[126:129], v[146:149], v[168:171], v[126:129]
	v_mfma_f32_16x16x32_bf16 v[122:125], v[160:163], v[168:171], v[122:125]
	v_mfma_f32_16x16x32_bf16 v[110:113], v[146:149], v[176:179], v[110:113]
	v_mfma_f32_16x16x32_bf16 v[106:109], v[160:163], v[176:179], v[106:109]
	v_mfma_f32_16x16x32_bf16 v[94:97], v[146:149], v[184:187], v[94:97]
	v_mfma_f32_16x16x32_bf16 v[90:93], v[160:163], v[184:187], v[90:93]
	v_mfma_f32_16x16x32_bf16 v[78:81], v[146:149], v[192:195], v[78:81]
	v_mfma_f32_16x16x32_bf16 v[74:77], v[160:163], v[192:195], v[74:77]
	v_mfma_f32_16x16x32_bf16 v[126:129], v[156:159], v[172:175], v[126:129]
	v_mfma_f32_16x16x32_bf16 v[122:125], v[164:167], v[172:175], v[122:125]
	v_mfma_f32_16x16x32_bf16 v[110:113], v[156:159], v[180:183], v[110:113]
	v_mfma_f32_16x16x32_bf16 v[106:109], v[164:167], v[180:183], v[106:109]
	v_mfma_f32_16x16x32_bf16 v[94:97], v[156:159], v[188:191], v[94:97]
	v_mfma_f32_16x16x32_bf16 v[90:93], v[164:167], v[188:191], v[90:93]
	v_mfma_f32_16x16x32_bf16 v[78:81], v[156:159], v[196:199], v[78:81]
	v_mfma_f32_16x16x32_bf16 v[74:77], v[164:167], v[196:199], v[74:77]
	s_setprio 0
	s_barrier
	s_add_i32 s28, 0, 0x1c000
	s_add_i32 s29, s55, s37
	v_add_u32_e32 v155, s28, v150
	v_lshl_add_u64 v[216:217], v[216:217], 0, s[10:11]
	s_mov_b32 m0, s29
	ds_read_b128 v[200:203], v155
	ds_read_b128 v[204:207], v155 offset:1024
	ds_read_b128 v[208:211], v155 offset:2048
	ds_read_b128 v[212:215], v155 offset:3072
	global_load_lds_dwordx4 v[216:217], off
	v_lshl_add_u64 v[216:217], v[218:219], 0, s[10:11]
	s_add_i32 m0, s29, 0x2000
	s_nop 0
	global_load_lds_dwordx4 v[216:217], off
	s_barrier
	s_waitcnt lgkmcnt(0)
	s_setprio 1
	s_waitcnt lgkmcnt(0)
	v_mfma_f32_16x16x32_bf16 v[118:121], v[200:203], v[168:171], v[118:121]
	v_mfma_f32_16x16x32_bf16 v[114:117], v[208:211], v[168:171], v[114:117]
	v_mfma_f32_16x16x32_bf16 v[102:105], v[200:203], v[176:179], v[102:105]
	v_mfma_f32_16x16x32_bf16 v[98:101], v[208:211], v[176:179], v[98:101]
	v_mfma_f32_16x16x32_bf16 v[86:89], v[200:203], v[184:187], v[86:89]
	v_mfma_f32_16x16x32_bf16 v[82:85], v[208:211], v[184:187], v[82:85]
	v_mfma_f32_16x16x32_bf16 v[70:73], v[200:203], v[192:195], v[70:73]
	v_mfma_f32_16x16x32_bf16 v[66:69], v[208:211], v[192:195], v[66:69]
	v_mfma_f32_16x16x32_bf16 v[118:121], v[204:207], v[172:175], v[118:121]
	v_mfma_f32_16x16x32_bf16 v[114:117], v[212:215], v[172:175], v[114:117]
	v_mfma_f32_16x16x32_bf16 v[102:105], v[204:207], v[180:183], v[102:105]
	v_mfma_f32_16x16x32_bf16 v[98:101], v[212:215], v[180:183], v[98:101]
	v_mfma_f32_16x16x32_bf16 v[86:89], v[204:207], v[188:191], v[86:89]
	v_mfma_f32_16x16x32_bf16 v[82:85], v[212:215], v[188:191], v[82:85]
	v_mfma_f32_16x16x32_bf16 v[70:73], v[204:207], v[196:199], v[70:73]
	v_mfma_f32_16x16x32_bf16 v[66:69], v[212:215], v[196:199], v[66:69]
	s_setprio 0
	s_mov_b32 m0, s42
	v_lshl_add_u64 v[216:217], v[220:221], 0, s[10:11]
	s_barrier
	ds_read_b128 v[168:171], v153 offset:49152
	ds_read_b128 v[172:175], v153 offset:50176
	ds_read_b128 v[176:179], v153 offset:51200
	ds_read_b128 v[180:183], v153 offset:52224
	ds_read_b128 v[184:187], v153 offset:53248
	ds_read_b128 v[188:191], v153 offset:54272
	ds_read_b128 v[192:195], v153 offset:55296
	ds_read_b128 v[196:199], v153 offset:56320
	global_load_lds_dwordx4 v[216:217], off
	v_lshl_add_u64 v[216:217], v[222:223], 0, s[10:11]
	s_mov_b32 m0, s43
	s_nop 0
	global_load_lds_dwordx4 v[216:217], off
	s_barrier
	s_waitcnt lgkmcnt(0)
	s_setprio 1
	s_waitcnt lgkmcnt(0)
	v_mfma_f32_16x16x32_bf16 v[62:65], v[146:149], v[168:171], v[62:65]
	v_mfma_f32_16x16x32_bf16 v[58:61], v[160:163], v[168:171], v[58:61]
	v_mfma_f32_16x16x32_bf16 v[46:49], v[146:149], v[176:179], v[46:49]
	v_mfma_f32_16x16x32_bf16 v[42:45], v[160:163], v[176:179], v[42:45]
	v_mfma_f32_16x16x32_bf16 v[30:33], v[146:149], v[184:187], v[30:33]
	v_mfma_f32_16x16x32_bf16 v[26:29], v[160:163], v[184:187], v[26:29]
	v_mfma_f32_16x16x32_bf16 v[14:17], v[146:149], v[192:195], v[14:17]
	v_mfma_f32_16x16x32_bf16 v[10:13], v[160:163], v[192:195], v[10:13]
	v_mfma_f32_16x16x32_bf16 v[62:65], v[156:159], v[172:175], v[62:65]
	v_mfma_f32_16x16x32_bf16 v[58:61], v[164:167], v[172:175], v[58:61]
	v_mfma_f32_16x16x32_bf16 v[46:49], v[156:159], v[180:183], v[46:49]
	v_mfma_f32_16x16x32_bf16 v[42:45], v[164:167], v[180:183], v[42:45]
	v_mfma_f32_16x16x32_bf16 v[30:33], v[156:159], v[188:191], v[30:33]
	v_mfma_f32_16x16x32_bf16 v[26:29], v[164:167], v[188:191], v[26:29]
	v_mfma_f32_16x16x32_bf16 v[14:17], v[156:159], v[196:199], v[14:17]
	v_mfma_f32_16x16x32_bf16 v[10:13], v[164:167], v[196:199], v[10:13]
	s_setprio 0
	s_barrier
	s_add_u32 s26, s26, 0x40080
	s_addc_u32 s27, s27, 0
	s_add_i32 s28, s28, s37
	v_lshl_add_u64 v[146:147], s[26:27], 0, v[132:133]
	s_mov_b32 m0, s28
	s_nop 0
	global_load_lds_dwordx4 v[146:147], off
	v_lshl_add_u64 v[146:147], s[26:27], 0, v[136:137]
	s_add_i32 m0, s28, 0x2000
	s_nop 0
	global_load_lds_dwordx4 v[146:147], off
	s_waitcnt vmcnt(6)
	s_barrier
	s_setprio 1
	v_mfma_f32_16x16x32_bf16 v[54:57], v[200:203], v[168:171], v[54:57]
	v_mfma_f32_16x16x32_bf16 v[50:53], v[208:211], v[168:171], v[50:53]
	v_mfma_f32_16x16x32_bf16 v[38:41], v[200:203], v[176:179], v[38:41]
	v_mfma_f32_16x16x32_bf16 v[34:37], v[208:211], v[176:179], v[34:37]
	v_mfma_f32_16x16x32_bf16 v[22:25], v[200:203], v[184:187], v[22:25]
	v_mfma_f32_16x16x32_bf16 v[18:21], v[208:211], v[184:187], v[18:21]
	v_mfma_f32_16x16x32_bf16 v[6:9], v[200:203], v[192:195], v[6:9]
	v_mfma_f32_16x16x32_bf16 v[2:5], v[208:211], v[192:195], v[2:5]
	v_mfma_f32_16x16x32_bf16 v[54:57], v[204:207], v[172:175], v[54:57]
	v_mfma_f32_16x16x32_bf16 v[50:53], v[212:215], v[172:175], v[50:53]
	v_mfma_f32_16x16x32_bf16 v[38:41], v[204:207], v[180:183], v[38:41]
	v_mfma_f32_16x16x32_bf16 v[34:37], v[212:215], v[180:183], v[34:37]
	v_mfma_f32_16x16x32_bf16 v[22:25], v[204:207], v[188:191], v[22:25]
	v_mfma_f32_16x16x32_bf16 v[18:21], v[212:215], v[188:191], v[18:21]
	v_mfma_f32_16x16x32_bf16 v[6:9], v[204:207], v[196:199], v[6:9]
	v_mfma_f32_16x16x32_bf16 v[2:5], v[212:215], v[196:199], v[2:5]
	s_setprio 0
	s_add_i32 s54, s54, 2
	s_add_u32 s24, s24, 0x100
	s_addc_u32 s25, s25, 0
	s_add_u32 s52, s52, 0x100
	s_addc_u32 s53, s53, 0
	s_cmp_gt_u32 s54, 13
	s_barrier
	s_cbranch_scc0 .LBB0_829
	v_readfirstlane_b32 s99, v0
	s_cmpk_gt_u32 s99, 0xff
	s_cbranch_scc1 .Lxb_p6_a
	s_barrier
.Lxb_p6_a:
	v_mul_f32_e32 v155, v127, v127
	v_fmac_f32_e32 v155, v126, v126
	v_fmac_f32_e32 v155, v128, v128
	v_fmac_f32_e32 v155, v129, v129
	v_fmac_f32_e32 v155, v122, v122
	v_fmac_f32_e32 v155, v123, v123
	v_fmac_f32_e32 v155, v124, v124
	v_cvt_pk_bf16_f32 v126, v126, v127
	v_cvt_pk_bf16_f32 v127, v128, v129
	v_cvt_pk_bf16_f32 v129, v124, v125
	v_mul_f32_e32 v124, v119, v119
	v_fmac_f32_e32 v124, v118, v118
	v_fmac_f32_e32 v124, v120, v120
	v_fmac_f32_e32 v124, v121, v121
	v_fmac_f32_e32 v124, v114, v114
	v_fmac_f32_e32 v124, v115, v115
	v_fmac_f32_e32 v124, v116, v116
	v_fmac_f32_e32 v155, v125, v125
	v_fmac_f32_e32 v124, v117, v117
	v_add_f32_e32 v124, v155, v124
	v_lshl_add_u32 v148, s20, 8, v1
	v_cvt_pk_bf16_f32 v118, v118, v119
	v_cvt_pk_bf16_f32 v119, v120, v121
	v_cvt_pk_bf16_f32 v120, v114, v115
	v_mov_b32_e32 v114, v124
	v_ashrrev_i32_e32 v149, 31, v148
	s_nop 0
	v_permlane16_swap_b32_e32 v124, v114
	v_lshl_or_b32 v146, s22, 8, v151
	v_lshlrev_b64 v[156:157], 11, v[148:149]
	v_add_f32_e32 v114, v124, v114
	v_ashrrev_i32_e32 v147, 31, v146
	v_cvt_pk_bf16_f32 v128, v122, v123
	v_lshl_add_u64 v[122:123], s[0:1], 0, v[156:157]
	v_mov_b32_e32 v115, v114
	v_lshl_add_u64 v[122:123], v[146:147], 1, v[122:123]
	v_cvt_pk_bf16_f32 v121, v116, v117
	v_permlane32_swap_b32_e32 v114, v115
	global_store_dwordx4 v[122:123], v[126:129], off
	global_store_dwordx4 v[122:123], v[118:121], off offset:256
	s_and_saveexec_b64 s[20:21], s[2:3]
	s_cbranch_execz .LBB0_832
	v_add_f32_e32 v116, v114, v115
	v_lshl_add_u64 v[114:115], v[148:149], 2, s[8:9]
	global_atomic_add_f32 v[114:115], v116, off

	.amdhsa_kernel _Z14fwd_megakernel6Params
		.amdhsa_group_segment_fixed_size 0
		.amdhsa_private_segment_fixed_size 0
		.amdhsa_kernarg_size 392
		.amdhsa_user_sgpr_count 2
		.amdhsa_user_sgpr_dispatch_ptr 0
		.amdhsa_user_sgpr_queue_ptr 0
		.amdhsa_user_sgpr_kernarg_segment_ptr 1
		.amdhsa_user_sgpr_dispatch_id 0
		.amdhsa_user_sgpr_kernarg_preload_length 0
		.amdhsa_user_sgpr_kernarg_preload_offset 0
		.amdhsa_user_sgpr_private_segment_size 0
		.amdhsa_uses_dynamic_stack 0
		.amdhsa_enable_private_segment 0
		.amdhsa_system_sgpr_workgroup_id_x 1
		.amdhsa_system_sgpr_workgroup_id_y 0
		.amdhsa_system_sgpr_workgroup_id_z 0
		.amdhsa_system_sgpr_workgroup_info 0
		.amdhsa_system_vgpr_workitem_id 0
		.amdhsa_next_free_vgpr 255
		.amdhsa_next_free_sgpr 102
		.amdhsa_accum_offset 256
		.amdhsa_reserve_vcc 1
		.amdhsa_float_round_mode_32 0
		.amdhsa_float_round_mode_16_64 0
		.amdhsa_float_denorm_mode_32 3
		.amdhsa_float_denorm_mode_16_64 3
		.amdhsa_dx10_clamp 1
		.amdhsa_ieee_mode 1
		.amdhsa_fp16_overflow 0
		.amdhsa_tg_split 0
		.amdhsa_exception_fp_ieee_invalid_op 0
		.amdhsa_exception_fp_denorm_src 0
		.amdhsa_exception_fp_ieee_div_zero 0
		.amdhsa_exception_fp_ieee_overflow 0
		.amdhsa_exception_fp_ieee_underflow 0
		.amdhsa_exception_fp_ieee_inexact 0
		.amdhsa_exception_int_div_zero 0
	.end_amdhsa_kernel

amdhsa.kernels:
  - .agpr_count:     0
    .args:
      - .offset:         0
        .size:           136
        .value_kind:     by_value
      - .offset:         136
        .size:           4
        .value_kind:     hidden_block_count_x
      - .offset:         140
        .size:           4
        .value_kind:     hidden_block_count_y
      - .offset:         144
        .size:           4
        .value_kind:     hidden_block_count_z
      - .offset:         148
        .size:           2
        .value_kind:     hidden_group_size_x
      - .offset:         150
        .size:           2
        .value_kind:     hidden_group_size_y
      - .offset:         152
        .size:           2
        .value_kind:     hidden_group_size_z
      - .offset:         154
        .size:           2
        .value_kind:     hidden_remainder_x
      - .offset:         156
        .size:           2
        .value_kind:     hidden_remainder_y
      - .offset:         158
        .size:           2
        .value_kind:     hidden_remainder_z
      - .offset:         176
        .size:           8
        .value_kind:     hidden_global_offset_x
      - .offset:         184
        .size:           8
        .value_kind:     hidden_global_offset_y
      - .offset:         192
        .size:           8
        .value_kind:     hidden_global_offset_z
      - .offset:         200
        .size:           2
        .value_kind:     hidden_grid_dims
      - .offset:         256
        .size:           4
        .value_kind:     hidden_dynamic_lds_size
    .group_segment_fixed_size: 0
    .kernarg_segment_align: 8
    .kernarg_segment_size: 392
    .language:       OpenCL C
    .language_version:
      - 2
      - 0
    .max_flat_workgroup_size: 512
    .name:           _Z14fwd_megakernel6Params
    .private_segment_fixed_size: 0
    .sgpr_count:     108
    .sgpr_spill_count: 16
    .symbol:         _Z14fwd_megakernel6Params.kd
    .uniform_work_group_size: 1
    .uses_dynamic_stack: false
    .vgpr_count:     255
    .vgpr_spill_count: 0
    .wavefront_size: 64
